# phase F GEMM port + f32 division sequences in activation epilogues replaced by v_rcp_f32 (sigmoid/silu/gelu/softmax 1/sum)
# speedup vs baseline: 1.0904x; 1.0204x over previous
.Lgm_loop_B:
	ds_read_b128 v[112:115], v213 offset:0
	ds_read_b128 v[116:119], v213 offset:4096
	ds_read_b128 v[120:123], v217 offset:32768
	ds_read_b128 v[124:127], v217 offset:36864
	s_waitcnt lgkmcnt(12)
	v_mfma_f32_32x32x16_bf16 v[48:63], v[64:67], v[72:75], v[48:63]
	v_mfma_f32_32x32x16_bf16 v[32:47], v[64:67], v[76:79], v[32:47]
	v_mfma_f32_32x32x16_bf16 v[16:31], v[68:71], v[72:75], v[16:31]
	v_mfma_f32_32x32x16_bf16 v[0:15], v[68:71], v[76:79], v[0:15]
	s_waitcnt vmcnt(0) lgkmcnt(0)
	s_barrier
	s_cmp_lt_u32 s64, 30
	s_cbranch_scc0 .Lgm_nodma0_B
	s_add_u32 m0, s65, 0x0
	s_nop 0
	global_load_lds_dwordx4 v206, s[68:69]
	s_add_u32 m0, s65, 0x1000
	s_nop 0
	global_load_lds_dwordx4 v207, s[68:69]
	s_add_u32 m0, s65, 0x2000
	s_nop 0
	global_load_lds_dwordx4 v208, s[68:69]
	s_add_u32 m0, s65, 0x3000
	s_nop 0
	global_load_lds_dwordx4 v209, s[68:69]
	s_add_u32 m0, s65, 0x8000
	s_nop 0
	global_load_lds_dwordx4 v206, s[70:71]
	s_add_u32 m0, s65, 0x9000
	s_nop 0
	global_load_lds_dwordx4 v207, s[70:71]
	s_add_u32 m0, s65, 0xa000
	s_nop 0
	global_load_lds_dwordx4 v208, s[70:71]
	s_add_u32 m0, s65, 0xb000
	s_nop 0
	global_load_lds_dwordx4 v209, s[70:71]
	s_add_u32 s68, s68, 0x80
	s_addc_u32 s69, s69, 0
	s_add_u32 s70, s70, 0x80
	s_addc_u32 s71, s71, 0
	ds_read_b128 v[64:67], v210 offset:16384
	ds_read_b128 v[68:71], v210 offset:20480
	ds_read_b128 v[72:75], v214 offset:49152
	ds_read_b128 v[76:79], v214 offset:53248
	v_mfma_f32_32x32x16_bf16 v[48:63], v[80:83], v[88:91], v[48:63]
	v_mfma_f32_32x32x16_bf16 v[32:47], v[80:83], v[92:95], v[32:47]
	v_mfma_f32_32x32x16_bf16 v[16:31], v[84:87], v[88:91], v[16:31]
	v_mfma_f32_32x32x16_bf16 v[0:15], v[84:87], v[92:95], v[0:15]
	ds_read_b128 v[80:83], v211 offset:16384
	ds_read_b128 v[84:87], v211 offset:20480
	ds_read_b128 v[88:91], v215 offset:49152
	ds_read_b128 v[92:95], v215 offset:53248
	v_mfma_f32_32x32x16_bf16 v[48:63], v[96:99], v[104:107], v[48:63]
	v_mfma_f32_32x32x16_bf16 v[32:47], v[96:99], v[108:111], v[32:47]
	v_mfma_f32_32x32x16_bf16 v[16:31], v[100:103], v[104:107], v[16:31]
	v_mfma_f32_32x32x16_bf16 v[0:15], v[100:103], v[108:111], v[0:15]
	ds_read_b128 v[96:99], v212 offset:16384
	ds_read_b128 v[100:103], v212 offset:20480
	ds_read_b128 v[104:107], v216 offset:49152
	ds_read_b128 v[108:111], v216 offset:53248
	v_mfma_f32_32x32x16_bf16 v[48:63], v[112:115], v[120:123], v[48:63]
	v_mfma_f32_32x32x16_bf16 v[32:47], v[112:115], v[124:127], v[32:47]
	v_mfma_f32_32x32x16_bf16 v[16:31], v[116:119], v[120:123], v[16:31]
	v_mfma_f32_32x32x16_bf16 v[0:15], v[116:119], v[124:127], v[0:15]
	s_branch .Lgm_join0_B

.Lgm_join0_B:
	ds_read_b128 v[112:115], v213 offset:16384
	ds_read_b128 v[116:119], v213 offset:20480
	ds_read_b128 v[120:123], v217 offset:49152
	ds_read_b128 v[124:127], v217 offset:53248
	s_waitcnt lgkmcnt(12)
	v_mfma_f32_32x32x16_bf16 v[48:63], v[64:67], v[72:75], v[48:63]
	v_mfma_f32_32x32x16_bf16 v[32:47], v[64:67], v[76:79], v[32:47]
	v_mfma_f32_32x32x16_bf16 v[16:31], v[68:71], v[72:75], v[16:31]
	v_mfma_f32_32x32x16_bf16 v[0:15], v[68:71], v[76:79], v[0:15]
	s_waitcnt vmcnt(0) lgkmcnt(0)
	s_barrier
	s_cmp_lt_u32 s64, 30
	s_cbranch_scc0 .Lgm_nodma1_B
	s_add_u32 m0, s65, 0x4000
	s_nop 0
	global_load_lds_dwordx4 v206, s[68:69]
	s_add_u32 m0, s65, 0x5000
	s_nop 0
	global_load_lds_dwordx4 v207, s[68:69]
	s_add_u32 m0, s65, 0x6000
	s_nop 0
	global_load_lds_dwordx4 v208, s[68:69]
	s_add_u32 m0, s65, 0x7000
	s_nop 0
	global_load_lds_dwordx4 v209, s[68:69]
	s_add_u32 m0, s65, 0xc000
	s_nop 0
	global_load_lds_dwordx4 v206, s[70:71]
	s_add_u32 m0, s65, 0xd000
	s_nop 0
	global_load_lds_dwordx4 v207, s[70:71]
	s_add_u32 m0, s65, 0xe000
	s_nop 0
	global_load_lds_dwordx4 v208, s[70:71]
	s_add_u32 m0, s65, 0xf000
	s_nop 0
	global_load_lds_dwordx4 v209, s[70:71]
	s_add_u32 s68, s68, 0x80
	s_addc_u32 s69, s69, 0
	s_add_u32 s70, s70, 0x80
	s_addc_u32 s71, s71, 0
	ds_read_b128 v[64:67], v210 offset:0
	ds_read_b128 v[68:71], v210 offset:4096
	ds_read_b128 v[72:75], v214 offset:32768
	ds_read_b128 v[76:79], v214 offset:36864
	v_mfma_f32_32x32x16_bf16 v[48:63], v[80:83], v[88:91], v[48:63]
	v_mfma_f32_32x32x16_bf16 v[32:47], v[80:83], v[92:95], v[32:47]
	v_mfma_f32_32x32x16_bf16 v[16:31], v[84:87], v[88:91], v[16:31]
	v_mfma_f32_32x32x16_bf16 v[0:15], v[84:87], v[92:95], v[0:15]
	ds_read_b128 v[80:83], v211 offset:0
	ds_read_b128 v[84:87], v211 offset:4096
	ds_read_b128 v[88:91], v215 offset:32768
	ds_read_b128 v[92:95], v215 offset:36864
	v_mfma_f32_32x32x16_bf16 v[48:63], v[96:99], v[104:107], v[48:63]
	v_mfma_f32_32x32x16_bf16 v[32:47], v[96:99], v[108:111], v[32:47]
	v_mfma_f32_32x32x16_bf16 v[16:31], v[100:103], v[104:107], v[16:31]
	v_mfma_f32_32x32x16_bf16 v[0:15], v[100:103], v[108:111], v[0:15]
	ds_read_b128 v[96:99], v212 offset:0
	ds_read_b128 v[100:103], v212 offset:4096
	ds_read_b128 v[104:107], v216 offset:32768
	ds_read_b128 v[108:111], v216 offset:36864
	v_mfma_f32_32x32x16_bf16 v[48:63], v[112:115], v[120:123], v[48:63]
	v_mfma_f32_32x32x16_bf16 v[32:47], v[112:115], v[124:127], v[32:47]
	v_mfma_f32_32x32x16_bf16 v[16:31], v[116:119], v[120:123], v[16:31]
	v_mfma_f32_32x32x16_bf16 v[0:15], v[116:119], v[124:127], v[0:15]
	s_branch .Lgm_join1_B

.Lgm_join1_B:
	s_add_u32 s64, s64, 2
	s_cmp_lt_u32 s64, 32
	s_cbranch_scc1 .Lgm_loop_B
	s_waitcnt lgkmcnt(0)
	s_barrier
	s_nop 7

.LBB0_277:
	s_andn2_b64 vcc, exec, s[0:1]
	s_cbranch_vccnz .LBB0_287
	s_mov_b64 s[0:1], -1
	s_and_b64 vcc, exec, s[70:71]
	s_cbranch_vccz .LBB0_281
	s_andn2_b64 vcc, exec, s[68:69]
	s_cbranch_vccnz .LBB0_340
	s_waitcnt lgkmcnt(1)
	v_mul_f32_e32 v74, 0xbfb8aa3b, v68
	v_mul_f32_e32 v75, 0xbfb8aa3b, v70
	v_exp_f32_e32 v74, v74
	v_exp_f32_e32 v75, v75
	v_mul_f32_e32 v76, 0xbfb8aa3b, v69
	v_mul_f32_e32 v77, 0xbfb8aa3b, v71
	v_exp_f32_e32 v76, v76
	v_pk_add_f32 v[74:75], v[74:75], 1.0 op_sel_hi:[1,0]
	v_exp_f32_e32 v77, v77
	s_nop 0
	v_pk_add_f32 v[76:77], v[76:77], 1.0 op_sel_hi:[1,0]
	v_rcp_f32_e32 v74, v74
	s_nop 0
	v_rcp_f32_e32 v75, v75
	s_nop 0
	v_rcp_f32_e32 v76, v76
	s_nop 0
	s_waitcnt lgkmcnt(0)
	v_mul_f32_e32 v81, 0xbfb8aa3b, v67
	v_mul_f32_e32 v78, 0xbfb8aa3b, v64
	v_mul_f32_e32 v79, 0xbfb8aa3b, v66
	v_exp_f32_e32 v78, v78
	v_exp_f32_e32 v79, v79
	v_rcp_f32_e32 v77, v77
	s_nop 0
	v_mul_f32_e32 v80, 0xbfb8aa3b, v65
	v_pk_add_f32 v[78:79], v[78:79], 1.0 op_sel_hi:[1,0]
	v_exp_f32_e32 v80, v80
	v_exp_f32_e32 v81, v81
	v_rcp_f32_e32 v78, v78
	s_nop 0
	v_pk_add_f32 v[80:81], v[80:81], 1.0 op_sel_hi:[1,0]
	v_rcp_f32_e32 v79, v79
	s_nop 0
	v_rcp_f32_e32 v80, v80
	s_nop 0
	s_mov_b64 s[0:1], 0
	v_rcp_f32_e32 v81, v81
	s_nop 0

.LBB0_282:
	s_waitcnt lgkmcnt(1)
	v_mul_f32_e32 v74, 0xbfb8aa3b, v68
	v_mul_f32_e32 v75, 0xbfb8aa3b, v70
	v_exp_f32_e32 v74, v74
	v_exp_f32_e32 v75, v75
	v_mul_f32_e32 v76, 0xbfb8aa3b, v69
	v_mul_f32_e32 v77, 0xbfb8aa3b, v71
	v_exp_f32_e32 v76, v76
	v_pk_add_f32 v[74:75], v[74:75], 1.0 op_sel_hi:[1,0]
	v_exp_f32_e32 v77, v77
	s_nop 0
	v_pk_add_f32 v[76:77], v[76:77], 1.0 op_sel_hi:[1,0]
	v_rcp_f32_e32 v78, v74
	s_nop 0
	v_mul_f32_e32 v74, v68, v78
	v_rcp_f32_e32 v68, v75
	s_nop 0
	v_mul_f32_e32 v75, v70, v68
	v_rcp_f32_e32 v68, v76
	s_nop 0
	v_mul_f32_e32 v76, v69, v68
	s_waitcnt lgkmcnt(0)
	v_mul_f32_e32 v68, 0xbfb8aa3b, v64
	v_mul_f32_e32 v69, 0xbfb8aa3b, v66
	v_exp_f32_e32 v68, v68
	v_exp_f32_e32 v69, v69
	v_mul_f32_e32 v78, 0xbfb8aa3b, v65
	v_mul_f32_e32 v79, 0xbfb8aa3b, v67
	v_exp_f32_e32 v78, v78
	v_pk_add_f32 v[68:69], v[68:69], 1.0 op_sel_hi:[1,0]
	v_exp_f32_e32 v79, v79
	v_rcp_f32_e32 v70, v77
	s_nop 0
	v_mul_f32_e32 v77, v71, v70
	v_pk_add_f32 v[70:71], v[78:79], 1.0 op_sel_hi:[1,0]
	v_rcp_f32_e32 v78, v68
	s_nop 0
	v_mul_f32_e32 v78, v64, v78
	v_rcp_f32_e32 v64, v69
	s_nop 0
	v_mul_f32_e32 v79, v66, v64
	v_rcp_f32_e32 v64, v70
	s_nop 0
	v_mul_f32_e32 v80, v65, v64
	v_rcp_f32_e32 v64, v71
	s_nop 0
	v_mul_f32_e32 v81, v67, v64

.LBB0_295:
	v_cndmask_b32_e64 v75, 0, 1, s[70:71]
	s_andn2_b64 vcc, exec, s[0:1]
	v_cmp_ne_u32_e64 s[0:1], 1, v75
	s_cbranch_vccnz .LBB0_305
	s_and_b64 vcc, exec, s[0:1]
	s_mov_b64 s[80:81], -1
	s_cbranch_vccnz .LBB0_299
	s_andn2_b64 vcc, exec, s[68:69]
	s_cbranch_vccnz .LBB0_341
	s_waitcnt lgkmcnt(1)
	v_mul_f32_e32 v75, 0xbfb8aa3b, v68
	v_exp_f32_e32 v76, v75
	v_mul_f32_e32 v75, 0xbfb8aa3b, v69
	v_exp_f32_e32 v78, v75
	v_mul_f32_e32 v75, 0xbfb8aa3b, v70
	v_exp_f32_e32 v77, v75
	v_mul_f32_e32 v75, 0xbfb8aa3b, v71
	v_exp_f32_e32 v79, v75
	v_pk_add_f32 v[76:77], v[76:77], 1.0 op_sel_hi:[1,0]
	s_nop 0
	v_pk_add_f32 v[78:79], v[78:79], 1.0 op_sel_hi:[1,0]
	v_rcp_f32_e32 v76, v76
	s_nop 0
	s_nop 0
	v_rcp_f32_e32 v77, v77
	s_nop 0
	s_nop 0
	v_rcp_f32_e32 v78, v78
	s_nop 0
	s_nop 0
	v_rcp_f32_e32 v79, v79
	s_nop 0
	s_waitcnt lgkmcnt(0)
	v_mul_f32_e32 v75, 0xbfb8aa3b, v64
	v_exp_f32_e32 v80, v75
	v_mul_f32_e32 v75, 0xbfb8aa3b, v65
	v_exp_f32_e32 v82, v75
	v_mul_f32_e32 v75, 0xbfb8aa3b, v66
	v_exp_f32_e32 v81, v75
	v_mul_f32_e32 v75, 0xbfb8aa3b, v67
	v_exp_f32_e32 v83, v75
	v_pk_add_f32 v[80:81], v[80:81], 1.0 op_sel_hi:[1,0]
	s_nop 0
	v_pk_add_f32 v[82:83], v[82:83], 1.0 op_sel_hi:[1,0]
	v_rcp_f32_e32 v80, v80
	s_nop 0
	s_nop 0
	v_rcp_f32_e32 v81, v81
	s_nop 0
	s_nop 0
	v_rcp_f32_e32 v82, v82
	s_nop 0
	s_mov_b64 s[80:81], 0
	v_rcp_f32_e32 v83, v83
	s_nop 0

.LBB0_300:
	s_waitcnt lgkmcnt(1)
	v_mul_f32_e32 v75, 0xbfb8aa3b, v68
	v_exp_f32_e32 v76, v75
	v_mul_f32_e32 v75, 0xbfb8aa3b, v69
	v_exp_f32_e32 v78, v75
	v_mul_f32_e32 v75, 0xbfb8aa3b, v70
	v_exp_f32_e32 v77, v75
	v_mul_f32_e32 v75, 0xbfb8aa3b, v71
	v_exp_f32_e32 v79, v75
	v_pk_add_f32 v[76:77], v[76:77], 1.0 op_sel_hi:[1,0]
	s_nop 0
	v_pk_add_f32 v[78:79], v[78:79], 1.0 op_sel_hi:[1,0]
	v_rcp_f32_e32 v75, v76
	s_nop 0
	v_mul_f32_e32 v76, v68, v75
	s_nop 0
	v_rcp_f32_e32 v68, v77
	s_nop 0
	v_mul_f32_e32 v77, v70, v68
	s_nop 0
	v_rcp_f32_e32 v68, v78
	s_nop 0
	v_mul_f32_e32 v78, v69, v68
	s_nop 0
	s_waitcnt lgkmcnt(0)
	v_mul_f32_e32 v69, 0xbfb8aa3b, v65
	v_rcp_f32_e32 v68, v79
	s_nop 0
	v_mul_f32_e32 v79, v71, v68
	v_mul_f32_e32 v68, 0xbfb8aa3b, v64
	v_exp_f32_e32 v70, v69
	v_mul_f32_e32 v69, 0xbfb8aa3b, v66
	v_exp_f32_e32 v68, v68
	v_exp_f32_e32 v69, v69
	v_mul_f32_e32 v71, 0xbfb8aa3b, v67
	v_exp_f32_e32 v71, v71
	v_pk_add_f32 v[68:69], v[68:69], 1.0 op_sel_hi:[1,0]
	s_nop 0
	v_pk_add_f32 v[70:71], v[70:71], 1.0 op_sel_hi:[1,0]
	v_rcp_f32_e32 v75, v68
	s_nop 0
	v_mul_f32_e32 v80, v64, v75
	s_nop 0
	v_rcp_f32_e32 v64, v69
	s_nop 0
	v_mul_f32_e32 v81, v66, v64
	s_nop 0
	v_rcp_f32_e32 v64, v70
	s_nop 0
	v_mul_f32_e32 v82, v65, v64
	s_nop 0
	v_rcp_f32_e32 v64, v71
	s_nop 0
	v_mul_f32_e32 v83, v67, v64

.LBB0_313:
	s_andn2_b64 vcc, exec, s[80:81]
	s_cbranch_vccnz .LBB0_323
	s_and_b64 vcc, exec, s[0:1]
	s_mov_b64 s[80:81], -1
	s_cbranch_vccnz .LBB0_317
	s_andn2_b64 vcc, exec, s[68:69]
	s_cbranch_vccnz .LBB0_342
	s_waitcnt lgkmcnt(1)
	v_mul_f32_e32 v75, 0xbfb8aa3b, v68
	v_exp_f32_e32 v76, v75
	v_mul_f32_e32 v75, 0xbfb8aa3b, v69
	v_exp_f32_e32 v78, v75
	v_mul_f32_e32 v75, 0xbfb8aa3b, v70
	v_exp_f32_e32 v77, v75
	v_mul_f32_e32 v75, 0xbfb8aa3b, v71
	v_exp_f32_e32 v79, v75
	v_pk_add_f32 v[76:77], v[76:77], 1.0 op_sel_hi:[1,0]
	s_nop 0
	v_pk_add_f32 v[78:79], v[78:79], 1.0 op_sel_hi:[1,0]
	v_rcp_f32_e32 v76, v76
	s_nop 0
	s_nop 0
	v_rcp_f32_e32 v77, v77
	s_nop 0
	s_nop 0
	v_rcp_f32_e32 v78, v78
	s_nop 0
	s_nop 0
	v_rcp_f32_e32 v79, v79
	s_nop 0
	s_waitcnt lgkmcnt(0)
	v_mul_f32_e32 v75, 0xbfb8aa3b, v64
	v_exp_f32_e32 v80, v75
	v_mul_f32_e32 v75, 0xbfb8aa3b, v65
	v_exp_f32_e32 v82, v75
	v_mul_f32_e32 v75, 0xbfb8aa3b, v66
	v_exp_f32_e32 v81, v75
	v_mul_f32_e32 v75, 0xbfb8aa3b, v67
	v_exp_f32_e32 v83, v75
	v_pk_add_f32 v[80:81], v[80:81], 1.0 op_sel_hi:[1,0]
	s_nop 0
	v_pk_add_f32 v[82:83], v[82:83], 1.0 op_sel_hi:[1,0]
	v_rcp_f32_e32 v80, v80
	s_nop 0
	s_nop 0
	v_rcp_f32_e32 v81, v81
	s_nop 0
	s_nop 0
	v_rcp_f32_e32 v82, v82
	s_nop 0
	s_mov_b64 s[80:81], 0
	v_rcp_f32_e32 v83, v83
	s_nop 0

.LBB0_331:
	s_andn2_b64 vcc, exec, s[10:11]
	s_cbranch_vccnz .LBB0_268
	s_and_b64 vcc, exec, s[0:1]
	s_mov_b64 s[0:1], -1
	s_cbranch_vccnz .LBB0_335
	s_andn2_b64 vcc, exec, s[68:69]
	s_cbranch_vccnz .LBB0_343
	s_waitcnt lgkmcnt(1)
	v_mul_f32_e32 v75, 0xbfb8aa3b, v68
	v_mul_f32_e32 v77, 0xbfb8aa3b, v70
	v_exp_f32_e32 v76, v75
	v_exp_f32_e32 v77, v77
	v_mul_f32_e32 v75, 0xbfb8aa3b, v69
	v_exp_f32_e32 v78, v75
	v_mul_f32_e32 v75, 0xbfb8aa3b, v71
	v_pk_add_f32 v[76:77], v[76:77], 1.0 op_sel_hi:[1,0]
	v_exp_f32_e32 v79, v75
	s_nop 0
	v_pk_add_f32 v[78:79], v[78:79], 1.0 op_sel_hi:[1,0]
	v_rcp_f32_e32 v76, v76
	s_nop 0
	v_rcp_f32_e32 v77, v77
	s_nop 0
	v_rcp_f32_e32 v78, v78
	s_nop 0
	s_waitcnt lgkmcnt(0)
	v_mul_f32_e32 v82, 0xbfb8aa3b, v65
	v_mul_f32_e32 v80, 0xbfb8aa3b, v64
	v_mul_f32_e32 v81, 0xbfb8aa3b, v66
	v_exp_f32_e32 v80, v80
	v_exp_f32_e32 v81, v81
	v_rcp_f32_e32 v79, v79
	s_nop 0
	v_mul_f32_e32 v83, 0xbfb8aa3b, v67
	v_pk_add_f32 v[80:81], v[80:81], 1.0 op_sel_hi:[1,0]
	v_exp_f32_e32 v82, v82
	v_exp_f32_e32 v83, v83
	v_rcp_f32_e32 v80, v80
	s_nop 0
	v_pk_add_f32 v[82:83], v[82:83], 1.0 op_sel_hi:[1,0]
	v_rcp_f32_e32 v81, v81
	s_nop 0
	v_rcp_f32_e32 v82, v82
	s_nop 0
	s_mov_b64 s[0:1], 0
	v_rcp_f32_e32 v83, v83
	s_nop 0

.LBB0_336:
	s_waitcnt lgkmcnt(1)
	v_mul_f32_e32 v75, 0xbfb8aa3b, v68
	v_mul_f32_e32 v77, 0xbfb8aa3b, v70
	v_exp_f32_e32 v76, v75
	v_exp_f32_e32 v77, v77
	v_mul_f32_e32 v75, 0xbfb8aa3b, v69
	v_exp_f32_e32 v78, v75
	v_mul_f32_e32 v75, 0xbfb8aa3b, v71
	v_pk_add_f32 v[76:77], v[76:77], 1.0 op_sel_hi:[1,0]
	v_exp_f32_e32 v79, v75
	s_nop 0
	v_pk_add_f32 v[78:79], v[78:79], 1.0 op_sel_hi:[1,0]
	v_rcp_f32_e32 v75, v76
	s_nop 0
	v_mul_f32_e32 v76, v68, v75
	v_rcp_f32_e32 v68, v77
	s_nop 0
	v_mul_f32_e32 v77, v70, v68
	v_rcp_f32_e32 v68, v78
	s_nop 0
	v_mul_f32_e32 v78, v69, v68
	s_waitcnt lgkmcnt(0)
	v_mul_f32_e32 v68, 0xbfb8aa3b, v64
	v_mul_f32_e32 v69, 0xbfb8aa3b, v66
	v_exp_f32_e32 v68, v68
	v_exp_f32_e32 v69, v69
	v_mul_f32_e32 v80, 0xbfb8aa3b, v65
	v_mul_f32_e32 v81, 0xbfb8aa3b, v67
	v_exp_f32_e32 v80, v80
	v_pk_add_f32 v[68:69], v[68:69], 1.0 op_sel_hi:[1,0]
	v_exp_f32_e32 v81, v81
	v_rcp_f32_e32 v70, v79
	s_nop 0
	v_mul_f32_e32 v79, v71, v70
	v_pk_add_f32 v[70:71], v[80:81], 1.0 op_sel_hi:[1,0]
	v_rcp_f32_e32 v75, v68
	s_nop 0
	v_mul_f32_e32 v80, v64, v75
	v_rcp_f32_e32 v64, v69
	s_nop 0
	v_mul_f32_e32 v81, v66, v64
	v_rcp_f32_e32 v64, v70
	s_nop 0
	v_mul_f32_e32 v82, v65, v64
	v_rcp_f32_e32 v64, v71
	s_nop 0
	v_mul_f32_e32 v83, v67, v64

.LBB0_525:
	v_mfma_f32_32x32x16_bf16 v[0:15], v[120:123], v[64:67], 0
	s_waitcnt lgkmcnt(0)
	v_mfma_f32_32x32x16_bf16 v[48:63], v[120:123], v[76:79], 0
	v_mfma_f32_32x32x16_bf16 v[16:31], v[120:123], v[68:71], 0
	v_mfma_f32_32x32x16_bf16 v[32:47], v[120:123], v[72:75], 0
	s_nop 8
	ds_write_b32 v152, v0
	s_nop 1
	ds_write2_b32 v153, v16, v32 offset0:32 offset1:64
	ds_write_b32 v153, v48 offset:384
	ds_write_b32 v154, v1
	ds_write2_b32 v155, v17, v33 offset0:32 offset1:64
	ds_write_b32 v155, v49 offset:384
	ds_write_b32 v156, v2
	ds_write2_b32 v157, v18, v34 offset0:32 offset1:64
	ds_write_b32 v157, v50 offset:384
	ds_write_b32 v158, v3
	ds_write2_b32 v159, v19, v35 offset0:32 offset1:64
	ds_write_b32 v159, v51 offset:384
	ds_write_b32 v160, v4
	ds_write2_b32 v161, v20, v36 offset0:32 offset1:64
	ds_write_b32 v161, v52 offset:384
	ds_write_b32 v162, v5
	ds_write2_b32 v163, v21, v37 offset0:32 offset1:64
	ds_write_b32 v163, v53 offset:384
	ds_write_b32 v164, v6
	ds_write2_b32 v165, v22, v38 offset0:32 offset1:64
	ds_write_b32 v165, v54 offset:384
	ds_write_b32 v166, v7
	ds_write2_b32 v167, v23, v39 offset0:32 offset1:64
	ds_write_b32 v167, v55 offset:384
	ds_write_b32 v189, v8
	ds_write2_b32 v190, v24, v40 offset0:32 offset1:64
	ds_write_b32 v190, v56 offset:384
	ds_write_b32 v191, v9
	ds_write2_b32 v192, v25, v41 offset0:32 offset1:64
	ds_write_b32 v192, v57 offset:384
	ds_write_b32 v193, v10
	ds_write2_b32 v194, v26, v42 offset0:32 offset1:64
	ds_write_b32 v194, v58 offset:384
	ds_write_b32 v195, v11
	ds_write2_b32 v196, v27, v43 offset0:32 offset1:64
	ds_write_b32 v196, v59 offset:384
	ds_write_b32 v197, v12
	ds_write2_b32 v198, v28, v44 offset0:32 offset1:64
	ds_write_b32 v198, v60 offset:384
	ds_write_b32 v199, v13
	ds_write2_b32 v200, v29, v45 offset0:32 offset1:64
	ds_write_b32 v200, v61 offset:384
	ds_write_b32 v201, v14
	ds_write2_b32 v202, v30, v46 offset0:32 offset1:64
	ds_write_b32 v202, v62 offset:384
	ds_write_b32 v203, v15
	ds_write2_b32 v204, v31, v47 offset0:32 offset1:64
	ds_write_b32 v204, v63 offset:384
	s_waitcnt lgkmcnt(0)
	ds_read2_b32 v[0:1], v205 offset1:32
	ds_read2_b32 v[2:3], v205 offset0:132 offset1:164
	v_pk_mul_f32 v[32:33], v[142:143], v[150:151]
	v_add_u32_e32 v6, 0x400, v205
	v_sub_f32_e32 v32, v32, v33
	s_waitcnt lgkmcnt(1)
	v_add_f32_e32 v0, v32, v0
	v_mul_f32_e32 v32, v124, v150
	v_fmac_f32_e32 v32, v142, v151
	v_add_f32_e32 v1, v32, v1
	v_bfe_u32 v32, v0, 16, 1
	v_add_u32_e32 v10, 0x800, v205
	v_add_u32_e32 v14, 0xc00, v205
	v_add_u32_e32 v18, 0x1000, v205
	v_add_u32_e32 v22, 0x1400, v205
	v_add_u32_e32 v26, 0x1800, v205
	v_add_u32_e32 v30, 0x1c00, v205
	v_add3_u32 v32, v0, v32, s33
	ds_read2_b32 v[4:5], v6 offset0:8 offset1:40
	ds_read2_b32 v[6:7], v6 offset0:140 offset1:172
	ds_read2_b32 v[8:9], v10 offset0:16 offset1:48
	ds_read2_b32 v[10:11], v10 offset0:148 offset1:180
	ds_read2_b32 v[12:13], v14 offset0:24 offset1:56
	ds_read2_b32 v[14:15], v14 offset0:156 offset1:188
	ds_read2_b32 v[16:17], v18 offset0:32 offset1:64
	ds_read2_b32 v[18:19], v18 offset0:164 offset1:196
	ds_read2_b32 v[20:21], v22 offset0:40 offset1:72
	ds_read2_b32 v[22:23], v22 offset0:172 offset1:204
	ds_read2_b32 v[24:25], v26 offset0:48 offset1:80
	ds_read2_b32 v[26:27], v26 offset0:180 offset1:212
	ds_read2_b32 v[28:29], v30 offset0:56 offset1:88
	ds_read2_b32 v[30:31], v30 offset0:188 offset1:220
	s_waitcnt lgkmcnt(0)
	ds_write_b16_d16_hi v206, v32
	v_bfe_u32 v32, v1, 16, 1
	v_add3_u32 v32, v1, v32, s33
	ds_write_b16_d16_hi v206, v32 offset:64
	v_mul_f32_e32 v32, v143, v1
	v_fma_f32 v32, v142, v0, -v32
	v_mul_f32_e32 v1, v142, v1
	s_waitcnt lgkmcnt(14)
	v_add_f32_e32 v2, v2, v32
	v_fmac_f32_e32 v1, v143, v0
	v_add_f32_e32 v0, v3, v1
	v_bfe_u32 v1, v2, 16, 1
	v_add3_u32 v1, v2, v1, s33
	ds_write_b16_d16_hi v206, v1 offset:528
	v_bfe_u32 v1, v0, 16, 1
	v_add3_u32 v1, v0, v1, s33
	ds_write_b16_d16_hi v206, v1 offset:592
	v_mul_f32_e32 v1, v143, v0
	v_fma_f32 v1, v142, v2, -v1
	v_mul_f32_e32 v2, v143, v2
	v_add_f32_e32 v1, v4, v1
	v_fmac_f32_e32 v2, v142, v0
	v_add_f32_e32 v0, v5, v2
	v_bfe_u32 v2, v1, 16, 1
	v_add3_u32 v2, v1, v2, s33
	ds_write_b16_d16_hi v206, v2 offset:1056
	v_bfe_u32 v2, v0, 16, 1
	v_add3_u32 v2, v0, v2, s33
	ds_write_b16_d16_hi v206, v2 offset:1120
	v_mul_f32_e32 v2, v143, v0
	v_fma_f32 v2, v142, v1, -v2
	v_mul_f32_e32 v1, v143, v1
	v_add_f32_e32 v2, v6, v2
	v_fmac_f32_e32 v1, v142, v0
	v_add_f32_e32 v0, v7, v1
	v_bfe_u32 v1, v2, 16, 1
	v_add3_u32 v1, v2, v1, s33
	ds_write_b16_d16_hi v206, v1 offset:1584
	v_bfe_u32 v1, v0, 16, 1
	v_add3_u32 v1, v0, v1, s33
	ds_write_b16_d16_hi v206, v1 offset:1648
	v_mul_f32_e32 v1, v143, v0
	v_fma_f32 v1, v142, v2, -v1
	v_mul_f32_e32 v2, v143, v2
	s_waitcnt lgkmcnt(14)
	v_add_f32_e32 v1, v8, v1
	v_fmac_f32_e32 v2, v142, v0
	v_add_f32_e32 v0, v9, v2
	v_bfe_u32 v2, v1, 16, 1
	v_add3_u32 v2, v1, v2, s33
	ds_write_b16_d16_hi v206, v2 offset:2112
	v_bfe_u32 v2, v0, 16, 1
	v_add3_u32 v2, v0, v2, s33
	ds_write_b16_d16_hi v206, v2 offset:2176
	v_mul_f32_e32 v2, v143, v0
	v_fma_f32 v2, v142, v1, -v2
	v_mul_f32_e32 v1, v143, v1
	v_add_f32_e32 v2, v10, v2
	v_fmac_f32_e32 v1, v142, v0
	v_add_f32_e32 v0, v11, v1
	v_bfe_u32 v1, v2, 16, 1
	v_add3_u32 v1, v2, v1, s33
	ds_write_b16_d16_hi v206, v1 offset:2640
	v_bfe_u32 v1, v0, 16, 1
	v_add3_u32 v1, v0, v1, s33
	ds_write_b16_d16_hi v206, v1 offset:2704
	v_mul_f32_e32 v1, v143, v0
	v_fma_f32 v1, v142, v2, -v1
	v_mul_f32_e32 v2, v143, v2
	v_add_f32_e32 v1, v12, v1
	v_fmac_f32_e32 v2, v142, v0
	v_add_f32_e32 v0, v13, v2
	v_bfe_u32 v2, v1, 16, 1
	v_add3_u32 v2, v1, v2, s33
	ds_write_b16_d16_hi v206, v2 offset:3168
	v_bfe_u32 v2, v0, 16, 1
	v_add3_u32 v2, v0, v2, s33
	ds_write_b16_d16_hi v206, v2 offset:3232
	v_mul_f32_e32 v2, v143, v0
	v_fma_f32 v2, v142, v1, -v2
	v_mul_f32_e32 v1, v143, v1
	v_add_f32_e32 v2, v14, v2
	v_fmac_f32_e32 v1, v142, v0
	v_add_f32_e32 v0, v15, v1
	v_bfe_u32 v1, v2, 16, 1
	v_add3_u32 v1, v2, v1, s33
	ds_write_b16_d16_hi v206, v1 offset:3696
	v_bfe_u32 v1, v0, 16, 1
	v_add3_u32 v1, v0, v1, s33
	ds_write_b16_d16_hi v206, v1 offset:3760
	v_mul_f32_e32 v1, v143, v0
	v_fma_f32 v1, v142, v2, -v1
	v_mul_f32_e32 v2, v143, v2
	v_add_f32_e32 v1, v16, v1
	v_fmac_f32_e32 v2, v142, v0
	v_add_f32_e32 v0, v17, v2
	v_bfe_u32 v2, v1, 16, 1
	v_add3_u32 v2, v1, v2, s33
	ds_write_b16_d16_hi v206, v2 offset:4224
	v_bfe_u32 v2, v0, 16, 1
	v_add3_u32 v2, v0, v2, s33
	ds_write_b16_d16_hi v206, v2 offset:4288
	v_mul_f32_e32 v2, v143, v0
	v_fma_f32 v2, v142, v1, -v2
	v_mul_f32_e32 v1, v143, v1
	v_add_f32_e32 v2, v18, v2
	v_fmac_f32_e32 v1, v142, v0
	v_add_f32_e32 v0, v19, v1
	v_bfe_u32 v1, v2, 16, 1
	v_add3_u32 v1, v2, v1, s33
	ds_write_b16_d16_hi v206, v1 offset:4752
	v_bfe_u32 v1, v0, 16, 1
	v_add3_u32 v1, v0, v1, s33
	ds_write_b16_d16_hi v206, v1 offset:4816
	v_mul_f32_e32 v1, v143, v0
	v_fma_f32 v1, v142, v2, -v1
	v_mul_f32_e32 v2, v143, v2
	s_waitcnt lgkmcnt(14)
	v_add_f32_e32 v1, v20, v1
	v_fmac_f32_e32 v2, v142, v0
	v_add_f32_e32 v0, v21, v2
	v_bfe_u32 v2, v1, 16, 1
	v_add3_u32 v2, v1, v2, s33
	ds_write_b16_d16_hi v206, v2 offset:5280
	v_bfe_u32 v2, v0, 16, 1
	v_add3_u32 v2, v0, v2, s33
	ds_write_b16_d16_hi v206, v2 offset:5344
	v_mul_f32_e32 v2, v143, v0
	v_fma_f32 v2, v142, v1, -v2
	v_mul_f32_e32 v1, v143, v1
	v_add_f32_e32 v2, v22, v2
	v_fmac_f32_e32 v1, v142, v0
	v_add_f32_e32 v0, v23, v1
	v_bfe_u32 v1, v2, 16, 1
	v_add3_u32 v1, v2, v1, s33
	ds_write_b16_d16_hi v206, v1 offset:5808
	v_bfe_u32 v1, v0, 16, 1
	v_add3_u32 v1, v0, v1, s33
	ds_write_b16_d16_hi v206, v1 offset:5872
	v_mul_f32_e32 v1, v143, v0
	v_fma_f32 v1, v142, v2, -v1
	v_mul_f32_e32 v2, v143, v2
	v_add_f32_e32 v1, v24, v1
	v_fmac_f32_e32 v2, v142, v0
	v_add_f32_e32 v0, v25, v2
	v_bfe_u32 v2, v1, 16, 1
	v_add3_u32 v2, v1, v2, s33
	ds_write_b16_d16_hi v206, v2 offset:6336
	v_bfe_u32 v2, v0, 16, 1
	v_add3_u32 v2, v0, v2, s33
	ds_write_b16_d16_hi v206, v2 offset:6400
	v_mul_f32_e32 v2, v143, v0
	v_fma_f32 v2, v142, v1, -v2
	v_mul_f32_e32 v1, v143, v1
	v_add_f32_e32 v2, v26, v2
	v_fmac_f32_e32 v1, v142, v0
	v_add_f32_e32 v0, v27, v1
	v_bfe_u32 v1, v2, 16, 1
	v_add3_u32 v1, v2, v1, s33
	ds_write_b16_d16_hi v206, v1 offset:6864
	v_bfe_u32 v1, v0, 16, 1
	v_add3_u32 v1, v0, v1, s33
	ds_write_b16_d16_hi v206, v1 offset:6928
	v_mul_f32_e32 v1, v143, v0
	v_fma_f32 v1, v142, v2, -v1
	v_mul_f32_e32 v2, v143, v2
	v_add_f32_e32 v1, v28, v1
	v_fmac_f32_e32 v2, v142, v0
	v_add_f32_e32 v0, v29, v2
	v_bfe_u32 v2, v1, 16, 1
	v_add3_u32 v2, v1, v2, s33
	ds_write_b16_d16_hi v206, v2 offset:7392
	v_bfe_u32 v2, v0, 16, 1
	v_add3_u32 v2, v0, v2, s33
	ds_write_b16_d16_hi v206, v2 offset:7456
	v_mul_f32_e32 v2, v143, v0
	v_fma_f32 v2, v142, v1, -v2
	v_add_f32_e32 v32, v30, v2
	v_mul_f32_e32 v1, v143, v1
	v_fmac_f32_e32 v1, v142, v0
	v_bfe_u32 v0, v32, 16, 1
	v_add_f32_e32 v33, v31, v1
	v_add3_u32 v0, v32, v0, s33
	ds_write_b16_d16_hi v206, v0 offset:7920
	v_bfe_u32 v0, v33, 16, 1
	v_add3_u32 v0, v33, v0, s33
	ds_write_b16_d16_hi v206, v0 offset:7984
	v_add_u32_e32 v2, 0x2000, v205
	ds_read2_b32 v[0:1], v2 offset0:64 offset1:96
	ds_read2_b32 v[2:3], v2 offset0:196 offset1:228
	v_mul_f32_e32 v34, v143, v33
	v_fma_f32 v34, v142, v32, -v34
	v_mul_f32_e32 v32, v143, v32
	s_waitcnt lgkmcnt(1)
	v_add_f32_e32 v0, v34, v0
	v_fmac_f32_e32 v32, v142, v33
	v_add_f32_e32 v1, v32, v1
	v_bfe_u32 v32, v0, 16, 1
	v_add_u32_e32 v6, 0x2400, v205
	v_add_u32_e32 v10, 0x2800, v205
	v_add_u32_e32 v14, 0x2c00, v205
	v_add_u32_e32 v16, 0x3000, v205
	v_add_u32_e32 v18, 0x3200, v205
	v_add_u32_e32 v20, 0x3400, v205
	v_add_u32_e32 v22, 0x3600, v205
	v_add_u32_e32 v24, 0x3800, v205
	v_add_u32_e32 v26, 0x3a00, v205
	v_add_u32_e32 v28, 0x3c00, v205
	v_add_u32_e32 v30, 0x3e00, v205
	v_add3_u32 v32, v0, v32, s33
	ds_read2_b32 v[4:5], v6 offset0:72 offset1:104
	ds_read2_b32 v[6:7], v6 offset0:204 offset1:236
	ds_read2_b32 v[8:9], v10 offset0:80 offset1:112
	ds_read2_b32 v[10:11], v10 offset0:212 offset1:244
	ds_read2_b32 v[12:13], v14 offset0:88 offset1:120
	ds_read2_b32 v[14:15], v14 offset0:220 offset1:252
	ds_read2_b32 v[16:17], v16 offset0:96 offset1:128
	ds_read2_b32 v[18:19], v18 offset0:100 offset1:132
	ds_read2_b32 v[20:21], v20 offset0:104 offset1:136
	ds_read2_b32 v[22:23], v22 offset0:108 offset1:140
	ds_read2_b32 v[24:25], v24 offset0:112 offset1:144
	ds_read2_b32 v[26:27], v26 offset0:116 offset1:148
	ds_read2_b32 v[28:29], v28 offset0:120 offset1:152
	ds_read2_b32 v[30:31], v30 offset0:124 offset1:156
	s_waitcnt lgkmcnt(0)
	ds_write_b16_d16_hi v206, v32 offset:8448
	v_bfe_u32 v32, v1, 16, 1
	v_add3_u32 v32, v1, v32, s33
	ds_write_b16_d16_hi v206, v32 offset:8512
	v_mul_f32_e32 v32, v143, v1
	v_fma_f32 v32, v142, v0, -v32
	v_mul_f32_e32 v1, v142, v1
	s_waitcnt lgkmcnt(14)
	v_add_f32_e32 v2, v2, v32
	v_fmac_f32_e32 v1, v143, v0
	v_add_f32_e32 v0, v3, v1
	v_bfe_u32 v1, v2, 16, 1
	v_add3_u32 v1, v2, v1, s33
	ds_write_b16_d16_hi v206, v1 offset:8976
	v_bfe_u32 v1, v0, 16, 1
	v_add3_u32 v1, v0, v1, s33
	ds_write_b16_d16_hi v206, v1 offset:9040
	v_mul_f32_e32 v1, v143, v0
	v_fma_f32 v1, v142, v2, -v1
	v_mul_f32_e32 v2, v143, v2
	v_add_f32_e32 v1, v4, v1
	v_fmac_f32_e32 v2, v142, v0
	v_add_f32_e32 v0, v5, v2
	v_bfe_u32 v2, v1, 16, 1
	v_add3_u32 v2, v1, v2, s33
	ds_write_b16_d16_hi v206, v2 offset:9504
	v_bfe_u32 v2, v0, 16, 1
	v_add3_u32 v2, v0, v2, s33
	ds_write_b16_d16_hi v206, v2 offset:9568
	v_mul_f32_e32 v2, v143, v0
	v_fma_f32 v2, v142, v1, -v2
	v_mul_f32_e32 v1, v143, v1
	v_add_f32_e32 v2, v6, v2
	v_fmac_f32_e32 v1, v142, v0
	v_add_f32_e32 v0, v7, v1
	v_bfe_u32 v1, v2, 16, 1
	v_add3_u32 v1, v2, v1, s33
	ds_write_b16_d16_hi v206, v1 offset:10032
	v_bfe_u32 v1, v0, 16, 1
	v_add3_u32 v1, v0, v1, s33
	ds_write_b16_d16_hi v206, v1 offset:10096
	v_mul_f32_e32 v1, v143, v0
	v_fma_f32 v1, v142, v2, -v1
	v_mul_f32_e32 v2, v143, v2
	s_waitcnt lgkmcnt(14)
	v_add_f32_e32 v1, v8, v1
	v_fmac_f32_e32 v2, v142, v0
	v_add_f32_e32 v0, v9, v2
	v_bfe_u32 v2, v1, 16, 1
	v_add3_u32 v2, v1, v2, s33
	ds_write_b16_d16_hi v206, v2 offset:10560
	v_bfe_u32 v2, v0, 16, 1
	v_add3_u32 v2, v0, v2, s33
	ds_write_b16_d16_hi v206, v2 offset:10624
	v_mul_f32_e32 v2, v143, v0
	v_fma_f32 v2, v142, v1, -v2
	v_mul_f32_e32 v1, v143, v1
	v_add_f32_e32 v2, v10, v2
	v_fmac_f32_e32 v1, v142, v0
	v_add_f32_e32 v0, v11, v1
	v_bfe_u32 v1, v2, 16, 1
	v_add3_u32 v1, v2, v1, s33
	ds_write_b16_d16_hi v206, v1 offset:11088
	v_bfe_u32 v1, v0, 16, 1
	v_add3_u32 v1, v0, v1, s33
	ds_write_b16_d16_hi v206, v1 offset:11152
	v_mul_f32_e32 v1, v143, v0
	v_fma_f32 v1, v142, v2, -v1
	v_mul_f32_e32 v2, v143, v2
	v_add_f32_e32 v1, v12, v1
	v_fmac_f32_e32 v2, v142, v0
	v_add_f32_e32 v0, v13, v2
	v_bfe_u32 v2, v1, 16, 1
	v_add3_u32 v2, v1, v2, s33
	ds_write_b16_d16_hi v206, v2 offset:11616
	v_bfe_u32 v2, v0, 16, 1
	v_add3_u32 v2, v0, v2, s33
	ds_write_b16_d16_hi v206, v2 offset:11680
	v_mul_f32_e32 v2, v143, v0
	v_fma_f32 v2, v142, v1, -v2
	v_mul_f32_e32 v1, v143, v1
	v_add_f32_e32 v2, v14, v2
	v_fmac_f32_e32 v1, v142, v0
	v_add_f32_e32 v0, v15, v1
	v_bfe_u32 v1, v2, 16, 1
	v_add3_u32 v1, v2, v1, s33
	ds_write_b16_d16_hi v206, v1 offset:12144
	v_bfe_u32 v1, v0, 16, 1
	v_add3_u32 v1, v0, v1, s33
	ds_write_b16_d16_hi v206, v1 offset:12208
	v_mul_f32_e32 v1, v143, v0
	v_fma_f32 v1, v142, v2, -v1
	v_mul_f32_e32 v2, v143, v2
	v_add_f32_e32 v1, v16, v1
	v_fmac_f32_e32 v2, v142, v0
	v_add_f32_e32 v0, v17, v2
	v_bfe_u32 v2, v1, 16, 1
	v_add3_u32 v2, v1, v2, s33
	ds_write_b16_d16_hi v206, v2 offset:12672
	v_bfe_u32 v2, v0, 16, 1
	v_add3_u32 v2, v0, v2, s33
	ds_write_b16_d16_hi v206, v2 offset:12736
	v_mul_f32_e32 v2, v143, v0
	v_fma_f32 v2, v142, v1, -v2
	v_mul_f32_e32 v1, v143, v1
	v_add_f32_e32 v2, v18, v2
	v_fmac_f32_e32 v1, v142, v0
	v_add_f32_e32 v0, v19, v1
	v_bfe_u32 v1, v2, 16, 1
	v_add3_u32 v1, v2, v1, s33
	ds_write_b16_d16_hi v206, v1 offset:13200
	v_bfe_u32 v1, v0, 16, 1
	v_add3_u32 v1, v0, v1, s33
	ds_write_b16_d16_hi v206, v1 offset:13264
	v_mul_f32_e32 v1, v143, v0
	v_fma_f32 v1, v142, v2, -v1
	v_mul_f32_e32 v2, v143, v2
	s_waitcnt lgkmcnt(14)
	v_add_f32_e32 v1, v20, v1
	v_fmac_f32_e32 v2, v142, v0
	v_add_f32_e32 v0, v21, v2
	v_bfe_u32 v2, v1, 16, 1
	v_add3_u32 v2, v1, v2, s33
	ds_write_b16_d16_hi v206, v2 offset:13728
	v_bfe_u32 v2, v0, 16, 1
	v_add3_u32 v2, v0, v2, s33
	ds_write_b16_d16_hi v206, v2 offset:13792
	v_mul_f32_e32 v2, v143, v0
	v_fma_f32 v2, v142, v1, -v2
	v_mul_f32_e32 v1, v143, v1
	v_add_f32_e32 v2, v22, v2
	v_fmac_f32_e32 v1, v142, v0
	v_add_f32_e32 v0, v23, v1
	v_bfe_u32 v1, v2, 16, 1
	v_add3_u32 v1, v2, v1, s33
	ds_write_b16_d16_hi v206, v1 offset:14256
	v_bfe_u32 v1, v0, 16, 1
	v_add3_u32 v1, v0, v1, s33
	ds_write_b16_d16_hi v206, v1 offset:14320
	v_mul_f32_e32 v1, v143, v0
	v_fma_f32 v1, v142, v2, -v1
	v_mul_f32_e32 v2, v143, v2
	v_add_f32_e32 v1, v24, v1
	v_fmac_f32_e32 v2, v142, v0
	v_add_f32_e32 v0, v25, v2
	v_bfe_u32 v2, v1, 16, 1
	v_add3_u32 v2, v1, v2, s33
	ds_write_b16_d16_hi v206, v2 offset:14784
	v_bfe_u32 v2, v0, 16, 1
	v_add3_u32 v2, v0, v2, s33
	ds_write_b16_d16_hi v206, v2 offset:14848
	v_mul_f32_e32 v2, v143, v0
	v_fma_f32 v2, v142, v1, -v2
	v_add_f32_e32 v2, v26, v2
	v_mul_f32_e32 v1, v143, v1
	v_fmac_f32_e32 v1, v142, v0
	v_bfe_u32 v0, v2, 16, 1
	v_add_f32_e32 v1, v27, v1
	v_add3_u32 v0, v2, v0, s33
	ds_write_b16_d16_hi v206, v0 offset:15312
	v_bfe_u32 v0, v1, 16, 1
	v_add3_u32 v0, v1, v0, s33
	ds_write_b16_d16_hi v206, v0 offset:15376
	v_mul_f32_e32 v0, v143, v1
	v_fma_f32 v0, v142, v2, -v0
	v_add_f32_e32 v0, v28, v0
	v_mul_f32_e32 v2, v143, v2
	v_fmac_f32_e32 v2, v142, v1
	v_bfe_u32 v1, v0, 16, 1
	v_add_f32_e32 v2, v29, v2
	v_add3_u32 v1, v0, v1, s33
	ds_write_b16_d16_hi v206, v1 offset:15840
	v_bfe_u32 v1, v2, 16, 1
	v_add3_u32 v1, v2, v1, s33
	v_pk_mul_f32 v[2:3], v[148:149], v[2:3] op_sel_hi:[1,0]
	ds_write_b16_d16_hi v206, v1 offset:15904
	v_pk_fma_f32 v[4:5], v[142:143], v[0:1], v[2:3] neg_lo:[0,0,1] neg_hi:[0,0,1]
	v_pk_fma_f32 v[0:1], v[142:143], v[0:1], v[2:3] op_sel_hi:[1,0,1]
	v_add_u32_e32 v24, v133, v130
	v_mov_b32_e32 v5, v1
	v_pk_add_f32 v[150:151], v[30:31], v[4:5]
	s_nop 0
	v_bfe_u32 v0, v150, 16, 1
	v_add3_u32 v0, v150, v0, s33
	ds_write_b16_d16_hi v206, v0 offset:16368
	v_bfe_u32 v0, v151, 16, 1
	v_add3_u32 v0, v151, v0, s33
	ds_write_b16_d16_hi v206, v0 offset:16432
	s_waitcnt lgkmcnt(0)
	ds_read_b128 v[0:3], v24
	ds_read_b128 v[16:19], v24 offset:32
	s_waitcnt lgkmcnt(1)
	v_mfma_f32_32x32x16_bf16 v[0:15], v[0:3], v[80:83], 0
	s_waitcnt lgkmcnt(0)
	v_mfma_f32_32x32x16_bf16 v[0:15], v[16:19], v[84:87], v[0:15]
	ds_read_b128 v[16:19], v24 offset:64
	ds_read_b128 v[20:23], v24 offset:96
	s_waitcnt lgkmcnt(1)
	v_mfma_f32_32x32x16_bf16 v[0:15], v[16:19], v[88:91], v[0:15]
	s_waitcnt lgkmcnt(0)
	v_mfma_f32_32x32x16_bf16 v[0:15], v[20:23], v[92:95], v[0:15]
	ds_read_b128 v[16:19], v24 offset:128
	ds_read_b128 v[20:23], v24 offset:160
	s_waitcnt lgkmcnt(1)
	v_mfma_f32_32x32x16_bf16 v[0:15], v[16:19], v[96:99], v[0:15]
	s_waitcnt lgkmcnt(0)
	v_mfma_f32_32x32x16_bf16 v[0:15], v[20:23], v[100:103], v[0:15]
	ds_read_b128 v[16:19], v24 offset:192
	ds_read_b128 v[20:23], v24 offset:224
	s_waitcnt lgkmcnt(1)
	v_mfma_f32_32x32x16_bf16 v[0:15], v[16:19], v[104:107], v[0:15]
	s_waitcnt lgkmcnt(0)
	v_mfma_f32_32x32x16_bf16 v[0:15], v[20:23], v[108:111], v[0:15]
	v_mfma_f32_32x32x16_bf16 v[0:15], v[120:123], v[112:115], v[0:15]
	s_and_saveexec_b64 s[34:35], s[16:17]
	s_cbranch_execz .LBB0_527
	s_nop 9
	v_mul_f32_e32 v16, 0x3d372713, v0
	v_mul_f32_e32 v16, v0, v16
	v_fma_f32 v16, v0, v16, v0
	v_mul_f32_e32 v16, 0x3f4c422a, v16
	v_add_f32_e32 v16, v16, v16
	v_mul_f32_e32 v16, 0x3fb8aa3b, v16
	v_exp_f32_e32 v16, v16
	v_mul_f32_e32 v17, 0x3d372713, v1
	v_mul_f32_e32 v17, v1, v17
	v_fma_f32 v17, v1, v17, v1
	v_add_f32_e32 v16, 1.0, v16
	v_mul_f32_e32 v17, 0x3f4c422a, v17
	v_add_f32_e32 v17, v17, v17
	v_mul_f32_e32 v17, 0x3fb8aa3b, v17
	v_exp_f32_e32 v17, v17
	v_rcp_f32_e32 v18, v16
	s_nop 0
	v_mul_f32_e32 v16, v0, v18
	v_sub_f32_e32 v0, v0, v16
	v_add_f32_e32 v16, 1.0, v17
	v_bfe_u32 v19, v0, 16, 1
	v_add3_u32 v0, v0, v19, s33
	ds_write_b16_d16_hi v207, v0 offset:256
	v_mul_f32_e32 v17, 0x3d372713, v2
	v_mul_f32_e32 v17, v2, v17
	v_fma_f32 v17, v2, v17, v2
	v_mul_f32_e32 v17, 0x3f4c422a, v17
	v_add_f32_e32 v17, v17, v17
	v_mul_f32_e32 v17, 0x3fb8aa3b, v17
	v_exp_f32_e32 v17, v17
	v_rcp_f32_e32 v0, v16
	s_nop 0
	v_mul_f32_e32 v0, v1, v0
	v_sub_f32_e32 v0, v1, v0
	v_add_f32_e32 v1, 1.0, v17
	v_bfe_u32 v18, v0, 16, 1
	v_add3_u32 v0, v0, v18, s33
	ds_write_b16_d16_hi v208, v0 offset:256
	v_mul_f32_e32 v16, 0x3d372713, v3
	v_mul_f32_e32 v16, v3, v16
	v_fma_f32 v16, v3, v16, v3
	v_mul_f32_e32 v16, 0x3f4c422a, v16
	v_add_f32_e32 v16, v16, v16
	v_mul_f32_e32 v16, 0x3fb8aa3b, v16
	v_exp_f32_e32 v16, v16
	v_rcp_f32_e32 v0, v1
	s_nop 0
	v_mul_f32_e32 v0, v2, v0
	v_sub_f32_e32 v0, v2, v0
	v_add_f32_e32 v1, 1.0, v16
	v_bfe_u32 v17, v0, 16, 1
	v_add3_u32 v0, v0, v17, s33
	ds_write_b16_d16_hi v209, v0 offset:256
	v_mul_f32_e32 v2, 0x3d372713, v4
	v_mul_f32_e32 v2, v4, v2
	v_fma_f32 v2, v4, v2, v4
	v_mul_f32_e32 v2, 0x3f4c422a, v2
	v_add_f32_e32 v2, v2, v2
	v_mul_f32_e32 v2, 0x3fb8aa3b, v2
	v_exp_f32_e32 v2, v2
	v_rcp_f32_e32 v0, v1
	s_nop 0
	v_mul_f32_e32 v0, v3, v0
	v_sub_f32_e32 v0, v3, v0
	v_add_f32_e32 v1, 1.0, v2
	v_bfe_u32 v16, v0, 16, 1
	v_add3_u32 v0, v0, v16, s33
	ds_write_b16_d16_hi v210, v0 offset:256
	v_mul_f32_e32 v2, 0x3d372713, v5
	v_mul_f32_e32 v2, v5, v2
	v_fma_f32 v2, v5, v2, v5
	v_mul_f32_e32 v2, 0x3f4c422a, v2
	v_add_f32_e32 v2, v2, v2
	v_mul_f32_e32 v2, 0x3fb8aa3b, v2
	v_exp_f32_e32 v2, v2
	v_rcp_f32_e32 v0, v1
	s_nop 0
	v_mul_f32_e32 v0, v4, v0
	v_sub_f32_e32 v0, v4, v0
	v_add_f32_e32 v1, 1.0, v2
	v_bfe_u32 v4, v0, 16, 1
	v_add3_u32 v0, v0, v4, s33
	ds_write_b16_d16_hi v211, v0 offset:256
	v_mul_f32_e32 v2, 0x3d372713, v6
	v_mul_f32_e32 v2, v6, v2
	v_fma_f32 v2, v6, v2, v6
	v_mul_f32_e32 v2, 0x3f4c422a, v2
	v_add_f32_e32 v2, v2, v2
	v_mul_f32_e32 v2, 0x3fb8aa3b, v2
	v_exp_f32_e32 v2, v2
	v_rcp_f32_e32 v0, v1
	s_nop 0
	v_mul_f32_e32 v0, v5, v0
	v_sub_f32_e32 v0, v5, v0
	v_add_f32_e32 v1, 1.0, v2
	v_bfe_u32 v4, v0, 16, 1
	v_add3_u32 v0, v0, v4, s33
	ds_write_b16_d16_hi v212, v0 offset:256
	v_mul_f32_e32 v2, 0x3d372713, v7
	v_mul_f32_e32 v2, v7, v2
	v_fma_f32 v2, v7, v2, v7
	v_mul_f32_e32 v2, 0x3f4c422a, v2
	v_add_f32_e32 v2, v2, v2
	v_mul_f32_e32 v2, 0x3fb8aa3b, v2
	v_exp_f32_e32 v2, v2
	v_rcp_f32_e32 v0, v1
	s_nop 0
	v_mul_f32_e32 v0, v6, v0
	v_sub_f32_e32 v0, v6, v0
	v_add_f32_e32 v1, 1.0, v2
	v_bfe_u32 v4, v0, 16, 1
	v_add3_u32 v0, v0, v4, s33
	ds_write_b16_d16_hi v213, v0 offset:256
	v_mul_f32_e32 v2, 0x3d372713, v8
	v_mul_f32_e32 v2, v8, v2
	v_fma_f32 v2, v8, v2, v8
	v_mul_f32_e32 v2, 0x3f4c422a, v2
	v_add_f32_e32 v2, v2, v2
	v_mul_f32_e32 v2, 0x3fb8aa3b, v2
	v_exp_f32_e32 v2, v2
	v_rcp_f32_e32 v0, v1
	s_nop 0
	v_mul_f32_e32 v0, v7, v0
	v_sub_f32_e32 v0, v7, v0
	v_add_f32_e32 v1, 1.0, v2
	v_bfe_u32 v4, v0, 16, 1
	v_add3_u32 v0, v0, v4, s33
	ds_write_b16_d16_hi v214, v0 offset:256
	v_mul_f32_e32 v2, 0x3d372713, v9
	v_mul_f32_e32 v2, v9, v2
	v_fma_f32 v2, v9, v2, v9
	v_mul_f32_e32 v2, 0x3f4c422a, v2
	v_add_f32_e32 v2, v2, v2
	v_mul_f32_e32 v2, 0x3fb8aa3b, v2
	v_exp_f32_e32 v2, v2
	v_rcp_f32_e32 v0, v1
	s_nop 0
	v_mul_f32_e32 v0, v8, v0
	v_sub_f32_e32 v0, v8, v0
	v_add_f32_e32 v1, 1.0, v2
	v_bfe_u32 v4, v0, 16, 1
	v_add3_u32 v0, v0, v4, s33
	ds_write_b16_d16_hi v215, v0 offset:256
	v_mul_f32_e32 v2, 0x3d372713, v10
	v_mul_f32_e32 v2, v10, v2
	v_fma_f32 v2, v10, v2, v10
	v_mul_f32_e32 v2, 0x3f4c422a, v2
	v_add_f32_e32 v2, v2, v2
	v_mul_f32_e32 v2, 0x3fb8aa3b, v2
	v_exp_f32_e32 v2, v2
	v_rcp_f32_e32 v0, v1
	s_nop 0
	v_mul_f32_e32 v0, v9, v0
	v_sub_f32_e32 v0, v9, v0
	v_add_f32_e32 v1, 1.0, v2
	v_bfe_u32 v4, v0, 16, 1
	v_add3_u32 v0, v0, v4, s33
	ds_write_b16_d16_hi v216, v0 offset:256
	v_mul_f32_e32 v2, 0x3d372713, v11
	v_mul_f32_e32 v2, v11, v2
	v_fma_f32 v2, v11, v2, v11
	v_mul_f32_e32 v2, 0x3f4c422a, v2
	v_add_f32_e32 v2, v2, v2
	v_mul_f32_e32 v2, 0x3fb8aa3b, v2
	v_exp_f32_e32 v2, v2
	v_rcp_f32_e32 v0, v1
	s_nop 0
	v_mul_f32_e32 v0, v10, v0
	v_sub_f32_e32 v0, v10, v0
	v_add_f32_e32 v1, 1.0, v2
	v_bfe_u32 v4, v0, 16, 1
	v_add3_u32 v0, v0, v4, s33
	ds_write_b16_d16_hi v217, v0 offset:256
	v_mul_f32_e32 v2, 0x3d372713, v12
	v_mul_f32_e32 v2, v12, v2
	v_fma_f32 v2, v12, v2, v12
	v_mul_f32_e32 v2, 0x3f4c422a, v2
	v_add_f32_e32 v2, v2, v2
	v_mul_f32_e32 v2, 0x3fb8aa3b, v2
	v_exp_f32_e32 v2, v2
	v_rcp_f32_e32 v0, v1
	s_nop 0
	v_mul_f32_e32 v0, v11, v0
	v_sub_f32_e32 v0, v11, v0
	v_add_f32_e32 v1, 1.0, v2
	v_bfe_u32 v4, v0, 16, 1
	v_add3_u32 v0, v0, v4, s33
	ds_write_b16_d16_hi v218, v0 offset:256
	v_mul_f32_e32 v2, 0x3d372713, v13
	v_mul_f32_e32 v2, v13, v2
	v_fma_f32 v2, v13, v2, v13
	v_mul_f32_e32 v2, 0x3f4c422a, v2
	v_add_f32_e32 v2, v2, v2
	v_mul_f32_e32 v2, 0x3fb8aa3b, v2
	v_exp_f32_e32 v2, v2
	v_rcp_f32_e32 v0, v1
	s_nop 0
	v_mul_f32_e32 v0, v12, v0
	v_sub_f32_e32 v0, v12, v0
	v_add_f32_e32 v1, 1.0, v2
	v_bfe_u32 v4, v0, 16, 1
	v_add3_u32 v0, v0, v4, s33
	ds_write_b16_d16_hi v219, v0 offset:256
	v_mul_f32_e32 v2, 0x3d372713, v14
	v_mul_f32_e32 v2, v14, v2
	v_fma_f32 v2, v14, v2, v14
	v_mul_f32_e32 v2, 0x3f4c422a, v2
	v_add_f32_e32 v2, v2, v2
	v_mul_f32_e32 v2, 0x3fb8aa3b, v2
	v_exp_f32_e32 v2, v2
	v_rcp_f32_e32 v0, v1
	s_nop 0
	v_mul_f32_e32 v0, v13, v0
	v_sub_f32_e32 v0, v13, v0
	v_add_f32_e32 v1, 1.0, v2
	v_bfe_u32 v4, v0, 16, 1
	v_add3_u32 v0, v0, v4, s33
	ds_write_b16_d16_hi v220, v0 offset:256
	v_mul_f32_e32 v2, 0x3d372713, v15
	v_mul_f32_e32 v2, v15, v2
	v_fma_f32 v2, v15, v2, v15
	v_mul_f32_e32 v2, 0x3f4c422a, v2
	v_add_f32_e32 v2, v2, v2
	v_mul_f32_e32 v2, 0x3fb8aa3b, v2
	v_exp_f32_e32 v2, v2
	v_rcp_f32_e32 v0, v1
	s_nop 0
	v_mul_f32_e32 v0, v14, v0
	v_sub_f32_e32 v0, v14, v0
	v_add_f32_e32 v1, 1.0, v2
	v_bfe_u32 v4, v0, 16, 1
	v_add3_u32 v0, v0, v4, s33
	ds_write_b16_d16_hi v221, v0 offset:256
	v_rcp_f32_e32 v0, v1
	s_nop 0
	v_mul_f32_e32 v0, v15, v0
	v_sub_f32_e32 v0, v15, v0
	v_bfe_u32 v1, v0, 16, 1
	v_add3_u32 v0, v0, v1, s33
	ds_write_b16_d16_hi v222, v0 offset:256

.LBB0_785:
	s_waitcnt vmcnt(5)
	v_add_u32_e32 v11, v56, v194
	s_waitcnt lgkmcnt(0)
	ds_read_b128 v[0:3], v11
	ds_read_b128 v[4:7], v11 offset:1024
	v_lshlrev_b64 v[32:33], 1, v[52:53]
	v_lshl_add_u64 v[66:67], s[58:59], 0, v[32:33]
	v_lshl_add_u64 v[68:69], s[56:57], 0, v[32:33]
	s_waitcnt lgkmcnt(1)
	v_max_f32_e32 v8, v3, v3
	v_max_f32_e32 v9, v2, v2
	v_max_f32_e32 v8, v9, v8
	v_max3_f32 v8, v0, v1, v8
	v_add3_u32 v32, v56, v209, v208
	v_add3_u32 v33, v56, v211, v210
	v_mov_b32_dpp v9, v8 quad_perm:[1,0,3,2] row_mask:0xf bank_mask:0xf bound_ctrl:1
	v_max_f32_e32 v9, v9, v9
	v_max_f32_e32 v8, v8, v9
	v_add3_u32 v34, v56, v212, v208
	v_add3_u32 v35, v56, v213, v210
	v_mov_b32_dpp v9, v8 quad_perm:[2,3,0,1] row_mask:0xf bank_mask:0xf bound_ctrl:1
	v_max_f32_e32 v9, v9, v9
	v_max_f32_e32 v8, v8, v9
	s_waitcnt vmcnt(0)
	v_add3_u32 v36, v56, v214, v208
	v_add3_u32 v37, v56, v215, v210
	v_mov_b32_dpp v9, v8 row_half_mirror row_mask:0xf bank_mask:0xf bound_ctrl:1
	v_max_f32_e32 v9, v9, v9
	v_max_f32_e32 v8, v8, v9
	v_add3_u32 v38, v56, v216, v208
	v_add3_u32 v39, v56, v217, v210
	v_mov_b32_dpp v9, v8 row_mirror row_mask:0xf bank_mask:0xf bound_ctrl:1
	v_max_f32_e32 v9, v9, v9
	v_max_f32_e32 v8, v8, v9
	v_add3_u32 v40, v56, v218, v208
	v_readlane_b32 s2, v8, 32
	v_readlane_b32 s20, v8, 48
	v_readlane_b32 s0, v8, 0
	v_readlane_b32 s1, v8, 16
	v_max_f32_e64 v8, s20, s20
	v_max_f32_e64 v9, s2, s2
	v_max_f32_e32 v8, v9, v8
	v_mov_b32_e32 v9, s1
	v_max3_f32 v8, s0, v9, v8
	v_sub_f32_e32 v0, v0, v8
	v_sub_f32_e32 v1, v1, v8
	v_mul_f32_e32 v0, 0x3fb8aa3b, v0
	v_mul_f32_e32 v1, 0x3fb8aa3b, v1
	v_sub_f32_e32 v2, v2, v8
	v_exp_f32_e32 v0, v0
	v_exp_f32_e32 v1, v1
	v_mul_f32_e32 v2, 0x3fb8aa3b, v2
	v_sub_f32_e32 v3, v3, v8
	v_exp_f32_e32 v2, v2
	v_mul_f32_e32 v3, 0x3fb8aa3b, v3
	v_exp_f32_e32 v3, v3
	v_add_f32_e32 v8, v0, v1
	v_add_f32_e32 v8, v2, v8
	v_add3_u32 v41, v56, v219, v210
	v_add_f32_e32 v8, v3, v8
	v_add3_u32 v42, v56, v220, v208
	v_add3_u32 v43, v56, v221, v210
	v_add_f32_dpp v8, v8, v8 quad_perm:[1,0,3,2] row_mask:0xf bank_mask:0xf bound_ctrl:1
	v_add3_u32 v44, v56, v222, v208
	v_add3_u32 v45, v56, v223, v210
	v_add_f32_dpp v8, v8, v8 quad_perm:[2,3,0,1] row_mask:0xf bank_mask:0xf bound_ctrl:1
	v_add3_u32 v46, v56, v224, v208
	v_add3_u32 v47, v56, v225, v210
	v_add_f32_dpp v8, v8, v8 row_half_mirror row_mask:0xf bank_mask:0xf bound_ctrl:1
	v_add3_u32 v77, v56, v207, v148
	v_add_u32_e32 v78, v32, v206
	v_add_f32_dpp v8, v8, v8 row_mirror row_mask:0xf bank_mask:0xf bound_ctrl:1
	v_add_u32_e32 v79, v33, v206
	v_readlane_b32 s1, v8, 16
	v_readlane_b32 s20, v8, 48
	v_readlane_b32 s0, v8, 0
	v_readlane_b32 s2, v8, 32
	v_mov_b32_e32 v8, s1
	v_mov_b32_e32 v9, s20
	v_add_f32_e32 v8, s0, v8
	v_add_f32_e32 v9, s2, v9
	v_add_f32_e32 v8, v8, v9
	v_add_u32_e32 v80, v34, v206
	v_add_u32_e32 v81, v35, v206
	v_add_u32_e32 v82, v36, v206
	v_rcp_f32_e32 v8, v8
	s_nop 0
	v_mul_f32_e32 v0, v0, v8
	v_mul_f32_e32 v1, v1, v8
	v_bfe_u32 v9, v0, 16, 1
	v_add3_u32 v0, v0, v9, s79
	v_bfe_u32 v9, v1, 16, 1
	v_lshrrev_b32_e32 v0, 16, v0
	v_add3_u32 v1, v1, v9, s79
	v_and_or_b32 v0, v1, s80, v0
	v_mul_f32_e32 v1, v2, v8
	v_mul_f32_e32 v2, v3, v8
	v_bfe_u32 v3, v1, 16, 1
	v_add3_u32 v1, v1, v3, s79
	s_waitcnt lgkmcnt(0)
	v_max_f32_e32 v3, v7, v7
	v_max_f32_e32 v8, v6, v6
	v_max_f32_e32 v3, v8, v3
	v_max3_f32 v3, v4, v5, v3
	v_bfe_u32 v10, v2, 16, 1
	v_lshrrev_b32_e32 v1, 16, v1
	v_mov_b32_dpp v8, v3 quad_perm:[1,0,3,2] row_mask:0xf bank_mask:0xf bound_ctrl:1
	v_max_f32_e32 v8, v8, v8
	v_max_f32_e32 v3, v3, v8
	v_add3_u32 v2, v2, v10, s79
	v_and_or_b32 v1, v2, s80, v1
	v_mov_b32_dpp v8, v3 quad_perm:[2,3,0,1] row_mask:0xf bank_mask:0xf bound_ctrl:1
	v_max_f32_e32 v8, v8, v8
	v_max_f32_e32 v3, v3, v8
	v_add_u32_e32 v83, v37, v206
	v_add_u32_e32 v84, v38, v206
	v_mov_b32_dpp v8, v3 row_half_mirror row_mask:0xf bank_mask:0xf bound_ctrl:1
	v_max_f32_e32 v8, v8, v8
	v_max_f32_e32 v3, v3, v8
	v_add_u32_e32 v85, v39, v206
	v_add_u32_e32 v86, v40, v206
	v_mov_b32_dpp v8, v3 row_mirror row_mask:0xf bank_mask:0xf bound_ctrl:1
	v_max_f32_e32 v8, v8, v8
	v_max_f32_e32 v3, v3, v8
	v_add_u32_e32 v87, v41, v206
	v_readlane_b32 s2, v3, 32
	v_readlane_b32 s20, v3, 48
	v_readlane_b32 s0, v3, 0
	v_readlane_b32 s1, v3, 16
	v_max_f32_e64 v3, s20, s20
	v_max_f32_e64 v8, s2, s2
	v_max_f32_e32 v3, v8, v3
	v_mov_b32_e32 v8, s1
	v_max3_f32 v3, s0, v8, v3
	v_sub_f32_e32 v4, v4, v3
	v_sub_f32_e32 v5, v5, v3
	v_mul_f32_e32 v4, 0x3fb8aa3b, v4
	v_mul_f32_e32 v5, 0x3fb8aa3b, v5
	v_sub_f32_e32 v6, v6, v3
	v_exp_f32_e32 v4, v4
	v_exp_f32_e32 v5, v5
	v_mul_f32_e32 v6, 0x3fb8aa3b, v6
	v_sub_f32_e32 v3, v7, v3
	v_exp_f32_e32 v6, v6
	v_mul_f32_e32 v3, 0x3fb8aa3b, v3
	v_exp_f32_e32 v3, v3
	v_add_f32_e32 v7, v4, v5
	v_add_f32_e32 v7, v6, v7
	v_add_u32_e32 v88, v42, v206
	v_add_f32_e32 v7, v3, v7
	v_add_u32_e32 v89, v43, v206
	v_add_u32_e32 v90, v44, v206
	v_add_f32_dpp v7, v7, v7 quad_perm:[1,0,3,2] row_mask:0xf bank_mask:0xf bound_ctrl:1
	v_add_u32_e32 v91, v45, v206
	v_add_u32_e32 v92, v46, v206
	v_add_f32_dpp v7, v7, v7 quad_perm:[2,3,0,1] row_mask:0xf bank_mask:0xf bound_ctrl:1
	v_add_u32_e32 v93, v47, v206
	s_nop 0
	v_add_f32_dpp v7, v7, v7 row_half_mirror row_mask:0xf bank_mask:0xf bound_ctrl:1
	s_nop 1
	v_add_f32_dpp v7, v7, v7 row_mirror row_mask:0xf bank_mask:0xf bound_ctrl:1
	s_nop 0
	v_readlane_b32 s1, v7, 16
	v_readlane_b32 s20, v7, 48
	v_readlane_b32 s0, v7, 0
	v_readlane_b32 s2, v7, 32
	v_mov_b32_e32 v7, s1
	v_mov_b32_e32 v8, s20
	v_add_f32_e32 v7, s0, v7
	v_add_f32_e32 v8, s2, v8
	v_add_f32_e32 v7, v7, v8
	s_nop 0
	v_rcp_f32_e32 v8, v7
	s_nop 0
	v_mul_f32_e32 v2, v4, v8
	v_mul_f32_e32 v4, v5, v8
	v_bfe_u32 v5, v2, 16, 1
	v_add3_u32 v2, v2, v5, s79
	v_bfe_u32 v5, v4, 16, 1
	v_lshrrev_b32_e32 v2, 16, v2
	v_add3_u32 v4, v4, v5, s79
	v_and_or_b32 v2, v4, s80, v2
	v_mul_f32_e32 v9, v6, v8
	ds_read_b128 v[4:7], v11 offset:2048
	v_mul_f32_e32 v3, v3, v8
	v_bfe_u32 v8, v9, 16, 1
	v_add3_u32 v8, v9, v8, s79
	v_bfe_u32 v17, v3, 16, 1
	s_waitcnt lgkmcnt(0)
	v_max_f32_e32 v9, v7, v7
	v_max_f32_e32 v10, v6, v6
	v_max_f32_e32 v9, v10, v9
	v_max3_f32 v9, v4, v5, v9
	v_lshrrev_b32_e32 v8, 16, v8
	v_add3_u32 v3, v3, v17, s79
	v_mov_b32_dpp v10, v9 quad_perm:[1,0,3,2] row_mask:0xf bank_mask:0xf bound_ctrl:1
	v_max_f32_e32 v10, v10, v10
	v_max_f32_e32 v9, v9, v10
	v_and_or_b32 v3, v3, s80, v8
	ds_read_b128 v[12:15], v11 offset:3072
	v_mov_b32_dpp v10, v9 quad_perm:[2,3,0,1] row_mask:0xf bank_mask:0xf bound_ctrl:1
	v_max_f32_e32 v10, v10, v10
	v_max_f32_e32 v9, v9, v10
	s_nop 1
	v_mov_b32_dpp v10, v9 row_half_mirror row_mask:0xf bank_mask:0xf bound_ctrl:1
	v_max_f32_e32 v10, v10, v10
	v_max_f32_e32 v9, v9, v10
	s_nop 1
	v_mov_b32_dpp v10, v9 row_mirror row_mask:0xf bank_mask:0xf bound_ctrl:1
	v_max_f32_e32 v10, v10, v10
	v_max_f32_e32 v9, v9, v10
	s_nop 0
	v_readlane_b32 s2, v9, 32
	v_readlane_b32 s20, v9, 48
	v_readlane_b32 s0, v9, 0
	v_readlane_b32 s1, v9, 16
	v_max_f32_e64 v9, s20, s20
	v_max_f32_e64 v10, s2, s2
	v_max_f32_e32 v9, v10, v9
	v_mov_b32_e32 v10, s1
	v_max3_f32 v9, s0, v10, v9
	v_sub_f32_e32 v4, v4, v9
	v_sub_f32_e32 v5, v5, v9
	v_mul_f32_e32 v4, 0x3fb8aa3b, v4
	v_mul_f32_e32 v5, 0x3fb8aa3b, v5
	v_sub_f32_e32 v6, v6, v9
	v_exp_f32_e32 v4, v4
	v_exp_f32_e32 v5, v5
	v_mul_f32_e32 v6, 0x3fb8aa3b, v6
	v_sub_f32_e32 v7, v7, v9
	v_exp_f32_e32 v6, v6
	v_mul_f32_e32 v7, 0x3fb8aa3b, v7
	v_exp_f32_e32 v7, v7
	v_add_f32_e32 v9, v4, v5
	v_add_f32_e32 v9, v6, v9
	v_add_f32_e32 v9, v7, v9
	s_nop 1
	v_add_f32_dpp v9, v9, v9 quad_perm:[1,0,3,2] row_mask:0xf bank_mask:0xf bound_ctrl:1
	s_nop 1
	v_add_f32_dpp v9, v9, v9 quad_perm:[2,3,0,1] row_mask:0xf bank_mask:0xf bound_ctrl:1
	s_nop 1
	v_add_f32_dpp v9, v9, v9 row_half_mirror row_mask:0xf bank_mask:0xf bound_ctrl:1
	s_nop 1
	v_add_f32_dpp v9, v9, v9 row_mirror row_mask:0xf bank_mask:0xf bound_ctrl:1
	s_nop 0
	v_readlane_b32 s1, v9, 16
	v_readlane_b32 s20, v9, 48
	v_readlane_b32 s0, v9, 0
	v_readlane_b32 s2, v9, 32
	v_mov_b32_e32 v9, s1
	v_mov_b32_e32 v10, s20
	v_add_f32_e32 v9, s0, v9
	v_add_f32_e32 v10, s2, v10
	v_add_f32_e32 v9, v9, v10
	s_nop 0
	v_rcp_f32_e32 v8, v9
	s_nop 0
	v_mul_f32_e32 v4, v4, v8
	v_mul_f32_e32 v5, v5, v8
	v_bfe_u32 v9, v4, 16, 1
	v_add3_u32 v4, v4, v9, s79
	v_bfe_u32 v9, v5, 16, 1
	v_lshrrev_b32_e32 v4, 16, v4
	v_add3_u32 v5, v5, v9, s79
	v_and_or_b32 v4, v5, s80, v4
	v_mul_f32_e32 v5, v6, v8
	v_mul_f32_e32 v6, v7, v8
	v_bfe_u32 v7, v5, 16, 1
	v_add3_u32 v5, v5, v7, s79
	s_waitcnt lgkmcnt(0)
	v_max_f32_e32 v7, v15, v15
	v_max_f32_e32 v8, v14, v14
	v_max_f32_e32 v7, v8, v7
	v_max3_f32 v7, v12, v13, v7
	v_lshrrev_b32_e32 v5, 16, v5
	s_nop 0
	v_mov_b32_dpp v8, v7 quad_perm:[1,0,3,2] row_mask:0xf bank_mask:0xf bound_ctrl:1
	v_max_f32_e32 v8, v8, v8
	v_max_f32_e32 v7, v7, v8
	s_nop 1
	v_mov_b32_dpp v8, v7 quad_perm:[2,3,0,1] row_mask:0xf bank_mask:0xf bound_ctrl:1
	v_max_f32_e32 v8, v8, v8
	v_max_f32_e32 v7, v7, v8
	s_nop 1
	v_mov_b32_dpp v8, v7 row_half_mirror row_mask:0xf bank_mask:0xf bound_ctrl:1
	v_max_f32_e32 v8, v8, v8
	v_max_f32_e32 v7, v7, v8
	s_nop 1
	v_mov_b32_dpp v8, v7 row_mirror row_mask:0xf bank_mask:0xf bound_ctrl:1
	v_max_f32_e32 v8, v8, v8
	v_max_f32_e32 v7, v7, v8
	s_nop 0
	v_readlane_b32 s2, v7, 32
	v_readlane_b32 s20, v7, 48
	v_readlane_b32 s0, v7, 0
	v_readlane_b32 s1, v7, 16
	v_max_f32_e64 v7, s20, s20
	v_max_f32_e64 v8, s2, s2
	v_max_f32_e32 v7, v8, v7
	v_mov_b32_e32 v8, s1
	v_max3_f32 v7, s0, v8, v7
	v_sub_f32_e32 v8, v12, v7
	v_sub_f32_e32 v9, v13, v7
	v_mul_f32_e32 v8, 0x3fb8aa3b, v8
	v_mul_f32_e32 v9, 0x3fb8aa3b, v9
	v_sub_f32_e32 v10, v14, v7
	v_exp_f32_e32 v8, v8
	v_exp_f32_e32 v9, v9
	v_mul_f32_e32 v10, 0x3fb8aa3b, v10
	v_sub_f32_e32 v7, v15, v7
	v_exp_f32_e32 v10, v10
	v_mul_f32_e32 v7, 0x3fb8aa3b, v7
	v_exp_f32_e32 v7, v7
	v_add_f32_e32 v12, v8, v9
	v_add_f32_e32 v12, v10, v12
	v_bfe_u32 v15, v6, 16, 1
	v_add_f32_e32 v12, v7, v12
	v_add3_u32 v6, v6, v15, s79
	v_and_or_b32 v5, v6, s80, v5
	v_add_f32_dpp v12, v12, v12 quad_perm:[1,0,3,2] row_mask:0xf bank_mask:0xf bound_ctrl:1
	s_nop 1
	v_add_f32_dpp v12, v12, v12 quad_perm:[2,3,0,1] row_mask:0xf bank_mask:0xf bound_ctrl:1
	s_nop 1
	v_add_f32_dpp v12, v12, v12 row_half_mirror row_mask:0xf bank_mask:0xf bound_ctrl:1
	s_nop 1
	v_add_f32_dpp v12, v12, v12 row_mirror row_mask:0xf bank_mask:0xf bound_ctrl:1
	s_nop 0
	v_readlane_b32 s1, v12, 16
	v_readlane_b32 s20, v12, 48
	v_readlane_b32 s0, v12, 0
	v_readlane_b32 s2, v12, 32
	v_mov_b32_e32 v12, s1
	v_mov_b32_e32 v13, s20
	v_add_f32_e32 v12, s0, v12
	v_add_f32_e32 v13, s2, v13
	v_add_f32_e32 v12, v12, v13
	s_nop 0
	v_rcp_f32_e32 v16, v12
	s_nop 0
	v_mul_f32_e32 v6, v8, v16
	v_mul_f32_e32 v8, v9, v16
	v_bfe_u32 v9, v6, 16, 1
	ds_read_b128 v[12:15], v11 offset:4096
	v_add3_u32 v6, v6, v9, s79
	v_bfe_u32 v9, v8, 16, 1
	v_lshrrev_b32_e32 v6, 16, v6
	v_add3_u32 v8, v8, v9, s79
	v_and_or_b32 v6, v8, s80, v6
	v_mul_f32_e32 v8, v10, v16
	v_bfe_u32 v9, v8, 16, 1
	v_add3_u32 v8, v8, v9, s79
	s_waitcnt lgkmcnt(0)
	v_max_f32_e32 v9, v15, v15
	v_max_f32_e32 v10, v14, v14
	v_max_f32_e32 v9, v10, v9
	v_max3_f32 v9, v12, v13, v9
	v_mul_f32_e32 v7, v7, v16
	v_bfe_u32 v21, v7, 16, 1
	v_mov_b32_dpp v10, v9 quad_perm:[1,0,3,2] row_mask:0xf bank_mask:0xf bound_ctrl:1
	v_max_f32_e32 v10, v10, v10
	v_max_f32_e32 v9, v9, v10
	v_lshrrev_b32_e32 v8, 16, v8
	v_add3_u32 v7, v7, v21, s79
	v_mov_b32_dpp v10, v9 quad_perm:[2,3,0,1] row_mask:0xf bank_mask:0xf bound_ctrl:1
	v_max_f32_e32 v10, v10, v10
	v_max_f32_e32 v9, v9, v10
	v_and_or_b32 v7, v7, s80, v8
	ds_read_b128 v[16:19], v11 offset:5120
	v_mov_b32_dpp v10, v9 row_half_mirror row_mask:0xf bank_mask:0xf bound_ctrl:1
	v_max_f32_e32 v10, v10, v10
	v_max_f32_e32 v9, v9, v10
	s_nop 1
	v_mov_b32_dpp v10, v9 row_mirror row_mask:0xf bank_mask:0xf bound_ctrl:1
	v_max_f32_e32 v10, v10, v10
	v_max_f32_e32 v9, v9, v10
	s_nop 0
	v_readlane_b32 s2, v9, 32
	v_readlane_b32 s20, v9, 48
	v_readlane_b32 s0, v9, 0
	v_readlane_b32 s1, v9, 16
	v_max_f32_e64 v9, s20, s20
	v_max_f32_e64 v10, s2, s2
	v_max_f32_e32 v9, v10, v9
	v_mov_b32_e32 v10, s1
	v_max3_f32 v9, s0, v10, v9
	v_sub_f32_e32 v10, v12, v9
	v_sub_f32_e32 v12, v13, v9
	v_mul_f32_e32 v10, 0x3fb8aa3b, v10
	v_mul_f32_e32 v12, 0x3fb8aa3b, v12
	v_sub_f32_e32 v13, v14, v9
	v_exp_f32_e32 v10, v10
	v_exp_f32_e32 v12, v12
	v_mul_f32_e32 v13, 0x3fb8aa3b, v13
	v_sub_f32_e32 v9, v15, v9
	v_exp_f32_e32 v13, v13
	v_mul_f32_e32 v9, 0x3fb8aa3b, v9
	v_exp_f32_e32 v9, v9
	v_add_f32_e32 v14, v10, v12
	v_add_f32_e32 v14, v13, v14
	v_add_f32_e32 v14, v9, v14
	s_nop 1
	v_add_f32_dpp v14, v14, v14 quad_perm:[1,0,3,2] row_mask:0xf bank_mask:0xf bound_ctrl:1
	s_nop 1
	v_add_f32_dpp v14, v14, v14 quad_perm:[2,3,0,1] row_mask:0xf bank_mask:0xf bound_ctrl:1
	s_nop 1
	v_add_f32_dpp v14, v14, v14 row_half_mirror row_mask:0xf bank_mask:0xf bound_ctrl:1
	s_nop 1
	v_add_f32_dpp v14, v14, v14 row_mirror row_mask:0xf bank_mask:0xf bound_ctrl:1
	s_nop 0
	v_readlane_b32 s1, v14, 16
	v_readlane_b32 s20, v14, 48
	v_readlane_b32 s0, v14, 0
	v_readlane_b32 s2, v14, 32
	v_mov_b32_e32 v14, s1
	v_mov_b32_e32 v15, s20
	v_add_f32_e32 v14, s0, v14
	v_add_f32_e32 v15, s2, v15
	v_add_f32_e32 v14, v14, v15
	s_nop 0
	v_rcp_f32_e32 v14, v14
	s_nop 0
	v_mul_f32_e32 v8, v10, v14
	v_mul_f32_e32 v10, v12, v14
	v_bfe_u32 v12, v8, 16, 1
	v_add3_u32 v8, v8, v12, s79
	v_bfe_u32 v12, v10, 16, 1
	v_lshrrev_b32_e32 v8, 16, v8
	v_add3_u32 v10, v10, v12, s79
	v_and_or_b32 v8, v10, s80, v8
	v_mul_f32_e32 v10, v13, v14
	v_bfe_u32 v12, v10, 16, 1
	v_add3_u32 v10, v10, v12, s79
	s_waitcnt lgkmcnt(0)
	v_max_f32_e32 v12, v19, v19
	v_max_f32_e32 v13, v18, v18
	v_max_f32_e32 v12, v13, v12
	v_max3_f32 v12, v16, v17, v12
	v_mul_f32_e32 v9, v9, v14
	v_lshrrev_b32_e32 v10, 16, v10
	v_mov_b32_dpp v13, v12 quad_perm:[1,0,3,2] row_mask:0xf bank_mask:0xf bound_ctrl:1
	v_max_f32_e32 v13, v13, v13
	v_max_f32_e32 v12, v12, v13
	s_nop 1
	v_mov_b32_dpp v13, v12 quad_perm:[2,3,0,1] row_mask:0xf bank_mask:0xf bound_ctrl:1
	v_max_f32_e32 v13, v13, v13
	v_max_f32_e32 v12, v12, v13
	s_nop 1
	v_mov_b32_dpp v13, v12 row_half_mirror row_mask:0xf bank_mask:0xf bound_ctrl:1
	v_max_f32_e32 v13, v13, v13
	v_max_f32_e32 v12, v12, v13
	s_nop 1
	v_mov_b32_dpp v13, v12 row_mirror row_mask:0xf bank_mask:0xf bound_ctrl:1
	v_max_f32_e32 v13, v13, v13
	v_max_f32_e32 v12, v12, v13
	s_nop 0
	v_readlane_b32 s2, v12, 32
	v_readlane_b32 s20, v12, 48
	v_readlane_b32 s0, v12, 0
	v_readlane_b32 s1, v12, 16
	v_max_f32_e64 v12, s20, s20
	v_max_f32_e64 v13, s2, s2
	v_max_f32_e32 v12, v13, v12
	v_mov_b32_e32 v13, s1
	v_max3_f32 v12, s0, v13, v12
	v_sub_f32_e32 v13, v16, v12
	v_sub_f32_e32 v14, v17, v12
	v_mul_f32_e32 v13, 0x3fb8aa3b, v13
	v_mul_f32_e32 v14, 0x3fb8aa3b, v14
	v_sub_f32_e32 v15, v18, v12
	v_exp_f32_e32 v13, v13
	v_exp_f32_e32 v14, v14
	v_mul_f32_e32 v15, 0x3fb8aa3b, v15
	v_sub_f32_e32 v12, v19, v12
	v_exp_f32_e32 v15, v15
	v_mul_f32_e32 v12, 0x3fb8aa3b, v12
	v_exp_f32_e32 v16, v12
	v_add_f32_e32 v12, v13, v14
	v_add_f32_e32 v12, v15, v12
	v_bfe_u32 v19, v9, 16, 1
	v_add_f32_e32 v12, v16, v12
	v_add3_u32 v9, v9, v19, s79
	v_and_or_b32 v9, v9, s80, v10
	v_add_f32_dpp v12, v12, v12 quad_perm:[1,0,3,2] row_mask:0xf bank_mask:0xf bound_ctrl:1
	s_nop 1
	v_add_f32_dpp v12, v12, v12 quad_perm:[2,3,0,1] row_mask:0xf bank_mask:0xf bound_ctrl:1
	s_nop 1
	v_add_f32_dpp v12, v12, v12 row_half_mirror row_mask:0xf bank_mask:0xf bound_ctrl:1
	s_nop 1
	v_add_f32_dpp v12, v12, v12 row_mirror row_mask:0xf bank_mask:0xf bound_ctrl:1
	s_nop 0
	v_readlane_b32 s1, v12, 16
	v_readlane_b32 s20, v12, 48
	v_readlane_b32 s0, v12, 0
	v_readlane_b32 s2, v12, 32
	v_mov_b32_e32 v12, s1
	v_mov_b32_e32 v17, s20
	v_add_f32_e32 v12, s0, v12
	v_add_f32_e32 v17, s2, v17
	v_add_f32_e32 v12, v12, v17
	s_nop 0
	v_rcp_f32_e32 v17, v12
	s_nop 0
	v_mul_f32_e32 v10, v13, v17
	v_mul_f32_e32 v12, v14, v17
	v_bfe_u32 v13, v10, 16, 1
	v_add3_u32 v10, v10, v13, s79
	v_bfe_u32 v13, v12, 16, 1
	v_lshrrev_b32_e32 v10, 16, v10
	v_add3_u32 v12, v12, v13, s79
	v_and_or_b32 v10, v12, s80, v10
	v_mul_f32_e32 v18, v15, v17
	ds_read_b128 v[12:15], v11 offset:6144
	v_mul_f32_e32 v20, v16, v17
	v_bfe_u32 v16, v18, 16, 1
	v_add3_u32 v21, v18, v16, s79
	ds_read_b128 v[16:19], v11 offset:7168
	s_waitcnt lgkmcnt(1)
	v_max_f32_e32 v11, v15, v15
	v_max_f32_e32 v22, v14, v14
	v_max_f32_e32 v11, v22, v11
	v_max3_f32 v11, v12, v13, v11
	v_bfe_u32 v24, v20, 16, 1
	v_add3_u32 v20, v20, v24, s79
	v_mov_b32_dpp v22, v11 quad_perm:[1,0,3,2] row_mask:0xf bank_mask:0xf bound_ctrl:1
	v_max_f32_e32 v22, v22, v22
	v_max_f32_e32 v11, v11, v22
	s_waitcnt lgkmcnt(0)
	s_nop 1
	v_mov_b32_dpp v22, v11 quad_perm:[2,3,0,1] row_mask:0xf bank_mask:0xf bound_ctrl:1
	v_max_f32_e32 v22, v22, v22
	v_max_f32_e32 v11, v11, v22
	s_nop 1
	v_mov_b32_dpp v22, v11 row_half_mirror row_mask:0xf bank_mask:0xf bound_ctrl:1
	v_max_f32_e32 v22, v22, v22
	v_max_f32_e32 v11, v11, v22
	s_nop 1
	v_mov_b32_dpp v22, v11 row_mirror row_mask:0xf bank_mask:0xf bound_ctrl:1
	v_max_f32_e32 v22, v22, v22
	v_max_f32_e32 v11, v11, v22
	s_nop 0
	v_readlane_b32 s2, v11, 32
	v_readlane_b32 s20, v11, 48
	v_readlane_b32 s0, v11, 0
	v_readlane_b32 s1, v11, 16
	v_max_f32_e64 v11, s20, s20
	v_max_f32_e64 v22, s2, s2
	v_max_f32_e32 v11, v22, v11
	v_mov_b32_e32 v22, s1
	v_max3_f32 v11, s0, v22, v11
	v_sub_f32_e32 v12, v12, v11
	v_sub_f32_e32 v13, v13, v11
	v_mul_f32_e32 v12, 0x3fb8aa3b, v12
	v_mul_f32_e32 v13, 0x3fb8aa3b, v13
	v_sub_f32_e32 v14, v14, v11
	v_exp_f32_e32 v12, v12
	v_exp_f32_e32 v13, v13
	v_mul_f32_e32 v14, 0x3fb8aa3b, v14
	v_sub_f32_e32 v11, v15, v11
	v_exp_f32_e32 v14, v14
	v_mul_f32_e32 v11, 0x3fb8aa3b, v11
	v_exp_f32_e32 v15, v11
	v_lshrrev_b32_e32 v11, 16, v21
	v_add_f32_e32 v21, v12, v13
	v_add_f32_e32 v21, v14, v21
	v_add_f32_e32 v21, v15, v21
	v_and_or_b32 v11, v20, s80, v11
	s_nop 0
	v_add_f32_dpp v21, v21, v21 quad_perm:[1,0,3,2] row_mask:0xf bank_mask:0xf bound_ctrl:1
	s_nop 1
	v_add_f32_dpp v21, v21, v21 quad_perm:[2,3,0,1] row_mask:0xf bank_mask:0xf bound_ctrl:1
	s_nop 1
	v_add_f32_dpp v21, v21, v21 row_half_mirror row_mask:0xf bank_mask:0xf bound_ctrl:1
	s_nop 1
	v_add_f32_dpp v21, v21, v21 row_mirror row_mask:0xf bank_mask:0xf bound_ctrl:1
	s_nop 0
	v_readlane_b32 s1, v21, 16
	v_readlane_b32 s20, v21, 48
	v_readlane_b32 s0, v21, 0
	v_readlane_b32 s2, v21, 32
	v_mov_b32_e32 v21, s1
	v_mov_b32_e32 v22, s20
	v_add_f32_e32 v21, s0, v21
	v_add_f32_e32 v22, s2, v22
	v_add_f32_e32 v21, v21, v22
	s_nop 0
	v_rcp_f32_e32 v20, v21
	s_nop 0
	v_mul_f32_e32 v12, v12, v20
	v_mul_f32_e32 v13, v13, v20
	v_bfe_u32 v21, v12, 16, 1
	v_add3_u32 v12, v12, v21, s79
	v_bfe_u32 v21, v13, 16, 1
	v_lshrrev_b32_e32 v12, 16, v12
	v_add3_u32 v13, v13, v21, s79
	v_and_or_b32 v12, v13, s80, v12
	v_mul_f32_e32 v13, v14, v20
	v_mul_f32_e32 v14, v15, v20
	v_bfe_u32 v15, v13, 16, 1
	v_add3_u32 v13, v13, v15, s79
	s_waitcnt lgkmcnt(0)
	v_max_f32_e32 v15, v19, v19
	v_max_f32_e32 v20, v18, v18
	v_max_f32_e32 v15, v20, v15
	v_max3_f32 v15, v16, v17, v15
	v_bfe_u32 v22, v14, 16, 1
	v_lshrrev_b32_e32 v13, 16, v13
	v_mov_b32_dpp v20, v15 quad_perm:[1,0,3,2] row_mask:0xf bank_mask:0xf bound_ctrl:1
	v_max_f32_e32 v20, v20, v20
	v_max_f32_e32 v15, v15, v20
	v_add3_u32 v14, v14, v22, s79
	v_and_or_b32 v13, v14, s80, v13
	v_mov_b32_dpp v20, v15 quad_perm:[2,3,0,1] row_mask:0xf bank_mask:0xf bound_ctrl:1
	v_max_f32_e32 v20, v20, v20
	v_max_f32_e32 v15, v15, v20
	s_nop 1
	v_mov_b32_dpp v20, v15 row_half_mirror row_mask:0xf bank_mask:0xf bound_ctrl:1
	v_max_f32_e32 v20, v20, v20
	v_max_f32_e32 v15, v15, v20
	s_nop 1
	v_mov_b32_dpp v20, v15 row_mirror row_mask:0xf bank_mask:0xf bound_ctrl:1
	v_max_f32_e32 v20, v20, v20
	v_max_f32_e32 v15, v15, v20
	s_nop 0
	v_readlane_b32 s2, v15, 32
	v_readlane_b32 s20, v15, 48
	v_readlane_b32 s0, v15, 0
	v_readlane_b32 s1, v15, 16
	v_max_f32_e64 v15, s20, s20
	v_max_f32_e64 v20, s2, s2
	v_max_f32_e32 v15, v20, v15
	v_mov_b32_e32 v20, s1
	v_max3_f32 v15, s0, v20, v15
	v_sub_f32_e32 v16, v16, v15
	v_sub_f32_e32 v17, v17, v15
	v_mul_f32_e32 v16, 0x3fb8aa3b, v16
	v_mul_f32_e32 v17, 0x3fb8aa3b, v17
	v_sub_f32_e32 v18, v18, v15
	v_exp_f32_e32 v16, v16
	v_exp_f32_e32 v17, v17
	v_mul_f32_e32 v18, 0x3fb8aa3b, v18
	v_sub_f32_e32 v15, v19, v15
	v_exp_f32_e32 v18, v18
	v_mul_f32_e32 v15, 0x3fb8aa3b, v15
	v_exp_f32_e32 v15, v15
	v_add_f32_e32 v19, v16, v17
	v_add_f32_e32 v19, v18, v19
	v_add_f32_e32 v19, v15, v19
	s_nop 1
	v_add_f32_dpp v19, v19, v19 quad_perm:[1,0,3,2] row_mask:0xf bank_mask:0xf bound_ctrl:1
	s_nop 1
	v_add_f32_dpp v19, v19, v19 quad_perm:[2,3,0,1] row_mask:0xf bank_mask:0xf bound_ctrl:1
	s_nop 1
	v_add_f32_dpp v19, v19, v19 row_half_mirror row_mask:0xf bank_mask:0xf bound_ctrl:1
	s_nop 1
	v_add_f32_dpp v19, v19, v19 row_mirror row_mask:0xf bank_mask:0xf bound_ctrl:1
	s_nop 0
	v_readlane_b32 s1, v19, 16
	v_readlane_b32 s20, v19, 48
	v_readlane_b32 s0, v19, 0
	v_readlane_b32 s2, v19, 32
	v_mov_b32_e32 v19, s1
	v_mov_b32_e32 v20, s20
	v_add_f32_e32 v19, s0, v19
	v_add_f32_e32 v20, s2, v20
	v_add_f32_e32 v19, v19, v20
	s_mov_b32 s2, 0
	s_mov_b64 s[0:1], -1
	v_rcp_f32_e32 v19, v19
	s_nop 0
	v_mul_f32_e32 v14, v16, v19
	v_mul_f32_e32 v16, v17, v19
	v_bfe_u32 v17, v14, 16, 1
	v_add3_u32 v14, v14, v17, s79
	v_bfe_u32 v17, v16, 16, 1
	v_lshrrev_b32_e32 v14, 16, v14
	v_add3_u32 v16, v16, v17, s79
	v_and_or_b32 v14, v16, s80, v14
	v_mul_f32_e32 v16, v18, v19
	v_mul_f32_e32 v15, v15, v19
	v_bfe_u32 v17, v16, 16, 1
	v_add3_u32 v16, v16, v17, s79
	v_bfe_u32 v17, v15, 16, 1
	v_lshrrev_b32_e32 v16, 16, v16
	v_add3_u32 v15, v15, v17, s79
	v_and_or_b32 v15, v15, s80, v16
	v_add_u32_e32 v16, v56, v195
	ds_write2st64_b64 v16, v[0:1], v[2:3] offset1:1
	ds_write2st64_b64 v16, v[4:5], v[6:7] offset0:2 offset1:3
	ds_write2st64_b64 v16, v[8:9], v[10:11] offset0:4 offset1:5
	ds_write2st64_b64 v16, v[12:13], v[14:15] offset0:6 offset1:7
	s_waitcnt lgkmcnt(0)
	ds_read_u16 v0, v72
	ds_read_u16 v2, v72 offset:8
	ds_read_u16 v8, v72 offset:16
	ds_read_u16 v10, v72 offset:24
	ds_read_u16 v16, v72 offset:32
	ds_read_u16 v18, v72 offset:40
	ds_read_u16 v24, v72 offset:48
	ds_read_u16 v26, v72 offset:56
	s_waitcnt lgkmcnt(7)
	v_lshlrev_b32_e32 v136, 9, v0
	v_lshl_add_u64 v[0:1], v[164:165], 0, v[136:137]
	s_waitcnt lgkmcnt(6)
	v_lshlrev_b32_e32 v136, 9, v2
	v_lshl_add_u64 v[4:5], v[164:165], 0, v[136:137]
	s_waitcnt lgkmcnt(5)
	v_lshlrev_b32_e32 v136, 9, v8
	v_lshl_add_u64 v[8:9], v[164:165], 0, v[136:137]
	s_waitcnt lgkmcnt(4)
	v_lshlrev_b32_e32 v136, 9, v10
	v_lshl_add_u64 v[12:13], v[164:165], 0, v[136:137]
	s_waitcnt lgkmcnt(3)
	v_lshlrev_b32_e32 v136, 9, v16
	v_lshl_add_u64 v[16:17], v[164:165], 0, v[136:137]
	s_waitcnt lgkmcnt(2)
	v_lshlrev_b32_e32 v136, 9, v18
	v_lshl_add_u64 v[20:21], v[164:165], 0, v[136:137]
	s_waitcnt lgkmcnt(1)
	v_lshlrev_b32_e32 v136, 9, v24
	v_lshl_add_u64 v[24:25], v[164:165], 0, v[136:137]
	s_waitcnt lgkmcnt(0)
	v_lshlrev_b32_e32 v136, 9, v26
	v_lshl_add_u64 v[28:29], v[164:165], 0, v[136:137]
	global_load_dwordx4 v[0:3], v[0:1], off
	s_nop 0
	global_load_dwordx4 v[4:7], v[4:5], off
	s_nop 0
	global_load_dwordx4 v[8:11], v[8:9], off
	s_nop 0
	global_load_dwordx4 v[12:15], v[12:13], off
	s_nop 0
	global_load_dwordx4 v[16:19], v[16:17], off
	s_nop 0
	global_load_dwordx4 v[20:23], v[20:21], off
	s_nop 0
	global_load_dwordx4 v[24:27], v[24:25], off
	s_nop 0
	global_load_dwordx4 v[28:31], v[28:29], off
	s_branch .LBB0_787

.LBB0_804:
	v_mfma_f32_32x32x16_bf16 v[0:15], v[120:123], v[64:67], 0
	s_waitcnt lgkmcnt(0)
	v_mfma_f32_32x32x16_bf16 v[48:63], v[120:123], v[76:79], 0
	v_mfma_f32_32x32x16_bf16 v[16:31], v[120:123], v[68:71], 0
	v_mfma_f32_32x32x16_bf16 v[32:47], v[120:123], v[72:75], 0
	s_nop 8
	ds_write_b32 v151, v0
	s_nop 1
	ds_write2_b32 v152, v16, v32 offset0:32 offset1:64
	ds_write_b32 v152, v48 offset:384
	ds_write_b32 v153, v1
	ds_write2_b32 v154, v17, v33 offset0:32 offset1:64
	ds_write_b32 v154, v49 offset:384
	ds_write_b32 v155, v2
	ds_write2_b32 v156, v18, v34 offset0:32 offset1:64
	ds_write_b32 v156, v50 offset:384
	ds_write_b32 v157, v3
	ds_write2_b32 v158, v19, v35 offset0:32 offset1:64
	ds_write_b32 v158, v51 offset:384
	ds_write_b32 v159, v4
	ds_write2_b32 v160, v20, v36 offset0:32 offset1:64
	ds_write_b32 v160, v52 offset:384
	ds_write_b32 v161, v5
	ds_write2_b32 v162, v21, v37 offset0:32 offset1:64
	ds_write_b32 v162, v53 offset:384
	ds_write_b32 v163, v6
	ds_write2_b32 v164, v22, v38 offset0:32 offset1:64
	ds_write_b32 v164, v54 offset:384
	ds_write_b32 v165, v7
	ds_write2_b32 v166, v23, v39 offset0:32 offset1:64
	ds_write_b32 v166, v55 offset:384
	ds_write_b32 v167, v8
	ds_write2_b32 v189, v24, v40 offset0:32 offset1:64
	ds_write_b32 v189, v56 offset:384
	ds_write_b32 v190, v9
	ds_write2_b32 v191, v25, v41 offset0:32 offset1:64
	ds_write_b32 v191, v57 offset:384
	ds_write_b32 v192, v10
	ds_write2_b32 v193, v26, v42 offset0:32 offset1:64
	ds_write_b32 v193, v58 offset:384
	ds_write_b32 v194, v11
	ds_write2_b32 v195, v27, v43 offset0:32 offset1:64
	ds_write_b32 v195, v59 offset:384
	ds_write_b32 v196, v12
	ds_write2_b32 v197, v28, v44 offset0:32 offset1:64
	ds_write_b32 v197, v60 offset:384
	ds_write_b32 v198, v13
	ds_write2_b32 v199, v29, v45 offset0:32 offset1:64
	ds_write_b32 v199, v61 offset:384
	ds_write_b32 v200, v14
	ds_write2_b32 v201, v30, v46 offset0:32 offset1:64
	ds_write_b32 v201, v62 offset:384
	ds_write_b32 v202, v15
	ds_write2_b32 v203, v31, v47 offset0:32 offset1:64
	ds_write_b32 v203, v63 offset:384
	s_waitcnt lgkmcnt(0)
	ds_read2_b32 v[0:1], v204 offset1:32
	ds_read2_b32 v[2:3], v204 offset0:132 offset1:164
	v_pk_mul_f32 v[32:33], v[140:141], v[148:149]
	v_add_u32_e32 v6, 0x400, v204
	v_sub_f32_e32 v32, v32, v33
	s_waitcnt lgkmcnt(1)
	v_add_f32_e32 v0, v32, v0
	v_mul_f32_e32 v32, v124, v148
	v_fmac_f32_e32 v32, v140, v149
	v_add_f32_e32 v1, v32, v1
	v_bfe_u32 v32, v0, 16, 1
	v_add_u32_e32 v10, 0x800, v204
	v_add_u32_e32 v14, 0xc00, v204
	v_add_u32_e32 v18, 0x1000, v204
	v_add_u32_e32 v22, 0x1400, v204
	v_add_u32_e32 v26, 0x1800, v204
	v_add_u32_e32 v30, 0x1c00, v204
	v_add3_u32 v32, v0, v32, s33
	ds_read2_b32 v[4:5], v6 offset0:8 offset1:40
	ds_read2_b32 v[6:7], v6 offset0:140 offset1:172
	ds_read2_b32 v[8:9], v10 offset0:16 offset1:48
	ds_read2_b32 v[10:11], v10 offset0:148 offset1:180
	ds_read2_b32 v[12:13], v14 offset0:24 offset1:56
	ds_read2_b32 v[14:15], v14 offset0:156 offset1:188
	ds_read2_b32 v[16:17], v18 offset0:32 offset1:64
	ds_read2_b32 v[18:19], v18 offset0:164 offset1:196
	ds_read2_b32 v[20:21], v22 offset0:40 offset1:72
	ds_read2_b32 v[22:23], v22 offset0:172 offset1:204
	ds_read2_b32 v[24:25], v26 offset0:48 offset1:80
	ds_read2_b32 v[26:27], v26 offset0:180 offset1:212
	ds_read2_b32 v[28:29], v30 offset0:56 offset1:88
	ds_read2_b32 v[30:31], v30 offset0:188 offset1:220
	s_waitcnt lgkmcnt(0)
	ds_write_b16_d16_hi v205, v32
	v_bfe_u32 v32, v1, 16, 1
	v_add3_u32 v32, v1, v32, s33
	ds_write_b16_d16_hi v205, v32 offset:64
	v_mul_f32_e32 v32, v141, v1
	v_fma_f32 v32, v140, v0, -v32
	v_mul_f32_e32 v1, v140, v1
	s_waitcnt lgkmcnt(14)
	v_add_f32_e32 v2, v2, v32
	v_fmac_f32_e32 v1, v141, v0
	v_add_f32_e32 v0, v3, v1
	v_bfe_u32 v1, v2, 16, 1
	v_add3_u32 v1, v2, v1, s33
	ds_write_b16_d16_hi v205, v1 offset:528
	v_bfe_u32 v1, v0, 16, 1
	v_add3_u32 v1, v0, v1, s33
	ds_write_b16_d16_hi v205, v1 offset:592
	v_mul_f32_e32 v1, v141, v0
	v_fma_f32 v1, v140, v2, -v1
	v_mul_f32_e32 v2, v141, v2
	v_add_f32_e32 v1, v4, v1
	v_fmac_f32_e32 v2, v140, v0
	v_add_f32_e32 v0, v5, v2
	v_bfe_u32 v2, v1, 16, 1
	v_add3_u32 v2, v1, v2, s33
	ds_write_b16_d16_hi v205, v2 offset:1056
	v_bfe_u32 v2, v0, 16, 1
	v_add3_u32 v2, v0, v2, s33
	ds_write_b16_d16_hi v205, v2 offset:1120
	v_mul_f32_e32 v2, v141, v0
	v_fma_f32 v2, v140, v1, -v2
	v_mul_f32_e32 v1, v141, v1
	v_add_f32_e32 v2, v6, v2
	v_fmac_f32_e32 v1, v140, v0
	v_add_f32_e32 v0, v7, v1
	v_bfe_u32 v1, v2, 16, 1
	v_add3_u32 v1, v2, v1, s33
	ds_write_b16_d16_hi v205, v1 offset:1584
	v_bfe_u32 v1, v0, 16, 1
	v_add3_u32 v1, v0, v1, s33
	ds_write_b16_d16_hi v205, v1 offset:1648
	v_mul_f32_e32 v1, v141, v0
	v_fma_f32 v1, v140, v2, -v1
	v_mul_f32_e32 v2, v141, v2
	s_waitcnt lgkmcnt(14)
	v_add_f32_e32 v1, v8, v1
	v_fmac_f32_e32 v2, v140, v0
	v_add_f32_e32 v0, v9, v2
	v_bfe_u32 v2, v1, 16, 1
	v_add3_u32 v2, v1, v2, s33
	ds_write_b16_d16_hi v205, v2 offset:2112
	v_bfe_u32 v2, v0, 16, 1
	v_add3_u32 v2, v0, v2, s33
	ds_write_b16_d16_hi v205, v2 offset:2176
	v_mul_f32_e32 v2, v141, v0
	v_fma_f32 v2, v140, v1, -v2
	v_mul_f32_e32 v1, v141, v1
	v_add_f32_e32 v2, v10, v2
	v_fmac_f32_e32 v1, v140, v0
	v_add_f32_e32 v0, v11, v1
	v_bfe_u32 v1, v2, 16, 1
	v_add3_u32 v1, v2, v1, s33
	ds_write_b16_d16_hi v205, v1 offset:2640
	v_bfe_u32 v1, v0, 16, 1
	v_add3_u32 v1, v0, v1, s33
	ds_write_b16_d16_hi v205, v1 offset:2704
	v_mul_f32_e32 v1, v141, v0
	v_fma_f32 v1, v140, v2, -v1
	v_mul_f32_e32 v2, v141, v2
	v_add_f32_e32 v1, v12, v1
	v_fmac_f32_e32 v2, v140, v0
	v_add_f32_e32 v0, v13, v2
	v_bfe_u32 v2, v1, 16, 1
	v_add3_u32 v2, v1, v2, s33
	ds_write_b16_d16_hi v205, v2 offset:3168
	v_bfe_u32 v2, v0, 16, 1
	v_add3_u32 v2, v0, v2, s33
	ds_write_b16_d16_hi v205, v2 offset:3232
	v_mul_f32_e32 v2, v141, v0
	v_fma_f32 v2, v140, v1, -v2
	v_mul_f32_e32 v1, v141, v1
	v_add_f32_e32 v2, v14, v2
	v_fmac_f32_e32 v1, v140, v0
	v_add_f32_e32 v0, v15, v1
	v_bfe_u32 v1, v2, 16, 1
	v_add3_u32 v1, v2, v1, s33
	ds_write_b16_d16_hi v205, v1 offset:3696
	v_bfe_u32 v1, v0, 16, 1
	v_add3_u32 v1, v0, v1, s33
	ds_write_b16_d16_hi v205, v1 offset:3760
	v_mul_f32_e32 v1, v141, v0
	v_fma_f32 v1, v140, v2, -v1
	v_mul_f32_e32 v2, v141, v2
	v_add_f32_e32 v1, v16, v1
	v_fmac_f32_e32 v2, v140, v0
	v_add_f32_e32 v0, v17, v2
	v_bfe_u32 v2, v1, 16, 1
	v_add3_u32 v2, v1, v2, s33
	ds_write_b16_d16_hi v205, v2 offset:4224
	v_bfe_u32 v2, v0, 16, 1
	v_add3_u32 v2, v0, v2, s33
	ds_write_b16_d16_hi v205, v2 offset:4288
	v_mul_f32_e32 v2, v141, v0
	v_fma_f32 v2, v140, v1, -v2
	v_mul_f32_e32 v1, v141, v1
	v_add_f32_e32 v2, v18, v2
	v_fmac_f32_e32 v1, v140, v0
	v_add_f32_e32 v0, v19, v1
	v_bfe_u32 v1, v2, 16, 1
	v_add3_u32 v1, v2, v1, s33
	ds_write_b16_d16_hi v205, v1 offset:4752
	v_bfe_u32 v1, v0, 16, 1
	v_add3_u32 v1, v0, v1, s33
	ds_write_b16_d16_hi v205, v1 offset:4816
	v_mul_f32_e32 v1, v141, v0
	v_fma_f32 v1, v140, v2, -v1
	v_mul_f32_e32 v2, v141, v2
	s_waitcnt lgkmcnt(14)
	v_add_f32_e32 v1, v20, v1
	v_fmac_f32_e32 v2, v140, v0
	v_add_f32_e32 v0, v21, v2
	v_bfe_u32 v2, v1, 16, 1
	v_add3_u32 v2, v1, v2, s33
	ds_write_b16_d16_hi v205, v2 offset:5280
	v_bfe_u32 v2, v0, 16, 1
	v_add3_u32 v2, v0, v2, s33
	ds_write_b16_d16_hi v205, v2 offset:5344
	v_mul_f32_e32 v2, v141, v0
	v_fma_f32 v2, v140, v1, -v2
	v_mul_f32_e32 v1, v141, v1
	v_add_f32_e32 v2, v22, v2
	v_fmac_f32_e32 v1, v140, v0
	v_add_f32_e32 v0, v23, v1
	v_bfe_u32 v1, v2, 16, 1
	v_add3_u32 v1, v2, v1, s33
	ds_write_b16_d16_hi v205, v1 offset:5808
	v_bfe_u32 v1, v0, 16, 1
	v_add3_u32 v1, v0, v1, s33
	ds_write_b16_d16_hi v205, v1 offset:5872
	v_mul_f32_e32 v1, v141, v0
	v_fma_f32 v1, v140, v2, -v1
	v_mul_f32_e32 v2, v141, v2
	v_add_f32_e32 v1, v24, v1
	v_fmac_f32_e32 v2, v140, v0
	v_add_f32_e32 v0, v25, v2
	v_bfe_u32 v2, v1, 16, 1
	v_add3_u32 v2, v1, v2, s33
	ds_write_b16_d16_hi v205, v2 offset:6336
	v_bfe_u32 v2, v0, 16, 1
	v_add3_u32 v2, v0, v2, s33
	ds_write_b16_d16_hi v205, v2 offset:6400
	v_mul_f32_e32 v2, v141, v0
	v_fma_f32 v2, v140, v1, -v2
	v_mul_f32_e32 v1, v141, v1
	v_add_f32_e32 v2, v26, v2
	v_fmac_f32_e32 v1, v140, v0
	v_add_f32_e32 v0, v27, v1
	v_bfe_u32 v1, v2, 16, 1
	v_add3_u32 v1, v2, v1, s33
	ds_write_b16_d16_hi v205, v1 offset:6864
	v_bfe_u32 v1, v0, 16, 1
	v_add3_u32 v1, v0, v1, s33
	ds_write_b16_d16_hi v205, v1 offset:6928
	v_mul_f32_e32 v1, v141, v0
	v_fma_f32 v1, v140, v2, -v1
	v_mul_f32_e32 v2, v141, v2
	v_add_f32_e32 v1, v28, v1
	v_fmac_f32_e32 v2, v140, v0
	v_add_f32_e32 v0, v29, v2
	v_bfe_u32 v2, v1, 16, 1
	v_add3_u32 v2, v1, v2, s33
	ds_write_b16_d16_hi v205, v2 offset:7392
	v_bfe_u32 v2, v0, 16, 1
	v_add3_u32 v2, v0, v2, s33
	ds_write_b16_d16_hi v205, v2 offset:7456
	v_mul_f32_e32 v2, v141, v0
	v_fma_f32 v2, v140, v1, -v2
	v_add_f32_e32 v32, v30, v2
	v_mul_f32_e32 v1, v141, v1
	v_fmac_f32_e32 v1, v140, v0
	v_bfe_u32 v0, v32, 16, 1
	v_add_f32_e32 v33, v31, v1
	v_add3_u32 v0, v32, v0, s33
	ds_write_b16_d16_hi v205, v0 offset:7920
	v_bfe_u32 v0, v33, 16, 1
	v_add3_u32 v0, v33, v0, s33
	ds_write_b16_d16_hi v205, v0 offset:7984
	v_add_u32_e32 v2, 0x2000, v204
	ds_read2_b32 v[0:1], v2 offset0:64 offset1:96
	ds_read2_b32 v[2:3], v2 offset0:196 offset1:228
	v_mul_f32_e32 v34, v141, v33
	v_fma_f32 v34, v140, v32, -v34
	v_mul_f32_e32 v32, v141, v32
	s_waitcnt lgkmcnt(1)
	v_add_f32_e32 v0, v34, v0
	v_fmac_f32_e32 v32, v140, v33
	v_add_f32_e32 v1, v32, v1
	v_bfe_u32 v32, v0, 16, 1
	v_add_u32_e32 v6, 0x2400, v204
	v_add_u32_e32 v10, 0x2800, v204
	v_add_u32_e32 v14, 0x2c00, v204
	v_add_u32_e32 v16, 0x3000, v204
	v_add_u32_e32 v18, 0x3200, v204
	v_add_u32_e32 v20, 0x3400, v204
	v_add_u32_e32 v22, 0x3600, v204
	v_add_u32_e32 v24, 0x3800, v204
	v_add_u32_e32 v26, 0x3a00, v204
	v_add_u32_e32 v28, 0x3c00, v204
	v_add_u32_e32 v30, 0x3e00, v204
	v_add3_u32 v32, v0, v32, s33
	ds_read2_b32 v[4:5], v6 offset0:72 offset1:104
	ds_read2_b32 v[6:7], v6 offset0:204 offset1:236
	ds_read2_b32 v[8:9], v10 offset0:80 offset1:112
	ds_read2_b32 v[10:11], v10 offset0:212 offset1:244
	ds_read2_b32 v[12:13], v14 offset0:88 offset1:120
	ds_read2_b32 v[14:15], v14 offset0:220 offset1:252
	ds_read2_b32 v[16:17], v16 offset0:96 offset1:128
	ds_read2_b32 v[18:19], v18 offset0:100 offset1:132
	ds_read2_b32 v[20:21], v20 offset0:104 offset1:136
	ds_read2_b32 v[22:23], v22 offset0:108 offset1:140
	ds_read2_b32 v[24:25], v24 offset0:112 offset1:144
	ds_read2_b32 v[26:27], v26 offset0:116 offset1:148
	ds_read2_b32 v[28:29], v28 offset0:120 offset1:152
	ds_read2_b32 v[30:31], v30 offset0:124 offset1:156
	s_waitcnt lgkmcnt(0)
	ds_write_b16_d16_hi v205, v32 offset:8448
	v_bfe_u32 v32, v1, 16, 1
	v_add3_u32 v32, v1, v32, s33
	ds_write_b16_d16_hi v205, v32 offset:8512
	v_mul_f32_e32 v32, v141, v1
	v_fma_f32 v32, v140, v0, -v32
	v_mul_f32_e32 v1, v140, v1
	s_waitcnt lgkmcnt(14)
	v_add_f32_e32 v2, v2, v32
	v_fmac_f32_e32 v1, v141, v0
	v_add_f32_e32 v0, v3, v1
	v_bfe_u32 v1, v2, 16, 1
	v_add3_u32 v1, v2, v1, s33
	ds_write_b16_d16_hi v205, v1 offset:8976
	v_bfe_u32 v1, v0, 16, 1
	v_add3_u32 v1, v0, v1, s33
	ds_write_b16_d16_hi v205, v1 offset:9040
	v_mul_f32_e32 v1, v141, v0
	v_fma_f32 v1, v140, v2, -v1
	v_mul_f32_e32 v2, v141, v2
	v_add_f32_e32 v1, v4, v1
	v_fmac_f32_e32 v2, v140, v0
	v_add_f32_e32 v0, v5, v2
	v_bfe_u32 v2, v1, 16, 1
	v_add3_u32 v2, v1, v2, s33
	ds_write_b16_d16_hi v205, v2 offset:9504
	v_bfe_u32 v2, v0, 16, 1
	v_add3_u32 v2, v0, v2, s33
	ds_write_b16_d16_hi v205, v2 offset:9568
	v_mul_f32_e32 v2, v141, v0
	v_fma_f32 v2, v140, v1, -v2
	v_mul_f32_e32 v1, v141, v1
	v_add_f32_e32 v2, v6, v2
	v_fmac_f32_e32 v1, v140, v0
	v_add_f32_e32 v0, v7, v1
	v_bfe_u32 v1, v2, 16, 1
	v_add3_u32 v1, v2, v1, s33
	ds_write_b16_d16_hi v205, v1 offset:10032
	v_bfe_u32 v1, v0, 16, 1
	v_add3_u32 v1, v0, v1, s33
	ds_write_b16_d16_hi v205, v1 offset:10096
	v_mul_f32_e32 v1, v141, v0
	v_fma_f32 v1, v140, v2, -v1
	v_mul_f32_e32 v2, v141, v2
	s_waitcnt lgkmcnt(14)
	v_add_f32_e32 v1, v8, v1
	v_fmac_f32_e32 v2, v140, v0
	v_add_f32_e32 v0, v9, v2
	v_bfe_u32 v2, v1, 16, 1
	v_add3_u32 v2, v1, v2, s33
	ds_write_b16_d16_hi v205, v2 offset:10560
	v_bfe_u32 v2, v0, 16, 1
	v_add3_u32 v2, v0, v2, s33
	ds_write_b16_d16_hi v205, v2 offset:10624
	v_mul_f32_e32 v2, v141, v0
	v_fma_f32 v2, v140, v1, -v2
	v_mul_f32_e32 v1, v141, v1
	v_add_f32_e32 v2, v10, v2
	v_fmac_f32_e32 v1, v140, v0
	v_add_f32_e32 v0, v11, v1
	v_bfe_u32 v1, v2, 16, 1
	v_add3_u32 v1, v2, v1, s33
	ds_write_b16_d16_hi v205, v1 offset:11088
	v_bfe_u32 v1, v0, 16, 1
	v_add3_u32 v1, v0, v1, s33
	ds_write_b16_d16_hi v205, v1 offset:11152
	v_mul_f32_e32 v1, v141, v0
	v_fma_f32 v1, v140, v2, -v1
	v_mul_f32_e32 v2, v141, v2
	v_add_f32_e32 v1, v12, v1
	v_fmac_f32_e32 v2, v140, v0
	v_add_f32_e32 v0, v13, v2
	v_bfe_u32 v2, v1, 16, 1
	v_add3_u32 v2, v1, v2, s33
	ds_write_b16_d16_hi v205, v2 offset:11616
	v_bfe_u32 v2, v0, 16, 1
	v_add3_u32 v2, v0, v2, s33
	ds_write_b16_d16_hi v205, v2 offset:11680
	v_mul_f32_e32 v2, v141, v0
	v_fma_f32 v2, v140, v1, -v2
	v_mul_f32_e32 v1, v141, v1
	v_add_f32_e32 v2, v14, v2
	v_fmac_f32_e32 v1, v140, v0
	v_add_f32_e32 v0, v15, v1
	v_bfe_u32 v1, v2, 16, 1
	v_add3_u32 v1, v2, v1, s33
	ds_write_b16_d16_hi v205, v1 offset:12144
	v_bfe_u32 v1, v0, 16, 1
	v_add3_u32 v1, v0, v1, s33
	ds_write_b16_d16_hi v205, v1 offset:12208
	v_mul_f32_e32 v1, v141, v0
	v_fma_f32 v1, v140, v2, -v1
	v_mul_f32_e32 v2, v141, v2
	v_add_f32_e32 v1, v16, v1
	v_fmac_f32_e32 v2, v140, v0
	v_add_f32_e32 v0, v17, v2
	v_bfe_u32 v2, v1, 16, 1
	v_add3_u32 v2, v1, v2, s33
	ds_write_b16_d16_hi v205, v2 offset:12672
	v_bfe_u32 v2, v0, 16, 1
	v_add3_u32 v2, v0, v2, s33
	ds_write_b16_d16_hi v205, v2 offset:12736
	v_mul_f32_e32 v2, v141, v0
	v_fma_f32 v2, v140, v1, -v2
	v_mul_f32_e32 v1, v141, v1
	v_add_f32_e32 v2, v18, v2
	v_fmac_f32_e32 v1, v140, v0
	v_add_f32_e32 v0, v19, v1
	v_bfe_u32 v1, v2, 16, 1
	v_add3_u32 v1, v2, v1, s33
	ds_write_b16_d16_hi v205, v1 offset:13200
	v_bfe_u32 v1, v0, 16, 1
	v_add3_u32 v1, v0, v1, s33
	ds_write_b16_d16_hi v205, v1 offset:13264
	v_mul_f32_e32 v1, v141, v0
	v_fma_f32 v1, v140, v2, -v1
	v_mul_f32_e32 v2, v141, v2
	s_waitcnt lgkmcnt(14)
	v_add_f32_e32 v1, v20, v1
	v_fmac_f32_e32 v2, v140, v0
	v_add_f32_e32 v0, v21, v2
	v_bfe_u32 v2, v1, 16, 1
	v_add3_u32 v2, v1, v2, s33
	ds_write_b16_d16_hi v205, v2 offset:13728
	v_bfe_u32 v2, v0, 16, 1
	v_add3_u32 v2, v0, v2, s33
	ds_write_b16_d16_hi v205, v2 offset:13792
	v_mul_f32_e32 v2, v141, v0
	v_fma_f32 v2, v140, v1, -v2
	v_mul_f32_e32 v1, v141, v1
	v_add_f32_e32 v2, v22, v2
	v_fmac_f32_e32 v1, v140, v0
	v_add_f32_e32 v0, v23, v1
	v_bfe_u32 v1, v2, 16, 1
	v_add3_u32 v1, v2, v1, s33
	ds_write_b16_d16_hi v205, v1 offset:14256
	v_bfe_u32 v1, v0, 16, 1
	v_add3_u32 v1, v0, v1, s33
	ds_write_b16_d16_hi v205, v1 offset:14320
	v_mul_f32_e32 v1, v141, v0
	v_fma_f32 v1, v140, v2, -v1
	v_mul_f32_e32 v2, v141, v2
	v_add_f32_e32 v1, v24, v1
	v_fmac_f32_e32 v2, v140, v0
	v_add_f32_e32 v0, v25, v2
	v_bfe_u32 v2, v1, 16, 1
	v_add3_u32 v2, v1, v2, s33
	ds_write_b16_d16_hi v205, v2 offset:14784
	v_bfe_u32 v2, v0, 16, 1
	v_add3_u32 v2, v0, v2, s33
	ds_write_b16_d16_hi v205, v2 offset:14848
	v_mul_f32_e32 v2, v141, v0
	v_fma_f32 v2, v140, v1, -v2
	v_add_f32_e32 v2, v26, v2
	v_mul_f32_e32 v1, v141, v1
	v_fmac_f32_e32 v1, v140, v0
	v_bfe_u32 v0, v2, 16, 1
	v_add_f32_e32 v1, v27, v1
	v_add3_u32 v0, v2, v0, s33
	ds_write_b16_d16_hi v205, v0 offset:15312
	v_bfe_u32 v0, v1, 16, 1
	v_add3_u32 v0, v1, v0, s33
	ds_write_b16_d16_hi v205, v0 offset:15376
	v_mul_f32_e32 v0, v141, v1
	v_fma_f32 v0, v140, v2, -v0
	v_add_f32_e32 v0, v28, v0
	v_mul_f32_e32 v2, v141, v2
	v_fmac_f32_e32 v2, v140, v1
	v_bfe_u32 v1, v0, 16, 1
	v_add_f32_e32 v2, v29, v2
	v_add3_u32 v1, v0, v1, s33
	ds_write_b16_d16_hi v205, v1 offset:15840
	v_bfe_u32 v1, v2, 16, 1
	v_add3_u32 v1, v2, v1, s33
	v_pk_mul_f32 v[2:3], v[146:147], v[2:3] op_sel_hi:[1,0]
	ds_write_b16_d16_hi v205, v1 offset:15904
	v_pk_fma_f32 v[4:5], v[140:141], v[0:1], v[2:3] neg_lo:[0,0,1] neg_hi:[0,0,1]
	v_pk_fma_f32 v[0:1], v[140:141], v[0:1], v[2:3] op_sel_hi:[1,0,1]
	v_add_u32_e32 v24, v150, v130
	v_mov_b32_e32 v5, v1
	v_pk_add_f32 v[148:149], v[30:31], v[4:5]
	s_nop 0
	v_bfe_u32 v0, v148, 16, 1
	v_add3_u32 v0, v148, v0, s33
	ds_write_b16_d16_hi v205, v0 offset:16368
	v_bfe_u32 v0, v149, 16, 1
	v_add3_u32 v0, v149, v0, s33
	ds_write_b16_d16_hi v205, v0 offset:16432
	s_waitcnt lgkmcnt(0)
	ds_read_b128 v[0:3], v24
	ds_read_b128 v[16:19], v24 offset:32
	s_waitcnt lgkmcnt(1)
	v_mfma_f32_32x32x16_bf16 v[0:15], v[0:3], v[80:83], 0
	s_waitcnt lgkmcnt(0)
	v_mfma_f32_32x32x16_bf16 v[0:15], v[16:19], v[84:87], v[0:15]
	ds_read_b128 v[16:19], v24 offset:64
	ds_read_b128 v[20:23], v24 offset:96
	s_waitcnt lgkmcnt(1)
	v_mfma_f32_32x32x16_bf16 v[0:15], v[16:19], v[88:91], v[0:15]
	s_waitcnt lgkmcnt(0)
	v_mfma_f32_32x32x16_bf16 v[0:15], v[20:23], v[92:95], v[0:15]
	ds_read_b128 v[16:19], v24 offset:128
	ds_read_b128 v[20:23], v24 offset:160
	s_waitcnt lgkmcnt(1)
	v_mfma_f32_32x32x16_bf16 v[0:15], v[16:19], v[96:99], v[0:15]
	s_waitcnt lgkmcnt(0)
	v_mfma_f32_32x32x16_bf16 v[0:15], v[20:23], v[100:103], v[0:15]
	ds_read_b128 v[16:19], v24 offset:192
	ds_read_b128 v[20:23], v24 offset:224
	s_waitcnt lgkmcnt(1)
	v_mfma_f32_32x32x16_bf16 v[0:15], v[16:19], v[104:107], v[0:15]
	s_waitcnt lgkmcnt(0)
	v_mfma_f32_32x32x16_bf16 v[0:15], v[20:23], v[108:111], v[0:15]
	v_mfma_f32_32x32x16_bf16 v[0:15], v[120:123], v[112:115], v[0:15]
	s_and_saveexec_b64 s[34:35], s[16:17]
	s_cbranch_execz .LBB0_806
	s_nop 9
	v_mul_f32_e32 v16, 0x3d372713, v0
	v_mul_f32_e32 v16, v0, v16
	v_fma_f32 v16, v0, v16, v0
	v_mul_f32_e32 v16, 0x3f4c422a, v16
	v_add_f32_e32 v16, v16, v16
	v_mul_f32_e32 v16, 0x3fb8aa3b, v16
	v_exp_f32_e32 v16, v16
	v_mul_f32_e32 v17, 0x3d372713, v1
	v_mul_f32_e32 v17, v1, v17
	v_fma_f32 v17, v1, v17, v1
	v_add_f32_e32 v16, 1.0, v16
	v_mul_f32_e32 v17, 0x3f4c422a, v17
	v_add_f32_e32 v17, v17, v17
	v_mul_f32_e32 v17, 0x3fb8aa3b, v17
	v_exp_f32_e32 v17, v17
	v_rcp_f32_e32 v18, v16
	s_nop 0
	v_mul_f32_e32 v16, v0, v18
	v_sub_f32_e32 v0, v0, v16
	v_add_f32_e32 v16, 1.0, v17
	v_bfe_u32 v19, v0, 16, 1
	v_add3_u32 v0, v0, v19, s33
	ds_write_b16_d16_hi v186, v0 offset:256
	v_mul_f32_e32 v17, 0x3d372713, v2
	v_mul_f32_e32 v17, v2, v17
	v_fma_f32 v17, v2, v17, v2
	v_mul_f32_e32 v17, 0x3f4c422a, v17
	v_add_f32_e32 v17, v17, v17
	v_mul_f32_e32 v17, 0x3fb8aa3b, v17
	v_exp_f32_e32 v17, v17
	v_rcp_f32_e32 v0, v16
	s_nop 0
	v_mul_f32_e32 v0, v1, v0
	v_sub_f32_e32 v0, v1, v0
	v_add_f32_e32 v1, 1.0, v17
	v_bfe_u32 v18, v0, 16, 1
	v_add3_u32 v0, v0, v18, s33
	ds_write_b16_d16_hi v188, v0 offset:256
	v_mul_f32_e32 v16, 0x3d372713, v3
	v_mul_f32_e32 v16, v3, v16
	v_fma_f32 v16, v3, v16, v3
	v_mul_f32_e32 v16, 0x3f4c422a, v16
	v_add_f32_e32 v16, v16, v16
	v_mul_f32_e32 v16, 0x3fb8aa3b, v16
	v_exp_f32_e32 v16, v16
	v_rcp_f32_e32 v0, v1
	s_nop 0
	v_mul_f32_e32 v0, v2, v0
	v_sub_f32_e32 v0, v2, v0
	v_add_f32_e32 v1, 1.0, v16
	v_bfe_u32 v17, v0, 16, 1
	v_add3_u32 v0, v0, v17, s33
	ds_write_b16_d16_hi v206, v0 offset:256
	v_mul_f32_e32 v2, 0x3d372713, v4
	v_mul_f32_e32 v2, v4, v2
	v_fma_f32 v2, v4, v2, v4
	v_mul_f32_e32 v2, 0x3f4c422a, v2
	v_add_f32_e32 v2, v2, v2
	v_mul_f32_e32 v2, 0x3fb8aa3b, v2
	v_exp_f32_e32 v2, v2
	v_rcp_f32_e32 v0, v1
	s_nop 0
	v_mul_f32_e32 v0, v3, v0
	v_sub_f32_e32 v0, v3, v0
	v_add_f32_e32 v1, 1.0, v2
	v_bfe_u32 v16, v0, 16, 1
	v_add3_u32 v0, v0, v16, s33
	ds_write_b16_d16_hi v207, v0 offset:256
	v_mul_f32_e32 v2, 0x3d372713, v5
	v_mul_f32_e32 v2, v5, v2
	v_fma_f32 v2, v5, v2, v5
	v_mul_f32_e32 v2, 0x3f4c422a, v2
	v_add_f32_e32 v2, v2, v2
	v_mul_f32_e32 v2, 0x3fb8aa3b, v2
	v_exp_f32_e32 v2, v2
	v_rcp_f32_e32 v0, v1
	s_nop 0
	v_mul_f32_e32 v0, v4, v0
	v_sub_f32_e32 v0, v4, v0
	v_add_f32_e32 v1, 1.0, v2
	v_bfe_u32 v4, v0, 16, 1
	v_add3_u32 v0, v0, v4, s33
	ds_write_b16_d16_hi v208, v0 offset:256
	v_mul_f32_e32 v2, 0x3d372713, v6
	v_mul_f32_e32 v2, v6, v2
	v_fma_f32 v2, v6, v2, v6
	v_mul_f32_e32 v2, 0x3f4c422a, v2
	v_add_f32_e32 v2, v2, v2
	v_mul_f32_e32 v2, 0x3fb8aa3b, v2
	v_exp_f32_e32 v2, v2
	v_rcp_f32_e32 v0, v1
	s_nop 0
	v_mul_f32_e32 v0, v5, v0
	v_sub_f32_e32 v0, v5, v0
	v_add_f32_e32 v1, 1.0, v2
	v_bfe_u32 v4, v0, 16, 1
	v_add3_u32 v0, v0, v4, s33
	ds_write_b16_d16_hi v209, v0 offset:256
	v_mul_f32_e32 v2, 0x3d372713, v7
	v_mul_f32_e32 v2, v7, v2
	v_fma_f32 v2, v7, v2, v7
	v_mul_f32_e32 v2, 0x3f4c422a, v2
	v_add_f32_e32 v2, v2, v2
	v_mul_f32_e32 v2, 0x3fb8aa3b, v2
	v_exp_f32_e32 v2, v2
	v_rcp_f32_e32 v0, v1
	s_nop 0
	v_mul_f32_e32 v0, v6, v0
	v_sub_f32_e32 v0, v6, v0
	v_add_f32_e32 v1, 1.0, v2
	v_bfe_u32 v4, v0, 16, 1
	v_add3_u32 v0, v0, v4, s33
	ds_write_b16_d16_hi v210, v0 offset:256
	v_mul_f32_e32 v2, 0x3d372713, v8
	v_mul_f32_e32 v2, v8, v2
	v_fma_f32 v2, v8, v2, v8
	v_mul_f32_e32 v2, 0x3f4c422a, v2
	v_add_f32_e32 v2, v2, v2
	v_mul_f32_e32 v2, 0x3fb8aa3b, v2
	v_exp_f32_e32 v2, v2
	v_rcp_f32_e32 v0, v1
	s_nop 0
	v_mul_f32_e32 v0, v7, v0
	v_sub_f32_e32 v0, v7, v0
	v_add_f32_e32 v1, 1.0, v2
	v_bfe_u32 v4, v0, 16, 1
	v_add3_u32 v0, v0, v4, s33
	ds_write_b16_d16_hi v211, v0 offset:256
	v_mul_f32_e32 v2, 0x3d372713, v9
	v_mul_f32_e32 v2, v9, v2
	v_fma_f32 v2, v9, v2, v9
	v_mul_f32_e32 v2, 0x3f4c422a, v2
	v_add_f32_e32 v2, v2, v2
	v_mul_f32_e32 v2, 0x3fb8aa3b, v2
	v_exp_f32_e32 v2, v2
	v_rcp_f32_e32 v0, v1
	s_nop 0
	v_mul_f32_e32 v0, v8, v0
	v_sub_f32_e32 v0, v8, v0
	v_add_f32_e32 v1, 1.0, v2
	v_bfe_u32 v4, v0, 16, 1
	v_add3_u32 v0, v0, v4, s33
	ds_write_b16_d16_hi v212, v0 offset:256
	v_mul_f32_e32 v2, 0x3d372713, v10
	v_mul_f32_e32 v2, v10, v2
	v_fma_f32 v2, v10, v2, v10
	v_mul_f32_e32 v2, 0x3f4c422a, v2
	v_add_f32_e32 v2, v2, v2
	v_mul_f32_e32 v2, 0x3fb8aa3b, v2
	v_exp_f32_e32 v2, v2
	v_rcp_f32_e32 v0, v1
	s_nop 0
	v_mul_f32_e32 v0, v9, v0
	v_sub_f32_e32 v0, v9, v0
	v_add_f32_e32 v1, 1.0, v2
	v_bfe_u32 v4, v0, 16, 1
	v_add3_u32 v0, v0, v4, s33
	ds_write_b16_d16_hi v213, v0 offset:256
	v_mul_f32_e32 v2, 0x3d372713, v11
	v_mul_f32_e32 v2, v11, v2
	v_fma_f32 v2, v11, v2, v11
	v_mul_f32_e32 v2, 0x3f4c422a, v2
	v_add_f32_e32 v2, v2, v2
	v_mul_f32_e32 v2, 0x3fb8aa3b, v2
	v_exp_f32_e32 v2, v2
	v_rcp_f32_e32 v0, v1
	s_nop 0
	v_mul_f32_e32 v0, v10, v0
	v_sub_f32_e32 v0, v10, v0
	v_add_f32_e32 v1, 1.0, v2
	v_bfe_u32 v4, v0, 16, 1
	v_add3_u32 v0, v0, v4, s33
	ds_write_b16_d16_hi v214, v0 offset:256
	v_mul_f32_e32 v2, 0x3d372713, v12
	v_mul_f32_e32 v2, v12, v2
	v_fma_f32 v2, v12, v2, v12
	v_mul_f32_e32 v2, 0x3f4c422a, v2
	v_add_f32_e32 v2, v2, v2
	v_mul_f32_e32 v2, 0x3fb8aa3b, v2
	v_exp_f32_e32 v2, v2
	v_rcp_f32_e32 v0, v1
	s_nop 0
	v_mul_f32_e32 v0, v11, v0
	v_sub_f32_e32 v0, v11, v0
	v_add_f32_e32 v1, 1.0, v2
	v_bfe_u32 v4, v0, 16, 1
	v_add3_u32 v0, v0, v4, s33
	ds_write_b16_d16_hi v215, v0 offset:256
	v_mul_f32_e32 v2, 0x3d372713, v13
	v_mul_f32_e32 v2, v13, v2
	v_fma_f32 v2, v13, v2, v13
	v_mul_f32_e32 v2, 0x3f4c422a, v2
	v_add_f32_e32 v2, v2, v2
	v_mul_f32_e32 v2, 0x3fb8aa3b, v2
	v_exp_f32_e32 v2, v2
	v_rcp_f32_e32 v0, v1
	s_nop 0
	v_mul_f32_e32 v0, v12, v0
	v_sub_f32_e32 v0, v12, v0
	v_add_f32_e32 v1, 1.0, v2
	v_bfe_u32 v4, v0, 16, 1
	v_add3_u32 v0, v0, v4, s33
	ds_write_b16_d16_hi v216, v0 offset:256
	v_mul_f32_e32 v2, 0x3d372713, v14
	v_mul_f32_e32 v2, v14, v2
	v_fma_f32 v2, v14, v2, v14
	v_mul_f32_e32 v2, 0x3f4c422a, v2
	v_add_f32_e32 v2, v2, v2
	v_mul_f32_e32 v2, 0x3fb8aa3b, v2
	v_exp_f32_e32 v2, v2
	v_rcp_f32_e32 v0, v1
	s_nop 0
	v_mul_f32_e32 v0, v13, v0
	v_sub_f32_e32 v0, v13, v0
	v_add_f32_e32 v1, 1.0, v2
	v_bfe_u32 v4, v0, 16, 1
	v_add3_u32 v0, v0, v4, s33
	ds_write_b16_d16_hi v217, v0 offset:256
	v_mul_f32_e32 v2, 0x3d372713, v15
	v_mul_f32_e32 v2, v15, v2
	v_fma_f32 v2, v15, v2, v15
	v_mul_f32_e32 v2, 0x3f4c422a, v2
	v_add_f32_e32 v2, v2, v2
	v_mul_f32_e32 v2, 0x3fb8aa3b, v2
	v_exp_f32_e32 v2, v2
	v_rcp_f32_e32 v0, v1
	s_nop 0
	v_mul_f32_e32 v0, v14, v0
	v_sub_f32_e32 v0, v14, v0
	v_add_f32_e32 v1, 1.0, v2
	v_bfe_u32 v4, v0, 16, 1
	v_add3_u32 v0, v0, v4, s33
	ds_write_b16_d16_hi v218, v0 offset:256
	v_rcp_f32_e32 v0, v1
	s_nop 0
	v_mul_f32_e32 v0, v15, v0
	v_sub_f32_e32 v0, v15, v0
	v_bfe_u32 v1, v0, 16, 1
	v_add3_u32 v0, v0, v1, s33
	ds_write_b16_d16_hi v219, v0 offset:256

.LBB0_864:
	s_and_b32 s6, s2, 0x1f80
	s_ashr_i32 s0, s45, 6
	s_lshl_b32 s40, s6, 11
	s_ashr_i32 s1, s0, 31
	v_lshl_add_u64 v[66:67], v[90:91], 0, s[40:41]
	s_lshl_b64 s[0:1], s[0:1], 18
	v_add_co_u32_e32 v68, vcc, 0x10000, v66
	v_lshl_add_u64 v[64:65], v[92:93], 0, s[0:1]
	s_mov_b64 s[0:1], vcc
	v_add_co_u32_e32 v70, vcc, 0x20000, v66
	s_mov_b64 s[4:5], vcc
	v_addc_co_u32_e64 v69, vcc, 0, v67, s[0:1]
	v_add_co_u32_e32 v72, vcc, 0x30000, v66
	s_mov_b64 s[0:1], vcc
	v_addc_co_u32_e64 v71, vcc, 0, v67, s[4:5]
	v_add_co_u32_e32 v74, vcc, 0x10000, v64
	s_mov_b64 s[4:5], vcc
	v_addc_co_u32_e64 v73, vcc, 0, v67, s[0:1]
	v_add_co_u32_e32 v76, vcc, 0x20000, v64
	s_mov_b64 s[0:1], vcc
	v_addc_co_u32_e64 v75, vcc, 0, v65, s[4:5]
	v_add_co_u32_e32 v78, vcc, 0x30000, v64
	v_addc_co_u32_e64 v77, s[0:1], 0, v65, s[0:1]
	s_nop 0
	v_addc_co_u32_e32 v79, vcc, 0, v65, vcc
	global_load_dwordx4 v[0:3], v[66:67], off
	global_load_dwordx4 v[4:7], v[64:65], off
	global_load_dwordx4 v[8:11], v[68:69], off
	global_load_dwordx4 v[12:15], v[70:71], off
	global_load_dwordx4 v[16:19], v[72:73], off
	global_load_dwordx4 v[20:23], v[74:75], off
	global_load_dwordx4 v[24:27], v[76:77], off
	global_load_dwordx4 v[28:31], v[78:79], off
	global_load_dwordx4 v[80:83], v[66:67], off offset:128
	global_load_dwordx4 v[84:87], v[64:65], off offset:128
	global_load_dwordx4 v[96:99], v[68:69], off offset:128
	global_load_dwordx4 v[100:103], v[70:71], off offset:128
	global_load_dwordx4 v[134:137], v[72:73], off offset:128
	global_load_dwordx4 v[138:141], v[74:75], off offset:128
	global_load_dwordx4 v[142:145], v[76:77], off offset:128
	global_load_dwordx4 v[146:149], v[78:79], off offset:128
	s_and_b32 s0, s45, 0xffffffc0
	s_ashr_i32 s1, s0, 31
	s_or_b32 s4, s6, 32
	s_add_i32 s45, s45, s92
	s_add_i32 s2, s2, s33
	s_cmpk_lt_i32 s45, 0x400
	s_waitcnt vmcnt(15)
	ds_write_b128 v104, v[0:3]
	s_waitcnt vmcnt(14)
	ds_write_b128 v104, v[4:7] offset:32768
	s_waitcnt vmcnt(13)
	ds_write_b128 v104, v[8:11] offset:4096
	s_waitcnt vmcnt(12)
	ds_write_b128 v104, v[12:15] offset:8192
	s_waitcnt vmcnt(11)
	ds_write_b128 v104, v[16:19] offset:12288
	s_waitcnt vmcnt(10)
	ds_write_b128 v104, v[20:23] offset:36864
	s_waitcnt vmcnt(9)
	ds_write_b128 v104, v[24:27] offset:40960
	s_waitcnt vmcnt(8)
	ds_write_b128 v104, v[28:31] offset:45056
	s_waitcnt lgkmcnt(0)
	s_barrier
	ds_read_b128 v[0:3], v111
	ds_read_b128 v[16:19], v111 offset:4096
	ds_read_b128 v[4:7], v112 offset:32768
	ds_read_b128 v[20:23], v112 offset:36864
	ds_read_b128 v[150:153], v113
	ds_read_b128 v[154:157], v113 offset:4096
	ds_read_b128 v[158:161], v114 offset:32768
	ds_read_b128 v[162:165], v114 offset:36864
	s_waitcnt lgkmcnt(5)
	v_mfma_f32_32x32x16_bf16 v[32:47], v[0:3], v[4:7], 0
	global_load_dwordx4 v[202:205], v[64:65], off offset:256
	global_load_dwordx4 v[206:209], v[76:77], off offset:256
	global_load_dwordx4 v[210:213], v[78:79], off offset:256
	s_waitcnt lgkmcnt(4)
	v_mfma_f32_32x32x16_bf16 v[48:63], v[0:3], v[20:23], 0
	v_mfma_f32_32x32x16_bf16 v[0:15], v[16:19], v[4:7], 0
	v_mfma_f32_32x32x16_bf16 v[16:31], v[16:19], v[20:23], 0
	ds_read_b128 v[186:189], v115
	ds_read_b128 v[190:193], v115 offset:4096
	ds_read_b128 v[194:197], v116 offset:32768
	ds_read_b128 v[198:201], v116 offset:36864
	s_waitcnt lgkmcnt(5)
	v_mfma_f32_32x32x16_bf16 v[32:47], v[150:153], v[158:161], v[32:47]
	s_waitcnt lgkmcnt(4)
	v_mfma_f32_32x32x16_bf16 v[48:63], v[150:153], v[162:165], v[48:63]
	v_mfma_f32_32x32x16_bf16 v[0:15], v[154:157], v[158:161], v[0:15]
	v_mfma_f32_32x32x16_bf16 v[16:31], v[154:157], v[162:165], v[16:31]
	ds_read_b128 v[150:153], v117
	ds_read_b128 v[154:157], v117 offset:4096
	ds_read_b128 v[158:161], v118 offset:32768
	ds_read_b128 v[162:165], v118 offset:36864
	s_waitcnt vmcnt(10)
	ds_write_b128 v104, v[80:83] offset:16384
	s_waitcnt vmcnt(8)
	ds_write_b128 v104, v[96:99] offset:20480
	s_waitcnt vmcnt(7)
	ds_write_b128 v104, v[100:103] offset:24576
	s_waitcnt lgkmcnt(8)
	v_mfma_f32_32x32x16_bf16 v[32:47], v[186:189], v[194:197], v[32:47]
	s_waitcnt vmcnt(6)
	ds_write_b128 v104, v[134:137] offset:28672
	ds_write_b128 v104, v[84:87] offset:49152
	s_waitcnt vmcnt(5)
	ds_write_b128 v104, v[138:141] offset:53248
	s_waitcnt vmcnt(4)
	ds_write_b128 v104, v[142:145] offset:57344
	s_waitcnt vmcnt(3)
	ds_write_b128 v104, v[146:149] offset:61440
	s_waitcnt lgkmcnt(12)
	v_mfma_f32_32x32x16_bf16 v[48:63], v[186:189], v[198:201], v[48:63]
	global_load_dwordx4 v[186:189], v[66:67], off offset:256
	v_mfma_f32_32x32x16_bf16 v[0:15], v[190:193], v[194:197], v[0:15]
	global_load_dwordx4 v[194:197], v[70:71], off offset:256
	v_mfma_f32_32x32x16_bf16 v[16:31], v[190:193], v[198:201], v[16:31]
	global_load_dwordx4 v[190:193], v[68:69], off offset:256
	global_load_dwordx4 v[198:201], v[72:73], off offset:256
	s_waitcnt lgkmcnt(9)
	v_mfma_f32_32x32x16_bf16 v[32:47], v[150:153], v[158:161], v[32:47]
	s_waitcnt lgkmcnt(8)
	v_mfma_f32_32x32x16_bf16 v[48:63], v[150:153], v[162:165], v[48:63]
	global_load_dwordx4 v[150:153], v[74:75], off offset:256
	s_waitcnt lgkmcnt(0)
	s_barrier
	s_waitcnt vmcnt(4)
	ds_write_b128 v104, v[186:189]
	v_mfma_f32_32x32x16_bf16 v[0:15], v[154:157], v[158:161], v[0:15]
	global_load_dwordx4 v[158:161], v[78:79], off offset:384
	v_mfma_f32_32x32x16_bf16 v[16:31], v[154:157], v[162:165], v[16:31]
	ds_read_b128 v[80:83], v111 offset:16384
	ds_read_b128 v[84:87], v111 offset:20480
	ds_read_b128 v[96:99], v112 offset:49152
	ds_read_b128 v[100:103], v112 offset:53248
	ds_read_b128 v[134:137], v113 offset:16384
	ds_read_b128 v[138:141], v113 offset:20480
	ds_read_b128 v[142:145], v114 offset:49152
	ds_read_b128 v[146:149], v114 offset:53248
	s_waitcnt lgkmcnt(5)
	v_mfma_f32_32x32x16_bf16 v[32:47], v[80:83], v[96:99], v[32:47]
	global_load_dwordx4 v[154:157], v[76:77], off offset:384
	s_waitcnt lgkmcnt(4)
	v_mfma_f32_32x32x16_bf16 v[48:63], v[80:83], v[100:103], v[48:63]
	v_mfma_f32_32x32x16_bf16 v[0:15], v[84:87], v[96:99], v[0:15]
	v_mfma_f32_32x32x16_bf16 v[16:31], v[84:87], v[100:103], v[16:31]
	ds_read_b128 v[80:83], v115 offset:16384
	ds_read_b128 v[84:87], v115 offset:20480
	ds_read_b128 v[96:99], v116 offset:49152
	ds_read_b128 v[100:103], v116 offset:53248
	s_waitcnt lgkmcnt(5)
	v_mfma_f32_32x32x16_bf16 v[32:47], v[134:137], v[142:145], v[32:47]
	s_waitcnt lgkmcnt(4)
	v_mfma_f32_32x32x16_bf16 v[48:63], v[134:137], v[146:149], v[48:63]
	v_mfma_f32_32x32x16_bf16 v[0:15], v[138:141], v[142:145], v[0:15]
	v_mfma_f32_32x32x16_bf16 v[16:31], v[138:141], v[146:149], v[16:31]
	ds_read_b128 v[134:137], v117 offset:16384
	ds_read_b128 v[138:141], v117 offset:20480
	ds_read_b128 v[142:145], v118 offset:49152
	ds_read_b128 v[146:149], v118 offset:53248
	s_waitcnt vmcnt(4)
	ds_write_b128 v104, v[190:193] offset:4096
	ds_write_b128 v104, v[194:197] offset:8192
	s_waitcnt vmcnt(3)
	ds_write_b128 v104, v[198:201] offset:12288
	s_waitcnt lgkmcnt(8)
	v_mfma_f32_32x32x16_bf16 v[32:47], v[80:83], v[96:99], v[32:47]
	ds_write_b128 v104, v[202:205] offset:32768
	s_waitcnt vmcnt(2)
	ds_write_b128 v104, v[150:153] offset:36864
	ds_write_b128 v104, v[206:209] offset:40960
	ds_write_b128 v104, v[210:213] offset:45056
	s_waitcnt lgkmcnt(11)
	v_mfma_f32_32x32x16_bf16 v[48:63], v[80:83], v[100:103], v[48:63]
	global_load_dwordx4 v[80:83], v[66:67], off offset:384
	v_mfma_f32_32x32x16_bf16 v[0:15], v[84:87], v[96:99], v[0:15]
	global_load_dwordx4 v[96:99], v[70:71], off offset:384
	v_mfma_f32_32x32x16_bf16 v[16:31], v[84:87], v[100:103], v[16:31]
	global_load_dwordx4 v[84:87], v[68:69], off offset:384
	global_load_dwordx4 v[100:103], v[72:73], off offset:384
	s_waitcnt lgkmcnt(8)
	v_mfma_f32_32x32x16_bf16 v[32:47], v[134:137], v[142:145], v[32:47]
	s_waitcnt lgkmcnt(7)
	v_mfma_f32_32x32x16_bf16 v[48:63], v[134:137], v[146:149], v[48:63]
	global_load_dwordx4 v[134:137], v[64:65], off offset:384
	v_mfma_f32_32x32x16_bf16 v[0:15], v[138:141], v[142:145], v[0:15]
	global_load_dwordx4 v[142:145], v[74:75], off offset:384
	s_waitcnt lgkmcnt(0)
	s_barrier
	global_load_dwordx4 v[202:205], v[64:65], off offset:512
	global_load_dwordx4 v[206:209], v[76:77], off offset:512
	global_load_dwordx4 v[210:213], v[78:79], off offset:512
	v_mfma_f32_32x32x16_bf16 v[16:31], v[138:141], v[146:149], v[16:31]
	ds_read_b128 v[138:141], v111
	ds_read_b128 v[146:149], v111 offset:4096
	ds_read_b128 v[150:153], v112 offset:32768
	ds_read_b128 v[162:165], v112 offset:36864
	ds_read_b128 v[186:189], v113
	ds_read_b128 v[190:193], v113 offset:4096
	ds_read_b128 v[194:197], v114 offset:32768
	ds_read_b128 v[198:201], v114 offset:36864
	s_waitcnt lgkmcnt(5)
	v_mfma_f32_32x32x16_bf16 v[32:47], v[138:141], v[150:153], v[32:47]
	s_waitcnt lgkmcnt(4)
	v_mfma_f32_32x32x16_bf16 v[48:63], v[138:141], v[162:165], v[48:63]
	v_mfma_f32_32x32x16_bf16 v[0:15], v[146:149], v[150:153], v[0:15]
	v_mfma_f32_32x32x16_bf16 v[16:31], v[146:149], v[162:165], v[16:31]
	ds_read_b128 v[138:141], v115
	ds_read_b128 v[146:149], v115 offset:4096
	ds_read_b128 v[150:153], v116 offset:32768
	ds_read_b128 v[162:165], v116 offset:36864
	s_waitcnt lgkmcnt(5)
	v_mfma_f32_32x32x16_bf16 v[32:47], v[186:189], v[194:197], v[32:47]
	s_waitcnt lgkmcnt(4)
	v_mfma_f32_32x32x16_bf16 v[48:63], v[186:189], v[198:201], v[48:63]
	v_mfma_f32_32x32x16_bf16 v[0:15], v[190:193], v[194:197], v[0:15]
	v_mfma_f32_32x32x16_bf16 v[16:31], v[190:193], v[198:201], v[16:31]
	ds_read_b128 v[186:189], v117
	ds_read_b128 v[190:193], v117 offset:4096
	ds_read_b128 v[194:197], v118 offset:32768
	ds_read_b128 v[198:201], v118 offset:36864
	s_waitcnt vmcnt(8)
	ds_write_b128 v104, v[80:83] offset:16384
	s_waitcnt vmcnt(6)
	ds_write_b128 v104, v[84:87] offset:20480
	ds_write_b128 v104, v[96:99] offset:24576
	s_waitcnt lgkmcnt(8)
	v_mfma_f32_32x32x16_bf16 v[32:47], v[138:141], v[150:153], v[32:47]
	s_waitcnt vmcnt(5)
	ds_write_b128 v104, v[100:103] offset:28672
	s_waitcnt vmcnt(4)
	ds_write_b128 v104, v[134:137] offset:49152
	s_waitcnt vmcnt(3)
	ds_write_b128 v104, v[142:145] offset:53248
	ds_write_b128 v104, v[154:157] offset:57344
	ds_write_b128 v104, v[158:161] offset:61440
	s_waitcnt lgkmcnt(12)
	v_mfma_f32_32x32x16_bf16 v[48:63], v[138:141], v[162:165], v[48:63]
	global_load_dwordx4 v[138:141], v[66:67], off offset:512
	v_mfma_f32_32x32x16_bf16 v[0:15], v[146:149], v[150:153], v[0:15]
	global_load_dwordx4 v[150:153], v[70:71], off offset:512
	v_mfma_f32_32x32x16_bf16 v[16:31], v[146:149], v[162:165], v[16:31]
	global_load_dwordx4 v[146:149], v[68:69], off offset:512
	global_load_dwordx4 v[162:165], v[72:73], off offset:512
	s_waitcnt lgkmcnt(9)
	v_mfma_f32_32x32x16_bf16 v[32:47], v[186:189], v[194:197], v[32:47]
	s_waitcnt lgkmcnt(8)
	v_mfma_f32_32x32x16_bf16 v[48:63], v[186:189], v[198:201], v[48:63]
	global_load_dwordx4 v[186:189], v[74:75], off offset:512
	s_waitcnt lgkmcnt(0)
	s_barrier
	s_waitcnt vmcnt(4)
	ds_write_b128 v104, v[138:141]
	v_mfma_f32_32x32x16_bf16 v[0:15], v[190:193], v[194:197], v[0:15]
	global_load_dwordx4 v[194:197], v[78:79], off offset:640
	v_mfma_f32_32x32x16_bf16 v[16:31], v[190:193], v[198:201], v[16:31]
	ds_read_b128 v[80:83], v111 offset:16384
	ds_read_b128 v[84:87], v111 offset:20480
	ds_read_b128 v[96:99], v112 offset:49152
	ds_read_b128 v[100:103], v112 offset:53248
	ds_read_b128 v[134:137], v113 offset:16384
	ds_read_b128 v[142:145], v113 offset:20480
	ds_read_b128 v[154:157], v114 offset:49152
	ds_read_b128 v[158:161], v114 offset:53248
	s_waitcnt lgkmcnt(5)
	v_mfma_f32_32x32x16_bf16 v[32:47], v[80:83], v[96:99], v[32:47]
	global_load_dwordx4 v[190:193], v[76:77], off offset:640
	s_waitcnt lgkmcnt(4)
	v_mfma_f32_32x32x16_bf16 v[48:63], v[80:83], v[100:103], v[48:63]
	v_mfma_f32_32x32x16_bf16 v[0:15], v[84:87], v[96:99], v[0:15]
	v_mfma_f32_32x32x16_bf16 v[16:31], v[84:87], v[100:103], v[16:31]
	ds_read_b128 v[80:83], v115 offset:16384
	ds_read_b128 v[84:87], v115 offset:20480
	ds_read_b128 v[96:99], v116 offset:49152
	ds_read_b128 v[100:103], v116 offset:53248
	s_waitcnt lgkmcnt(5)
	v_mfma_f32_32x32x16_bf16 v[32:47], v[134:137], v[154:157], v[32:47]
	s_waitcnt lgkmcnt(4)
	v_mfma_f32_32x32x16_bf16 v[48:63], v[134:137], v[158:161], v[48:63]
	v_mfma_f32_32x32x16_bf16 v[0:15], v[142:145], v[154:157], v[0:15]
	v_mfma_f32_32x32x16_bf16 v[16:31], v[142:145], v[158:161], v[16:31]
	ds_read_b128 v[134:137], v117 offset:16384
	ds_read_b128 v[142:145], v117 offset:20480
	ds_read_b128 v[154:157], v118 offset:49152
	ds_read_b128 v[158:161], v118 offset:53248
	s_waitcnt vmcnt(4)
	ds_write_b128 v104, v[146:149] offset:4096
	ds_write_b128 v104, v[150:153] offset:8192
	s_waitcnt vmcnt(3)
	ds_write_b128 v104, v[162:165] offset:12288
	s_waitcnt lgkmcnt(8)
	v_mfma_f32_32x32x16_bf16 v[32:47], v[80:83], v[96:99], v[32:47]
	ds_write_b128 v104, v[202:205] offset:32768
	s_waitcnt vmcnt(2)
	ds_write_b128 v104, v[186:189] offset:36864
	ds_write_b128 v104, v[206:209] offset:40960
	ds_write_b128 v104, v[210:213] offset:45056
	s_waitcnt lgkmcnt(11)
	v_mfma_f32_32x32x16_bf16 v[48:63], v[80:83], v[100:103], v[48:63]
	global_load_dwordx4 v[80:83], v[66:67], off offset:640
	v_mfma_f32_32x32x16_bf16 v[0:15], v[84:87], v[96:99], v[0:15]
	global_load_dwordx4 v[96:99], v[70:71], off offset:640
	v_mfma_f32_32x32x16_bf16 v[16:31], v[84:87], v[100:103], v[16:31]
	global_load_dwordx4 v[84:87], v[68:69], off offset:640
	global_load_dwordx4 v[100:103], v[72:73], off offset:640
	s_waitcnt lgkmcnt(8)
	v_mfma_f32_32x32x16_bf16 v[32:47], v[134:137], v[154:157], v[32:47]
	s_waitcnt lgkmcnt(7)
	v_mfma_f32_32x32x16_bf16 v[48:63], v[134:137], v[158:161], v[48:63]
	global_load_dwordx4 v[134:137], v[64:65], off offset:640
	v_mfma_f32_32x32x16_bf16 v[0:15], v[142:145], v[154:157], v[0:15]
	global_load_dwordx4 v[154:157], v[74:75], off offset:640
	s_waitcnt lgkmcnt(0)
	s_barrier
	global_load_dwordx4 v[202:205], v[64:65], off offset:768
	global_load_dwordx4 v[206:209], v[76:77], off offset:768
	global_load_dwordx4 v[210:213], v[78:79], off offset:768
	v_mfma_f32_32x32x16_bf16 v[16:31], v[142:145], v[158:161], v[16:31]
	ds_read_b128 v[138:141], v111
	ds_read_b128 v[142:145], v111 offset:4096
	ds_read_b128 v[146:149], v112 offset:32768
	ds_read_b128 v[150:153], v112 offset:36864
	ds_read_b128 v[158:161], v113
	ds_read_b128 v[162:165], v113 offset:4096
	ds_read_b128 v[186:189], v114 offset:32768
	ds_read_b128 v[198:201], v114 offset:36864
	s_waitcnt lgkmcnt(5)
	v_mfma_f32_32x32x16_bf16 v[32:47], v[138:141], v[146:149], v[32:47]
	s_waitcnt lgkmcnt(4)
	v_mfma_f32_32x32x16_bf16 v[48:63], v[138:141], v[150:153], v[48:63]
	v_mfma_f32_32x32x16_bf16 v[0:15], v[142:145], v[146:149], v[0:15]
	v_mfma_f32_32x32x16_bf16 v[16:31], v[142:145], v[150:153], v[16:31]
	ds_read_b128 v[138:141], v115
	ds_read_b128 v[142:145], v115 offset:4096
	ds_read_b128 v[146:149], v116 offset:32768
	ds_read_b128 v[150:153], v116 offset:36864
	s_waitcnt lgkmcnt(5)
	v_mfma_f32_32x32x16_bf16 v[32:47], v[158:161], v[186:189], v[32:47]
	s_waitcnt lgkmcnt(4)
	v_mfma_f32_32x32x16_bf16 v[48:63], v[158:161], v[198:201], v[48:63]
	v_mfma_f32_32x32x16_bf16 v[0:15], v[162:165], v[186:189], v[0:15]
	v_mfma_f32_32x32x16_bf16 v[16:31], v[162:165], v[198:201], v[16:31]
	ds_read_b128 v[158:161], v117
	ds_read_b128 v[162:165], v117 offset:4096
	ds_read_b128 v[186:189], v118 offset:32768
	ds_read_b128 v[198:201], v118 offset:36864
	s_waitcnt vmcnt(8)
	ds_write_b128 v104, v[80:83] offset:16384
	s_waitcnt vmcnt(6)
	ds_write_b128 v104, v[84:87] offset:20480
	ds_write_b128 v104, v[96:99] offset:24576
	s_waitcnt lgkmcnt(8)
	v_mfma_f32_32x32x16_bf16 v[32:47], v[138:141], v[146:149], v[32:47]
	s_waitcnt vmcnt(5)
	ds_write_b128 v104, v[100:103] offset:28672
	s_waitcnt vmcnt(4)
	ds_write_b128 v104, v[134:137] offset:49152
	s_waitcnt vmcnt(3)
	ds_write_b128 v104, v[154:157] offset:53248
	ds_write_b128 v104, v[190:193] offset:57344
	ds_write_b128 v104, v[194:197] offset:61440
	s_waitcnt lgkmcnt(12)
	v_mfma_f32_32x32x16_bf16 v[48:63], v[138:141], v[150:153], v[48:63]
	global_load_dwordx4 v[138:141], v[66:67], off offset:768
	v_mfma_f32_32x32x16_bf16 v[0:15], v[142:145], v[146:149], v[0:15]
	global_load_dwordx4 v[146:149], v[70:71], off offset:768
	v_mfma_f32_32x32x16_bf16 v[16:31], v[142:145], v[150:153], v[16:31]
	global_load_dwordx4 v[142:145], v[68:69], off offset:768
	global_load_dwordx4 v[150:153], v[72:73], off offset:768
	s_waitcnt lgkmcnt(9)
	v_mfma_f32_32x32x16_bf16 v[32:47], v[158:161], v[186:189], v[32:47]
	s_waitcnt lgkmcnt(8)
	v_mfma_f32_32x32x16_bf16 v[48:63], v[158:161], v[198:201], v[48:63]
	global_load_dwordx4 v[158:161], v[74:75], off offset:768
	s_waitcnt lgkmcnt(0)
	s_barrier
	global_load_dwordx4 v[190:193], v[76:77], off offset:896
	global_load_dwordx4 v[194:197], v[78:79], off offset:896
	s_waitcnt vmcnt(6)
	ds_write_b128 v104, v[138:141]
	v_mfma_f32_32x32x16_bf16 v[0:15], v[162:165], v[186:189], v[0:15]
	v_mfma_f32_32x32x16_bf16 v[16:31], v[162:165], v[198:201], v[16:31]
	ds_read_b128 v[80:83], v111 offset:16384
	ds_read_b128 v[84:87], v111 offset:20480
	ds_read_b128 v[96:99], v112 offset:49152
	ds_read_b128 v[100:103], v112 offset:53248
	ds_read_b128 v[134:137], v113 offset:16384
	ds_read_b128 v[154:157], v113 offset:20480
	ds_read_b128 v[162:165], v114 offset:49152
	ds_read_b128 v[186:189], v114 offset:53248
	s_waitcnt lgkmcnt(5)
	v_mfma_f32_32x32x16_bf16 v[32:47], v[80:83], v[96:99], v[32:47]
	s_waitcnt lgkmcnt(4)
	v_mfma_f32_32x32x16_bf16 v[48:63], v[80:83], v[100:103], v[48:63]
	v_mfma_f32_32x32x16_bf16 v[0:15], v[84:87], v[96:99], v[0:15]
	v_mfma_f32_32x32x16_bf16 v[16:31], v[84:87], v[100:103], v[16:31]
	ds_read_b128 v[80:83], v115 offset:16384
	ds_read_b128 v[84:87], v115 offset:20480
	ds_read_b128 v[96:99], v116 offset:49152
	ds_read_b128 v[100:103], v116 offset:53248
	s_waitcnt lgkmcnt(5)
	v_mfma_f32_32x32x16_bf16 v[32:47], v[134:137], v[162:165], v[32:47]
	s_waitcnt lgkmcnt(4)
	v_mfma_f32_32x32x16_bf16 v[48:63], v[134:137], v[186:189], v[48:63]
	v_mfma_f32_32x32x16_bf16 v[0:15], v[154:157], v[162:165], v[0:15]
	v_mfma_f32_32x32x16_bf16 v[16:31], v[154:157], v[186:189], v[16:31]
	ds_read_b128 v[134:137], v117 offset:16384
	ds_read_b128 v[154:157], v117 offset:20480
	ds_read_b128 v[162:165], v118 offset:49152
	ds_read_b128 v[186:189], v118 offset:53248
	s_waitcnt vmcnt(4)
	ds_write_b128 v104, v[142:145] offset:4096
	ds_write_b128 v104, v[146:149] offset:8192
	s_waitcnt vmcnt(3)
	ds_write_b128 v104, v[150:153] offset:12288
	s_waitcnt lgkmcnt(8)
	v_mfma_f32_32x32x16_bf16 v[32:47], v[80:83], v[96:99], v[32:47]
	ds_write_b128 v104, v[202:205] offset:32768
	s_waitcnt vmcnt(2)
	ds_write_b128 v104, v[158:161] offset:36864
	ds_write_b128 v104, v[206:209] offset:40960
	ds_write_b128 v104, v[210:213] offset:45056
	s_waitcnt lgkmcnt(11)
	v_mfma_f32_32x32x16_bf16 v[48:63], v[80:83], v[100:103], v[48:63]
	global_load_dwordx4 v[80:83], v[66:67], off offset:896
	v_mfma_f32_32x32x16_bf16 v[0:15], v[84:87], v[96:99], v[0:15]
	global_load_dwordx4 v[96:99], v[70:71], off offset:896
	v_mfma_f32_32x32x16_bf16 v[16:31], v[84:87], v[100:103], v[16:31]
	global_load_dwordx4 v[84:87], v[68:69], off offset:896
	global_load_dwordx4 v[100:103], v[72:73], off offset:896
	s_waitcnt lgkmcnt(8)
	v_mfma_f32_32x32x16_bf16 v[32:47], v[134:137], v[162:165], v[32:47]
	s_waitcnt lgkmcnt(7)
	v_mfma_f32_32x32x16_bf16 v[48:63], v[134:137], v[186:189], v[48:63]
	global_load_dwordx4 v[134:137], v[64:65], off offset:896
	v_mfma_f32_32x32x16_bf16 v[0:15], v[154:157], v[162:165], v[0:15]
	global_load_dwordx4 v[162:165], v[74:75], off offset:896
	s_waitcnt lgkmcnt(0)
	s_barrier
	global_load_dwordx4 v[202:205], v[64:65], off offset:1024
	global_load_dwordx4 v[206:209], v[76:77], off offset:1024
	global_load_dwordx4 v[210:213], v[78:79], off offset:1024
	v_mfma_f32_32x32x16_bf16 v[16:31], v[154:157], v[186:189], v[16:31]
	ds_read_b128 v[138:141], v111
	ds_read_b128 v[142:145], v111 offset:4096
	ds_read_b128 v[146:149], v112 offset:32768
	ds_read_b128 v[150:153], v112 offset:36864
	ds_read_b128 v[154:157], v113
	ds_read_b128 v[158:161], v113 offset:4096
	ds_read_b128 v[186:189], v114 offset:32768
	ds_read_b128 v[198:201], v114 offset:36864
	s_waitcnt lgkmcnt(5)
	v_mfma_f32_32x32x16_bf16 v[32:47], v[138:141], v[146:149], v[32:47]
	s_waitcnt lgkmcnt(4)
	v_mfma_f32_32x32x16_bf16 v[48:63], v[138:141], v[150:153], v[48:63]
	v_mfma_f32_32x32x16_bf16 v[0:15], v[142:145], v[146:149], v[0:15]
	v_mfma_f32_32x32x16_bf16 v[16:31], v[142:145], v[150:153], v[16:31]
	ds_read_b128 v[138:141], v115
	ds_read_b128 v[142:145], v115 offset:4096
	ds_read_b128 v[146:149], v116 offset:32768
	ds_read_b128 v[150:153], v116 offset:36864
	s_waitcnt lgkmcnt(5)
	v_mfma_f32_32x32x16_bf16 v[32:47], v[154:157], v[186:189], v[32:47]
	s_waitcnt lgkmcnt(4)
	v_mfma_f32_32x32x16_bf16 v[48:63], v[154:157], v[198:201], v[48:63]
	v_mfma_f32_32x32x16_bf16 v[0:15], v[158:161], v[186:189], v[0:15]
	v_mfma_f32_32x32x16_bf16 v[16:31], v[158:161], v[198:201], v[16:31]
	ds_read_b128 v[154:157], v117
	ds_read_b128 v[158:161], v117 offset:4096
	ds_read_b128 v[186:189], v118 offset:32768
	ds_read_b128 v[198:201], v118 offset:36864
	s_waitcnt vmcnt(8)
	ds_write_b128 v104, v[80:83] offset:16384
	s_waitcnt vmcnt(6)
	ds_write_b128 v104, v[84:87] offset:20480
	ds_write_b128 v104, v[96:99] offset:24576
	s_waitcnt lgkmcnt(8)
	v_mfma_f32_32x32x16_bf16 v[32:47], v[138:141], v[146:149], v[32:47]
	s_waitcnt vmcnt(5)
	ds_write_b128 v104, v[100:103] offset:28672
	s_waitcnt vmcnt(4)
	ds_write_b128 v104, v[134:137] offset:49152
	s_waitcnt vmcnt(3)
	ds_write_b128 v104, v[162:165] offset:53248
	ds_write_b128 v104, v[190:193] offset:57344
	ds_write_b128 v104, v[194:197] offset:61440
	s_waitcnt lgkmcnt(12)
	v_mfma_f32_32x32x16_bf16 v[48:63], v[138:141], v[150:153], v[48:63]
	global_load_dwordx4 v[138:141], v[66:67], off offset:1024
	v_mfma_f32_32x32x16_bf16 v[0:15], v[142:145], v[146:149], v[0:15]
	global_load_dwordx4 v[146:149], v[70:71], off offset:1024
	v_mfma_f32_32x32x16_bf16 v[16:31], v[142:145], v[150:153], v[16:31]
	global_load_dwordx4 v[142:145], v[68:69], off offset:1024
	global_load_dwordx4 v[150:153], v[72:73], off offset:1024
	s_waitcnt lgkmcnt(9)
	v_mfma_f32_32x32x16_bf16 v[32:47], v[154:157], v[186:189], v[32:47]
	s_waitcnt lgkmcnt(8)
	v_mfma_f32_32x32x16_bf16 v[48:63], v[154:157], v[198:201], v[48:63]
	global_load_dwordx4 v[154:157], v[74:75], off offset:1024
	s_waitcnt lgkmcnt(0)
	s_barrier
	global_load_dwordx4 v[190:193], v[76:77], off offset:1152
	global_load_dwordx4 v[194:197], v[78:79], off offset:1152
	s_waitcnt vmcnt(6)
	ds_write_b128 v104, v[138:141]
	v_mfma_f32_32x32x16_bf16 v[0:15], v[158:161], v[186:189], v[0:15]
	v_mfma_f32_32x32x16_bf16 v[16:31], v[158:161], v[198:201], v[16:31]
	ds_read_b128 v[80:83], v111 offset:16384
	ds_read_b128 v[84:87], v111 offset:20480
	ds_read_b128 v[96:99], v112 offset:49152
	ds_read_b128 v[100:103], v112 offset:53248
	ds_read_b128 v[134:137], v113 offset:16384
	ds_read_b128 v[158:161], v113 offset:20480
	ds_read_b128 v[162:165], v114 offset:49152
	ds_read_b128 v[186:189], v114 offset:53248
	s_waitcnt lgkmcnt(5)
	v_mfma_f32_32x32x16_bf16 v[32:47], v[80:83], v[96:99], v[32:47]
	s_waitcnt lgkmcnt(4)
	v_mfma_f32_32x32x16_bf16 v[48:63], v[80:83], v[100:103], v[48:63]
	v_mfma_f32_32x32x16_bf16 v[0:15], v[84:87], v[96:99], v[0:15]
	v_mfma_f32_32x32x16_bf16 v[16:31], v[84:87], v[100:103], v[16:31]
	ds_read_b128 v[80:83], v115 offset:16384
	ds_read_b128 v[84:87], v115 offset:20480
	ds_read_b128 v[96:99], v116 offset:49152
	ds_read_b128 v[100:103], v116 offset:53248
	s_waitcnt lgkmcnt(5)
	v_mfma_f32_32x32x16_bf16 v[32:47], v[134:137], v[162:165], v[32:47]
	s_waitcnt lgkmcnt(4)
	v_mfma_f32_32x32x16_bf16 v[48:63], v[134:137], v[186:189], v[48:63]
	v_mfma_f32_32x32x16_bf16 v[0:15], v[158:161], v[162:165], v[0:15]
	v_mfma_f32_32x32x16_bf16 v[16:31], v[158:161], v[186:189], v[16:31]
	ds_read_b128 v[134:137], v117 offset:16384
	ds_read_b128 v[158:161], v117 offset:20480
	ds_read_b128 v[162:165], v118 offset:49152
	ds_read_b128 v[186:189], v118 offset:53248
	s_waitcnt vmcnt(4)
	ds_write_b128 v104, v[142:145] offset:4096
	ds_write_b128 v104, v[146:149] offset:8192
	s_waitcnt vmcnt(3)
	ds_write_b128 v104, v[150:153] offset:12288
	s_waitcnt lgkmcnt(8)
	v_mfma_f32_32x32x16_bf16 v[32:47], v[80:83], v[96:99], v[32:47]
	ds_write_b128 v104, v[202:205] offset:32768
	s_waitcnt vmcnt(2)
	ds_write_b128 v104, v[154:157] offset:36864
	ds_write_b128 v104, v[206:209] offset:40960
	ds_write_b128 v104, v[210:213] offset:45056
	s_waitcnt lgkmcnt(11)
	v_mfma_f32_32x32x16_bf16 v[48:63], v[80:83], v[100:103], v[48:63]
	global_load_dwordx4 v[80:83], v[66:67], off offset:1152
	v_mfma_f32_32x32x16_bf16 v[0:15], v[84:87], v[96:99], v[0:15]
	global_load_dwordx4 v[96:99], v[70:71], off offset:1152
	v_mfma_f32_32x32x16_bf16 v[16:31], v[84:87], v[100:103], v[16:31]
	global_load_dwordx4 v[84:87], v[68:69], off offset:1152
	global_load_dwordx4 v[100:103], v[72:73], off offset:1152
	s_waitcnt lgkmcnt(8)
	v_mfma_f32_32x32x16_bf16 v[32:47], v[134:137], v[162:165], v[32:47]
	s_waitcnt lgkmcnt(7)
	v_mfma_f32_32x32x16_bf16 v[48:63], v[134:137], v[186:189], v[48:63]
	global_load_dwordx4 v[134:137], v[64:65], off offset:1152
	v_mfma_f32_32x32x16_bf16 v[0:15], v[158:161], v[162:165], v[0:15]
	global_load_dwordx4 v[162:165], v[74:75], off offset:1152
	s_waitcnt lgkmcnt(0)
	s_barrier
	global_load_dwordx4 v[202:205], v[64:65], off offset:1280
	global_load_dwordx4 v[206:209], v[76:77], off offset:1280
	global_load_dwordx4 v[210:213], v[78:79], off offset:1280
	v_mfma_f32_32x32x16_bf16 v[16:31], v[158:161], v[186:189], v[16:31]
	ds_read_b128 v[138:141], v111
	ds_read_b128 v[142:145], v111 offset:4096
	ds_read_b128 v[146:149], v112 offset:32768
	ds_read_b128 v[150:153], v112 offset:36864
	ds_read_b128 v[154:157], v113
	ds_read_b128 v[158:161], v113 offset:4096
	ds_read_b128 v[186:189], v114 offset:32768
	ds_read_b128 v[198:201], v114 offset:36864
	s_waitcnt lgkmcnt(5)
	v_mfma_f32_32x32x16_bf16 v[32:47], v[138:141], v[146:149], v[32:47]
	s_waitcnt lgkmcnt(4)
	v_mfma_f32_32x32x16_bf16 v[48:63], v[138:141], v[150:153], v[48:63]
	v_mfma_f32_32x32x16_bf16 v[0:15], v[142:145], v[146:149], v[0:15]
	v_mfma_f32_32x32x16_bf16 v[16:31], v[142:145], v[150:153], v[16:31]
	ds_read_b128 v[138:141], v115
	ds_read_b128 v[142:145], v115 offset:4096
	ds_read_b128 v[146:149], v116 offset:32768
	ds_read_b128 v[150:153], v116 offset:36864
	s_waitcnt lgkmcnt(5)
	v_mfma_f32_32x32x16_bf16 v[32:47], v[154:157], v[186:189], v[32:47]
	s_waitcnt lgkmcnt(4)
	v_mfma_f32_32x32x16_bf16 v[48:63], v[154:157], v[198:201], v[48:63]
	v_mfma_f32_32x32x16_bf16 v[0:15], v[158:161], v[186:189], v[0:15]
	v_mfma_f32_32x32x16_bf16 v[16:31], v[158:161], v[198:201], v[16:31]
	ds_read_b128 v[154:157], v117
	ds_read_b128 v[158:161], v117 offset:4096
	ds_read_b128 v[186:189], v118 offset:32768
	ds_read_b128 v[198:201], v118 offset:36864
	s_waitcnt vmcnt(8)
	ds_write_b128 v104, v[80:83] offset:16384
	s_waitcnt vmcnt(6)
	ds_write_b128 v104, v[84:87] offset:20480
	ds_write_b128 v104, v[96:99] offset:24576
	s_waitcnt lgkmcnt(8)
	v_mfma_f32_32x32x16_bf16 v[32:47], v[138:141], v[146:149], v[32:47]
	s_waitcnt vmcnt(5)
	ds_write_b128 v104, v[100:103] offset:28672
	s_waitcnt vmcnt(4)
	ds_write_b128 v104, v[134:137] offset:49152
	s_waitcnt vmcnt(3)
	ds_write_b128 v104, v[162:165] offset:53248
	ds_write_b128 v104, v[190:193] offset:57344
	ds_write_b128 v104, v[194:197] offset:61440
	s_waitcnt lgkmcnt(12)
	v_mfma_f32_32x32x16_bf16 v[48:63], v[138:141], v[150:153], v[48:63]
	global_load_dwordx4 v[138:141], v[66:67], off offset:1280
	v_mfma_f32_32x32x16_bf16 v[0:15], v[142:145], v[146:149], v[0:15]
	global_load_dwordx4 v[146:149], v[70:71], off offset:1280
	v_mfma_f32_32x32x16_bf16 v[16:31], v[142:145], v[150:153], v[16:31]
	global_load_dwordx4 v[142:145], v[68:69], off offset:1280
	global_load_dwordx4 v[150:153], v[72:73], off offset:1280
	s_waitcnt lgkmcnt(9)
	v_mfma_f32_32x32x16_bf16 v[32:47], v[154:157], v[186:189], v[32:47]
	s_waitcnt lgkmcnt(8)
	v_mfma_f32_32x32x16_bf16 v[48:63], v[154:157], v[198:201], v[48:63]
	global_load_dwordx4 v[154:157], v[74:75], off offset:1280
	s_waitcnt lgkmcnt(0)
	s_barrier
	global_load_dwordx4 v[190:193], v[76:77], off offset:1408
	global_load_dwordx4 v[194:197], v[78:79], off offset:1408
	s_waitcnt vmcnt(6)
	ds_write_b128 v104, v[138:141]
	v_mfma_f32_32x32x16_bf16 v[0:15], v[158:161], v[186:189], v[0:15]
	v_mfma_f32_32x32x16_bf16 v[16:31], v[158:161], v[198:201], v[16:31]
	ds_read_b128 v[80:83], v111 offset:16384
	ds_read_b128 v[84:87], v111 offset:20480
	ds_read_b128 v[96:99], v112 offset:49152
	ds_read_b128 v[100:103], v112 offset:53248
	ds_read_b128 v[134:137], v113 offset:16384
	ds_read_b128 v[158:161], v113 offset:20480
	ds_read_b128 v[162:165], v114 offset:49152
	ds_read_b128 v[186:189], v114 offset:53248
	s_waitcnt lgkmcnt(5)
	v_mfma_f32_32x32x16_bf16 v[32:47], v[80:83], v[96:99], v[32:47]
	s_waitcnt lgkmcnt(4)
	v_mfma_f32_32x32x16_bf16 v[48:63], v[80:83], v[100:103], v[48:63]
	v_mfma_f32_32x32x16_bf16 v[0:15], v[84:87], v[96:99], v[0:15]
	v_mfma_f32_32x32x16_bf16 v[16:31], v[84:87], v[100:103], v[16:31]
	ds_read_b128 v[80:83], v115 offset:16384
	ds_read_b128 v[84:87], v115 offset:20480
	ds_read_b128 v[96:99], v116 offset:49152
	ds_read_b128 v[100:103], v116 offset:53248
	s_waitcnt lgkmcnt(5)
	v_mfma_f32_32x32x16_bf16 v[32:47], v[134:137], v[162:165], v[32:47]
	s_waitcnt lgkmcnt(4)
	v_mfma_f32_32x32x16_bf16 v[48:63], v[134:137], v[186:189], v[48:63]
	v_mfma_f32_32x32x16_bf16 v[0:15], v[158:161], v[162:165], v[0:15]
	v_mfma_f32_32x32x16_bf16 v[16:31], v[158:161], v[186:189], v[16:31]
	ds_read_b128 v[134:137], v117 offset:16384
	ds_read_b128 v[158:161], v117 offset:20480
	ds_read_b128 v[162:165], v118 offset:49152
	ds_read_b128 v[186:189], v118 offset:53248
	s_waitcnt vmcnt(4)
	ds_write_b128 v104, v[142:145] offset:4096
	ds_write_b128 v104, v[146:149] offset:8192
	s_waitcnt vmcnt(3)
	ds_write_b128 v104, v[150:153] offset:12288
	s_waitcnt lgkmcnt(8)
	v_mfma_f32_32x32x16_bf16 v[32:47], v[80:83], v[96:99], v[32:47]
	ds_write_b128 v104, v[202:205] offset:32768
	s_waitcnt vmcnt(2)
	ds_write_b128 v104, v[154:157] offset:36864
	ds_write_b128 v104, v[206:209] offset:40960
	ds_write_b128 v104, v[210:213] offset:45056
	s_waitcnt lgkmcnt(11)
	v_mfma_f32_32x32x16_bf16 v[48:63], v[80:83], v[100:103], v[48:63]
	global_load_dwordx4 v[80:83], v[66:67], off offset:1408
	v_mfma_f32_32x32x16_bf16 v[0:15], v[84:87], v[96:99], v[0:15]
	global_load_dwordx4 v[96:99], v[70:71], off offset:1408
	v_mfma_f32_32x32x16_bf16 v[16:31], v[84:87], v[100:103], v[16:31]
	global_load_dwordx4 v[84:87], v[68:69], off offset:1408
	global_load_dwordx4 v[100:103], v[72:73], off offset:1408
	s_waitcnt lgkmcnt(8)
	v_mfma_f32_32x32x16_bf16 v[32:47], v[134:137], v[162:165], v[32:47]
	s_waitcnt lgkmcnt(7)
	v_mfma_f32_32x32x16_bf16 v[48:63], v[134:137], v[186:189], v[48:63]
	global_load_dwordx4 v[134:137], v[64:65], off offset:1408
	v_mfma_f32_32x32x16_bf16 v[0:15], v[158:161], v[162:165], v[0:15]
	global_load_dwordx4 v[162:165], v[74:75], off offset:1408
	s_waitcnt lgkmcnt(0)
	s_barrier
	global_load_dwordx4 v[202:205], v[64:65], off offset:1536
	global_load_dwordx4 v[206:209], v[76:77], off offset:1536
	global_load_dwordx4 v[210:213], v[78:79], off offset:1536
	v_mfma_f32_32x32x16_bf16 v[16:31], v[158:161], v[186:189], v[16:31]
	ds_read_b128 v[138:141], v111
	ds_read_b128 v[142:145], v111 offset:4096
	ds_read_b128 v[146:149], v112 offset:32768
	ds_read_b128 v[150:153], v112 offset:36864
	ds_read_b128 v[154:157], v113
	ds_read_b128 v[158:161], v113 offset:4096
	ds_read_b128 v[186:189], v114 offset:32768
	ds_read_b128 v[198:201], v114 offset:36864
	s_waitcnt lgkmcnt(5)
	v_mfma_f32_32x32x16_bf16 v[32:47], v[138:141], v[146:149], v[32:47]
	s_waitcnt lgkmcnt(4)
	v_mfma_f32_32x32x16_bf16 v[48:63], v[138:141], v[150:153], v[48:63]
	v_mfma_f32_32x32x16_bf16 v[0:15], v[142:145], v[146:149], v[0:15]
	v_mfma_f32_32x32x16_bf16 v[16:31], v[142:145], v[150:153], v[16:31]
	ds_read_b128 v[138:141], v115
	ds_read_b128 v[142:145], v115 offset:4096
	ds_read_b128 v[146:149], v116 offset:32768
	ds_read_b128 v[150:153], v116 offset:36864
	s_waitcnt lgkmcnt(5)
	v_mfma_f32_32x32x16_bf16 v[32:47], v[154:157], v[186:189], v[32:47]
	s_waitcnt lgkmcnt(4)
	v_mfma_f32_32x32x16_bf16 v[48:63], v[154:157], v[198:201], v[48:63]
	v_mfma_f32_32x32x16_bf16 v[0:15], v[158:161], v[186:189], v[0:15]
	v_mfma_f32_32x32x16_bf16 v[16:31], v[158:161], v[198:201], v[16:31]
	ds_read_b128 v[154:157], v117
	ds_read_b128 v[158:161], v117 offset:4096
	ds_read_b128 v[186:189], v118 offset:32768
	ds_read_b128 v[198:201], v118 offset:36864
	s_waitcnt vmcnt(8)
	ds_write_b128 v104, v[80:83] offset:16384
	s_waitcnt vmcnt(6)
	ds_write_b128 v104, v[84:87] offset:20480
	ds_write_b128 v104, v[96:99] offset:24576
	s_waitcnt lgkmcnt(8)
	v_mfma_f32_32x32x16_bf16 v[32:47], v[138:141], v[146:149], v[32:47]
	s_waitcnt vmcnt(5)
	ds_write_b128 v104, v[100:103] offset:28672
	s_waitcnt vmcnt(4)
	ds_write_b128 v104, v[134:137] offset:49152
	s_waitcnt vmcnt(3)
	ds_write_b128 v104, v[162:165] offset:53248
	ds_write_b128 v104, v[190:193] offset:57344
	ds_write_b128 v104, v[194:197] offset:61440
	s_waitcnt lgkmcnt(12)
	v_mfma_f32_32x32x16_bf16 v[48:63], v[138:141], v[150:153], v[48:63]
	global_load_dwordx4 v[138:141], v[66:67], off offset:1536
	v_mfma_f32_32x32x16_bf16 v[0:15], v[142:145], v[146:149], v[0:15]
	global_load_dwordx4 v[146:149], v[70:71], off offset:1536
	v_mfma_f32_32x32x16_bf16 v[16:31], v[142:145], v[150:153], v[16:31]
	global_load_dwordx4 v[142:145], v[68:69], off offset:1536
	global_load_dwordx4 v[150:153], v[72:73], off offset:1536
	s_waitcnt lgkmcnt(9)
	v_mfma_f32_32x32x16_bf16 v[32:47], v[154:157], v[186:189], v[32:47]
	s_waitcnt lgkmcnt(8)
	v_mfma_f32_32x32x16_bf16 v[48:63], v[154:157], v[198:201], v[48:63]
	global_load_dwordx4 v[154:157], v[74:75], off offset:1536
	s_waitcnt lgkmcnt(0)
	s_barrier
	global_load_dwordx4 v[190:193], v[76:77], off offset:1664
	global_load_dwordx4 v[194:197], v[78:79], off offset:1664
	s_waitcnt vmcnt(6)
	ds_write_b128 v104, v[138:141]
	v_mfma_f32_32x32x16_bf16 v[0:15], v[158:161], v[186:189], v[0:15]
	v_mfma_f32_32x32x16_bf16 v[16:31], v[158:161], v[198:201], v[16:31]
	ds_read_b128 v[80:83], v111 offset:16384
	ds_read_b128 v[84:87], v111 offset:20480
	ds_read_b128 v[96:99], v112 offset:49152
	ds_read_b128 v[100:103], v112 offset:53248
	ds_read_b128 v[134:137], v113 offset:16384
	ds_read_b128 v[158:161], v113 offset:20480
	ds_read_b128 v[162:165], v114 offset:49152
	ds_read_b128 v[186:189], v114 offset:53248
	s_waitcnt lgkmcnt(5)
	v_mfma_f32_32x32x16_bf16 v[32:47], v[80:83], v[96:99], v[32:47]
	s_waitcnt lgkmcnt(4)
	v_mfma_f32_32x32x16_bf16 v[48:63], v[80:83], v[100:103], v[48:63]
	v_mfma_f32_32x32x16_bf16 v[0:15], v[84:87], v[96:99], v[0:15]
	v_mfma_f32_32x32x16_bf16 v[16:31], v[84:87], v[100:103], v[16:31]
	ds_read_b128 v[80:83], v115 offset:16384
	ds_read_b128 v[84:87], v115 offset:20480
	ds_read_b128 v[96:99], v116 offset:49152
	ds_read_b128 v[100:103], v116 offset:53248
	s_waitcnt lgkmcnt(5)
	v_mfma_f32_32x32x16_bf16 v[32:47], v[134:137], v[162:165], v[32:47]
	s_waitcnt lgkmcnt(4)
	v_mfma_f32_32x32x16_bf16 v[48:63], v[134:137], v[186:189], v[48:63]
	v_mfma_f32_32x32x16_bf16 v[0:15], v[158:161], v[162:165], v[0:15]
	v_mfma_f32_32x32x16_bf16 v[16:31], v[158:161], v[186:189], v[16:31]
	ds_read_b128 v[134:137], v117 offset:16384
	ds_read_b128 v[158:161], v117 offset:20480
	ds_read_b128 v[162:165], v118 offset:49152
	ds_read_b128 v[186:189], v118 offset:53248
	s_waitcnt vmcnt(4)
	ds_write_b128 v104, v[142:145] offset:4096
	ds_write_b128 v104, v[146:149] offset:8192
	s_waitcnt vmcnt(3)
	ds_write_b128 v104, v[150:153] offset:12288
	s_waitcnt lgkmcnt(8)
	v_mfma_f32_32x32x16_bf16 v[32:47], v[80:83], v[96:99], v[32:47]
	ds_write_b128 v104, v[202:205] offset:32768
	s_waitcnt vmcnt(2)
	ds_write_b128 v104, v[154:157] offset:36864
	ds_write_b128 v104, v[206:209] offset:40960
	ds_write_b128 v104, v[210:213] offset:45056
	s_waitcnt lgkmcnt(11)
	v_mfma_f32_32x32x16_bf16 v[48:63], v[80:83], v[100:103], v[48:63]
	global_load_dwordx4 v[80:83], v[66:67], off offset:1664
	v_mfma_f32_32x32x16_bf16 v[0:15], v[84:87], v[96:99], v[0:15]
	global_load_dwordx4 v[96:99], v[70:71], off offset:1664
	v_mfma_f32_32x32x16_bf16 v[16:31], v[84:87], v[100:103], v[16:31]
	global_load_dwordx4 v[84:87], v[68:69], off offset:1664
	global_load_dwordx4 v[100:103], v[72:73], off offset:1664
	s_waitcnt lgkmcnt(8)
	v_mfma_f32_32x32x16_bf16 v[32:47], v[134:137], v[162:165], v[32:47]
	s_waitcnt lgkmcnt(7)
	v_mfma_f32_32x32x16_bf16 v[48:63], v[134:137], v[186:189], v[48:63]
	global_load_dwordx4 v[134:137], v[64:65], off offset:1664
	v_mfma_f32_32x32x16_bf16 v[0:15], v[158:161], v[162:165], v[0:15]
	global_load_dwordx4 v[162:165], v[74:75], off offset:1664
	s_waitcnt lgkmcnt(0)
	s_barrier
	global_load_dwordx4 v[202:205], v[64:65], off offset:1792
	global_load_dwordx4 v[206:209], v[76:77], off offset:1792
	global_load_dwordx4 v[210:213], v[78:79], off offset:1792
	v_mfma_f32_32x32x16_bf16 v[16:31], v[158:161], v[186:189], v[16:31]
	ds_read_b128 v[138:141], v111
	ds_read_b128 v[142:145], v111 offset:4096
	ds_read_b128 v[146:149], v112 offset:32768
	ds_read_b128 v[150:153], v112 offset:36864
	ds_read_b128 v[154:157], v113
	ds_read_b128 v[158:161], v113 offset:4096
	ds_read_b128 v[186:189], v114 offset:32768
	ds_read_b128 v[198:201], v114 offset:36864
	s_waitcnt lgkmcnt(5)
	v_mfma_f32_32x32x16_bf16 v[32:47], v[138:141], v[146:149], v[32:47]
	s_waitcnt lgkmcnt(4)
	v_mfma_f32_32x32x16_bf16 v[48:63], v[138:141], v[150:153], v[48:63]
	v_mfma_f32_32x32x16_bf16 v[0:15], v[142:145], v[146:149], v[0:15]
	v_mfma_f32_32x32x16_bf16 v[16:31], v[142:145], v[150:153], v[16:31]
	ds_read_b128 v[138:141], v115
	ds_read_b128 v[142:145], v115 offset:4096
	ds_read_b128 v[146:149], v116 offset:32768
	ds_read_b128 v[150:153], v116 offset:36864
	s_waitcnt lgkmcnt(5)
	v_mfma_f32_32x32x16_bf16 v[32:47], v[154:157], v[186:189], v[32:47]
	s_waitcnt lgkmcnt(4)
	v_mfma_f32_32x32x16_bf16 v[48:63], v[154:157], v[198:201], v[48:63]
	v_mfma_f32_32x32x16_bf16 v[0:15], v[158:161], v[186:189], v[0:15]
	v_mfma_f32_32x32x16_bf16 v[16:31], v[158:161], v[198:201], v[16:31]
	ds_read_b128 v[154:157], v117
	ds_read_b128 v[158:161], v117 offset:4096
	ds_read_b128 v[186:189], v118 offset:32768
	ds_read_b128 v[198:201], v118 offset:36864
	s_waitcnt vmcnt(8)
	ds_write_b128 v104, v[80:83] offset:16384
	s_waitcnt vmcnt(6)
	ds_write_b128 v104, v[84:87] offset:20480
	ds_write_b128 v104, v[96:99] offset:24576
	s_waitcnt lgkmcnt(8)
	v_mfma_f32_32x32x16_bf16 v[32:47], v[138:141], v[146:149], v[32:47]
	s_waitcnt vmcnt(5)
	ds_write_b128 v104, v[100:103] offset:28672
	s_waitcnt vmcnt(4)
	ds_write_b128 v104, v[134:137] offset:49152
	s_waitcnt vmcnt(3)
	ds_write_b128 v104, v[162:165] offset:53248
	ds_write_b128 v104, v[190:193] offset:57344
	ds_write_b128 v104, v[194:197] offset:61440
	s_waitcnt lgkmcnt(12)
	v_mfma_f32_32x32x16_bf16 v[48:63], v[138:141], v[150:153], v[48:63]
	global_load_dwordx4 v[138:141], v[66:67], off offset:1792
	v_mfma_f32_32x32x16_bf16 v[0:15], v[142:145], v[146:149], v[0:15]
	global_load_dwordx4 v[146:149], v[70:71], off offset:1792
	v_mfma_f32_32x32x16_bf16 v[16:31], v[142:145], v[150:153], v[16:31]
	global_load_dwordx4 v[142:145], v[68:69], off offset:1792
	global_load_dwordx4 v[150:153], v[72:73], off offset:1792
	s_waitcnt lgkmcnt(9)
	v_mfma_f32_32x32x16_bf16 v[32:47], v[154:157], v[186:189], v[32:47]
	s_waitcnt lgkmcnt(8)
	v_mfma_f32_32x32x16_bf16 v[48:63], v[154:157], v[198:201], v[48:63]
	global_load_dwordx4 v[154:157], v[74:75], off offset:1792
	s_waitcnt lgkmcnt(0)
	s_barrier
	s_waitcnt vmcnt(4)
	ds_write_b128 v104, v[138:141]
	v_mfma_f32_32x32x16_bf16 v[0:15], v[158:161], v[186:189], v[0:15]
	v_mfma_f32_32x32x16_bf16 v[16:31], v[158:161], v[198:201], v[16:31]
	ds_read_b128 v[80:83], v111 offset:16384
	ds_read_b128 v[96:99], v112 offset:49152
	ds_read_b128 v[100:103], v112 offset:53248
	ds_read_b128 v[84:87], v111 offset:20480
	ds_read_b128 v[134:137], v113 offset:16384
	ds_read_b128 v[158:161], v113 offset:20480
	ds_read_b128 v[162:165], v114 offset:49152
	ds_read_b128 v[186:189], v114 offset:53248
	s_waitcnt lgkmcnt(6)
	v_mfma_f32_32x32x16_bf16 v[32:47], v[80:83], v[96:99], v[32:47]
	s_waitcnt lgkmcnt(5)
	v_mfma_f32_32x32x16_bf16 v[48:63], v[80:83], v[100:103], v[48:63]
	s_waitcnt lgkmcnt(4)
	v_mfma_f32_32x32x16_bf16 v[0:15], v[84:87], v[96:99], v[0:15]
	v_mfma_f32_32x32x16_bf16 v[16:31], v[84:87], v[100:103], v[16:31]
	ds_read_b128 v[80:83], v115 offset:16384
	ds_read_b128 v[84:87], v115 offset:20480
	ds_read_b128 v[96:99], v116 offset:49152
	ds_read_b128 v[100:103], v116 offset:53248
	s_waitcnt lgkmcnt(5)
	v_mfma_f32_32x32x16_bf16 v[32:47], v[134:137], v[162:165], v[32:47]
	s_waitcnt lgkmcnt(4)
	v_mfma_f32_32x32x16_bf16 v[48:63], v[134:137], v[186:189], v[48:63]
	v_mfma_f32_32x32x16_bf16 v[0:15], v[158:161], v[162:165], v[0:15]
	v_mfma_f32_32x32x16_bf16 v[16:31], v[158:161], v[186:189], v[16:31]
	ds_read_b128 v[134:137], v117 offset:16384
	ds_read_b128 v[158:161], v117 offset:20480
	ds_read_b128 v[162:165], v118 offset:49152
	ds_read_b128 v[186:189], v118 offset:53248
	s_waitcnt vmcnt(2)
	ds_write_b128 v104, v[142:145] offset:4096
	ds_write_b128 v104, v[146:149] offset:8192
	s_waitcnt vmcnt(1)
	ds_write_b128 v104, v[150:153] offset:12288
	s_waitcnt lgkmcnt(8)
	v_mfma_f32_32x32x16_bf16 v[32:47], v[80:83], v[96:99], v[32:47]
	ds_write_b128 v104, v[202:205] offset:32768
	s_waitcnt vmcnt(0)
	ds_write_b128 v104, v[154:157] offset:36864
	ds_write_b128 v104, v[206:209] offset:40960
	ds_write_b128 v104, v[210:213] offset:45056
	s_waitcnt lgkmcnt(11)
	v_mfma_f32_32x32x16_bf16 v[48:63], v[80:83], v[100:103], v[48:63]
	global_load_dwordx4 v[80:83], v[66:67], off offset:1920
	s_nop 0
	global_load_dwordx4 v[66:69], v[68:69], off offset:1920
	v_mfma_f32_32x32x16_bf16 v[0:15], v[84:87], v[96:99], v[0:15]
	global_load_dwordx4 v[96:99], v[64:65], off offset:1920
	v_mfma_f32_32x32x16_bf16 v[16:31], v[84:87], v[100:103], v[16:31]
	global_load_dwordx4 v[84:87], v[70:71], off offset:1920
	global_load_dwordx4 v[100:103], v[74:75], off offset:1920
	s_nop 0
	global_load_dwordx4 v[70:73], v[72:73], off offset:1920
	s_nop 0
	global_load_dwordx4 v[74:77], v[76:77], off offset:1920
	s_waitcnt lgkmcnt(8)
	v_mfma_f32_32x32x16_bf16 v[32:47], v[134:137], v[162:165], v[32:47]
	s_waitcnt lgkmcnt(7)
	v_mfma_f32_32x32x16_bf16 v[48:63], v[134:137], v[186:189], v[48:63]
	global_load_dwordx4 v[134:137], v[78:79], off offset:1920
	s_waitcnt lgkmcnt(0)
	s_barrier
	v_mfma_f32_32x32x16_bf16 v[0:15], v[158:161], v[162:165], v[0:15]
	v_mfma_f32_32x32x16_bf16 v[16:31], v[158:161], v[186:189], v[16:31]
	ds_read_b128 v[138:141], v111
	ds_read_b128 v[142:145], v111 offset:4096
	ds_read_b128 v[146:149], v112 offset:32768
	ds_read_b128 v[150:153], v112 offset:36864
	ds_read_b128 v[154:157], v113
	ds_read_b128 v[158:161], v113 offset:4096
	ds_read_b128 v[162:165], v114 offset:32768
	ds_read_b128 v[186:189], v114 offset:36864
	s_waitcnt lgkmcnt(5)
	v_mfma_f32_32x32x16_bf16 v[32:47], v[138:141], v[146:149], v[32:47]
	s_waitcnt lgkmcnt(4)
	v_mfma_f32_32x32x16_bf16 v[48:63], v[138:141], v[150:153], v[48:63]
	v_mfma_f32_32x32x16_bf16 v[0:15], v[142:145], v[146:149], v[0:15]
	v_mfma_f32_32x32x16_bf16 v[16:31], v[142:145], v[150:153], v[16:31]
	ds_read_b128 v[138:141], v115
	ds_read_b128 v[142:145], v115 offset:4096
	ds_read_b128 v[146:149], v116 offset:32768
	ds_read_b128 v[150:153], v116 offset:36864
	s_waitcnt lgkmcnt(5)
	v_mfma_f32_32x32x16_bf16 v[32:47], v[154:157], v[162:165], v[32:47]
	s_waitcnt lgkmcnt(4)
	v_mfma_f32_32x32x16_bf16 v[48:63], v[154:157], v[186:189], v[48:63]
	v_mfma_f32_32x32x16_bf16 v[0:15], v[158:161], v[162:165], v[0:15]
	v_mfma_f32_32x32x16_bf16 v[16:31], v[158:161], v[186:189], v[16:31]
	ds_read_b128 v[154:157], v117
	ds_read_b128 v[158:161], v117 offset:4096
	ds_read_b128 v[162:165], v118 offset:32768
	ds_read_b128 v[186:189], v118 offset:36864
	s_waitcnt vmcnt(7)
	ds_write_b128 v104, v[80:83] offset:16384
	s_waitcnt vmcnt(6)
	ds_write_b128 v104, v[66:69] offset:20480
	s_waitcnt vmcnt(4)
	ds_write_b128 v104, v[84:87] offset:24576
	s_waitcnt lgkmcnt(8)
	v_mfma_f32_32x32x16_bf16 v[32:47], v[138:141], v[146:149], v[32:47]
	s_waitcnt vmcnt(2)
	ds_write_b128 v104, v[70:73] offset:28672
	ds_write_b128 v104, v[96:99] offset:49152
	ds_write_b128 v104, v[100:103] offset:53248
	s_waitcnt vmcnt(1)
	ds_write_b128 v104, v[74:77] offset:57344
	s_waitcnt vmcnt(0)
	ds_write_b128 v104, v[134:137] offset:61440
	s_waitcnt lgkmcnt(0)
	s_barrier
	v_mfma_f32_32x32x16_bf16 v[48:63], v[138:141], v[150:153], v[48:63]
	v_mfma_f32_32x32x16_bf16 v[0:15], v[142:145], v[146:149], v[0:15]
	v_mfma_f32_32x32x16_bf16 v[16:31], v[142:145], v[150:153], v[16:31]
	v_mfma_f32_32x32x16_bf16 v[32:47], v[154:157], v[162:165], v[32:47]
	v_mfma_f32_32x32x16_bf16 v[48:63], v[154:157], v[186:189], v[48:63]
	v_mfma_f32_32x32x16_bf16 v[0:15], v[158:161], v[162:165], v[0:15]
	v_mfma_f32_32x32x16_bf16 v[16:31], v[158:161], v[186:189], v[16:31]
	ds_read_b128 v[68:71], v111 offset:20480
	ds_read_b128 v[64:67], v111 offset:16384
	ds_read_b128 v[72:75], v112 offset:49152
	ds_read_b128 v[76:79], v112 offset:53248
	ds_read_b128 v[100:103], v113 offset:20480
	ds_read_b128 v[96:99], v113 offset:16384
	ds_read_b128 v[134:137], v114 offset:49152
	ds_read_b128 v[138:141], v114 offset:53248
	s_waitcnt lgkmcnt(5)
	v_mfma_f32_32x32x16_bf16 v[0:15], v[68:71], v[72:75], v[0:15]
	s_waitcnt lgkmcnt(4)
	v_mfma_f32_32x32x16_bf16 v[16:31], v[68:71], v[76:79], v[16:31]
	v_mfma_f32_32x32x16_bf16 v[48:63], v[64:67], v[76:79], v[48:63]
	v_mfma_f32_32x32x16_bf16 v[32:47], v[64:67], v[72:75], v[32:47]
	ds_read_b128 v[80:83], v115 offset:20480
	ds_read_b128 v[142:145], v115 offset:16384
	ds_read_b128 v[146:149], v116 offset:49152
	ds_read_b128 v[84:87], v116 offset:53248
	s_waitcnt lgkmcnt(5)
	v_mfma_f32_32x32x16_bf16 v[0:15], v[100:103], v[134:137], v[0:15]
	s_waitcnt lgkmcnt(4)
	v_mfma_f32_32x32x16_bf16 v[16:31], v[100:103], v[138:141], v[16:31]
	v_mfma_f32_32x32x16_bf16 v[48:63], v[96:99], v[138:141], v[48:63]
	v_mfma_f32_32x32x16_bf16 v[32:47], v[96:99], v[134:137], v[32:47]
	v_or_b32_e32 v98, s6, v105
	ds_read_b128 v[76:79], v117 offset:16384
	ds_read_b128 v[64:67], v117 offset:20480
	ds_read_b128 v[72:75], v118 offset:49152
	ds_read_b128 v[68:71], v118 offset:53248
	v_add_lshl_u32 v88, v98, v106, 11
	v_or_b32_e32 v96, s0, v108
	s_waitcnt lgkmcnt(5)
	v_mfma_f32_32x32x16_bf16 v[0:15], v[80:83], v[146:149], v[0:15]
	v_ashrrev_i32_e32 v97, 31, v96
	s_waitcnt lgkmcnt(0)
	s_barrier
	v_mfma_f32_32x32x16_bf16 v[16:31], v[80:83], v[84:87], v[16:31]
	v_lshl_add_u64 v[80:81], s[0:1], 1, v[94:95]
	v_lshl_add_u64 v[82:83], v[80:81], 0, v[88:89]
	v_add_lshl_u32 v88, v98, v107, 11
	v_lshl_add_u64 v[134:135], v[80:81], 0, v[88:89]
	v_mfma_f32_32x32x16_bf16 v[48:63], v[142:145], v[84:87], v[48:63]
	v_or_b32_e32 v86, 32, v98
	v_add_lshl_u32 v88, v86, v106, 11
	v_lshl_add_u64 v[136:137], v[80:81], 0, v[88:89]
	v_add_lshl_u32 v88, v86, v107, 11
	v_lshl_add_u64 v[84:85], v[96:97], 1, s[42:43]
	v_lshl_add_u64 v[138:139], v[80:81], 0, v[88:89]
	v_add_lshl_u32 v88, s6, v109, 11
	v_mfma_f32_32x32x16_bf16 v[32:47], v[142:145], v[146:149], v[32:47]
	v_lshl_add_u64 v[100:101], v[84:85], 0, v[88:89]
	v_add_lshl_u32 v88, s6, v110, 11
	v_lshl_add_u64 v[102:103], v[84:85], 0, v[88:89]
	v_add_lshl_u32 v88, s4, v109, 11
	v_lshl_add_u64 v[98:99], v[84:85], 0, v[88:89]
	v_add_lshl_u32 v88, s4, v110, 11
	v_lshl_add_u64 v[96:97], v[84:85], 0, v[88:89]
	global_load_dwordx4 v[84:87], v[82:83], off nt
	v_mfma_f32_32x32x16_bf16 v[32:47], v[76:79], v[72:75], v[32:47]
	global_load_dwordx4 v[80:83], v[134:135], off nt
	v_mfma_f32_32x32x16_bf16 v[48:63], v[76:79], v[68:71], v[48:63]
	global_load_dwordx4 v[76:79], v[136:137], off nt
	v_mfma_f32_32x32x16_bf16 v[0:15], v[64:67], v[72:75], v[0:15]
	global_load_dwordx4 v[72:75], v[138:139], off nt
	s_nop 8
	ds_write2_b32 v119, v32, v48 offset1:32
	ds_write2_b32 v119, v33, v49 offset0:132 offset1:164
	ds_write2_b32 v122, v34, v50 offset0:8 offset1:40
	ds_write2_b32 v122, v35, v51 offset0:140 offset1:172
	ds_write2_b32 v123, v36, v52 offset0:32 offset1:64
	ds_write2_b32 v123, v37, v53 offset0:164 offset1:196
	ds_write2_b32 v124, v38, v54 offset0:40 offset1:72
	ds_write2_b32 v124, v39, v55 offset0:172 offset1:204
	ds_write2_b32 v125, v40, v56 offset0:64 offset1:96
	ds_write2_b32 v125, v41, v57 offset0:196 offset1:228
	ds_write2_b32 v126, v42, v58 offset0:72 offset1:104
	ds_write2_b32 v126, v43, v59 offset0:204 offset1:236
	ds_write2_b32 v127, v44, v60 offset0:96 offset1:128
	ds_write2_b32 v129, v45, v61 offset0:100 offset1:132
	ds_write2_b32 v130, v46, v62 offset0:104 offset1:136
	ds_write2_b32 v131, v47, v63 offset0:108 offset1:140
	s_waitcnt lgkmcnt(0)
	s_barrier
	ds_read_b128 v[32:35], v120 offset:128
	ds_read_b128 v[40:43], v120
	ds_read_b128 v[44:47], v120 offset:16
	ds_read_b128 v[36:39], v120 offset:144
	v_mfma_f32_32x32x16_bf16 v[16:31], v[64:67], v[68:71], v[16:31]
	ds_read_b128 v[48:51], v121 offset:128
	s_waitcnt lgkmcnt(4)
	v_mul_f32_e32 v64, 0xbfb8aa3b, v32
	v_mul_f32_e32 v66, 0xbfb8aa3b, v34
	v_mul_f32_e32 v65, 0xbfb8aa3b, v33
	s_waitcnt lgkmcnt(3)
	v_mov_b32_e32 v32, v40
	v_mov_b32_e32 v33, v42
	v_mov_b32_e32 v42, v41
	v_exp_f32_e32 v40, v64
	v_exp_f32_e32 v41, v66
	v_mul_f32_e32 v67, 0xbfb8aa3b, v35
	s_waitcnt lgkmcnt(2)
	v_mov_b32_e32 v34, v44
	v_mov_b32_e32 v35, v46
	v_mov_b32_e32 v46, v45
	v_exp_f32_e32 v44, v65
	v_exp_f32_e32 v45, v67
	ds_read_b128 v[52:55], v121 offset:144
	s_waitcnt lgkmcnt(2)
	v_mul_f32_e32 v68, 0xbfb8aa3b, v36
	v_mul_f32_e32 v70, 0xbfb8aa3b, v38
	s_waitcnt lgkmcnt(1)
	v_mul_f32_e32 v88, 0xbfb8aa3b, v48
	v_mul_f32_e32 v133, 0xbfb8aa3b, v49
	v_exp_f32_e32 v48, v68
	v_exp_f32_e32 v49, v70
	v_pk_add_f32 v[40:41], v[40:41], 1.0 op_sel_hi:[1,0]
	v_mul_f32_e32 v69, 0xbfb8aa3b, v37
	v_mul_f32_e32 v71, 0xbfb8aa3b, v39
	ds_read_b128 v[56:59], v121
	v_mul_f32_e32 v134, 0xbfb8aa3b, v50
	v_mul_f32_e32 v135, 0xbfb8aa3b, v51
	v_exp_f32_e32 v50, v69
	v_exp_f32_e32 v51, v71
	v_pk_add_f32 v[44:45], v[44:45], 1.0 op_sel_hi:[1,0]
	s_waitcnt lgkmcnt(1)
	v_mul_f32_e32 v136, 0xbfb8aa3b, v52
	v_mul_f32_e32 v137, 0xbfb8aa3b, v53
	v_exp_f32_e32 v52, v88
	v_exp_f32_e32 v53, v134
	v_pk_add_f32 v[48:49], v[48:49], 1.0 op_sel_hi:[1,0]
	ds_read_b128 v[60:63], v121 offset:16
	v_mul_f32_e32 v138, 0xbfb8aa3b, v54
	v_mul_f32_e32 v139, 0xbfb8aa3b, v55
	v_exp_f32_e32 v54, v133
	v_exp_f32_e32 v55, v135
	v_pk_add_f32 v[50:51], v[50:51], 1.0 op_sel_hi:[1,0]
	s_waitcnt lgkmcnt(1)
	v_mov_b32_e32 v36, v56
	v_exp_f32_e32 v56, v136
	v_mov_b32_e32 v37, v58
	v_mov_b32_e32 v58, v57
	v_exp_f32_e32 v57, v138
	v_pk_add_f32 v[52:53], v[52:53], 1.0 op_sel_hi:[1,0]
	s_waitcnt lgkmcnt(0)
	v_mov_b32_e32 v38, v60
	v_mov_b32_e32 v39, v62
	v_mov_b32_e32 v62, v61
	v_exp_f32_e32 v60, v137
	v_exp_f32_e32 v61, v139
	v_pk_add_f32 v[54:55], v[54:55], 1.0 op_sel_hi:[1,0]
	v_pk_add_f32 v[56:57], v[56:57], 1.0 op_sel_hi:[1,0]
	s_mov_b64 vcc, s[30:31]
	v_rcp_f32_e32 v41, v41
	s_nop 0
	s_mov_b64 vcc, s[28:29]
	v_pk_add_f32 v[60:61], v[60:61], 1.0 op_sel_hi:[1,0]
	v_rcp_f32_e32 v40, v40
	s_nop 0
	s_mov_b64 vcc, s[26:27]
	v_pk_mul_f32 v[64:65], v[32:33], v[40:41]
	s_mov_b64 vcc, s[24:25]
	v_rcp_f32_e32 v33, v45
	s_nop 0
	v_rcp_f32_e32 v32, v44
	s_nop 0
	s_mov_b64 vcc, s[22:23]
	v_pk_mul_f32 v[66:67], v[42:43], v[32:33]
	s_mov_b64 vcc, s[20:21]
	v_rcp_f32_e32 v33, v49
	s_nop 0
	v_rcp_f32_e32 v32, v48
	s_nop 0
	s_mov_b64 vcc, s[16:17]
	v_pk_mul_f32 v[48:49], v[34:35], v[32:33]
	s_mov_b64 vcc, s[14:15]
	v_rcp_f32_e32 v33, v51
	s_nop 0
	v_rcp_f32_e32 v32, v50
	s_nop 0
	s_mov_b64 vcc, s[12:13]
	v_pk_mul_f32 v[50:51], v[46:47], v[32:33]
	s_mov_b64 vcc, s[10:11]
	v_rcp_f32_e32 v33, v53
	s_nop 0
	v_rcp_f32_e32 v32, v52
	s_nop 0
	s_mov_b64 vcc, s[8:9]
	v_pk_mul_f32 v[52:53], v[36:37], v[32:33]
	s_mov_b64 vcc, s[6:7]
	v_rcp_f32_e32 v33, v55
	s_nop 0
	v_rcp_f32_e32 v32, v54
	s_nop 0
	s_mov_b64 vcc, s[4:5]
	v_pk_mul_f32 v[54:55], v[58:59], v[32:33]
	s_mov_b64 vcc, s[34:35]
	v_rcp_f32_e32 v33, v57
	s_nop 0
	v_rcp_f32_e32 v32, v56
	s_nop 0
	s_mov_b64 vcc, s[0:1]
	v_pk_mul_f32 v[56:57], v[38:39], v[32:33]
	v_rcp_f32_e32 v33, v61
	s_nop 0
	v_rcp_f32_e32 v32, v60
	s_nop 0
	v_pk_mul_f32 v[58:59], v[62:63], v[32:33]
	s_waitcnt vmcnt(3)
	v_lshlrev_b32_e32 v61, 16, v85
	v_lshlrev_b32_e32 v60, 16, v84
	v_and_b32_e32 v63, 0xffff0000, v85
	v_and_b32_e32 v62, 0xffff0000, v84
	v_lshlrev_b32_e32 v69, 16, v87
	v_lshlrev_b32_e32 v68, 16, v86
	v_and_b32_e32 v71, 0xffff0000, v87
	v_and_b32_e32 v70, 0xffff0000, v86
	s_waitcnt vmcnt(2)
	v_lshlrev_b32_e32 v85, 16, v81
	v_lshlrev_b32_e32 v84, 16, v80
	v_and_b32_e32 v81, 0xffff0000, v81
	v_and_b32_e32 v80, 0xffff0000, v80
	v_lshlrev_b32_e32 v87, 16, v83
	v_lshlrev_b32_e32 v86, 16, v82
	v_and_b32_e32 v83, 0xffff0000, v83
	v_and_b32_e32 v82, 0xffff0000, v82
	v_pk_mul_f32 v[60:61], v[64:65], v[60:61]
	v_pk_mul_f32 v[62:63], v[66:67], v[62:63]
	v_pk_mul_f32 v[48:49], v[48:49], v[68:69]
	v_pk_mul_f32 v[50:51], v[50:51], v[70:71]
	v_pk_mul_f32 v[54:55], v[54:55], v[80:81]
	v_pk_mul_f32 v[56:57], v[56:57], v[86:87]
	v_pk_mul_f32 v[58:59], v[58:59], v[82:83]
	s_waitcnt vmcnt(1)
	v_lshlrev_b32_e32 v47, 16, v77
	v_lshlrev_b32_e32 v46, 16, v76
	v_and_b32_e32 v45, 0xffff0000, v77
	v_and_b32_e32 v44, 0xffff0000, v76
	v_lshlrev_b32_e32 v43, 16, v79
	v_lshlrev_b32_e32 v42, 16, v78
	v_and_b32_e32 v41, 0xffff0000, v79
	v_and_b32_e32 v40, 0xffff0000, v78
	s_waitcnt vmcnt(0)
	v_lshlrev_b32_e32 v35, 16, v75
	v_lshlrev_b32_e32 v34, 16, v74
	v_and_b32_e32 v33, 0xffff0000, v75
	v_and_b32_e32 v32, 0xffff0000, v74
	v_pk_mul_f32 v[52:53], v[52:53], v[84:85]
	v_and_b32_sdwa v64, v61, v132 dst_sel:DWORD dst_unused:UNUSED_PAD src0_sel:WORD_1 src1_sel:DWORD
	v_and_b32_sdwa v65, v60, v132 dst_sel:DWORD dst_unused:UNUSED_PAD src0_sel:WORD_1 src1_sel:DWORD
	v_and_b32_sdwa v66, v63, v132 dst_sel:DWORD dst_unused:UNUSED_PAD src0_sel:WORD_1 src1_sel:DWORD
	v_and_b32_sdwa v67, v62, v132 dst_sel:DWORD dst_unused:UNUSED_PAD src0_sel:WORD_1 src1_sel:DWORD
	v_and_b32_sdwa v68, v49, v132 dst_sel:DWORD dst_unused:UNUSED_PAD src0_sel:WORD_1 src1_sel:DWORD
	v_and_b32_sdwa v69, v48, v132 dst_sel:DWORD dst_unused:UNUSED_PAD src0_sel:WORD_1 src1_sel:DWORD
	v_and_b32_sdwa v70, v51, v132 dst_sel:DWORD dst_unused:UNUSED_PAD src0_sel:WORD_1 src1_sel:DWORD
	v_and_b32_sdwa v71, v50, v132 dst_sel:DWORD dst_unused:UNUSED_PAD src0_sel:WORD_1 src1_sel:DWORD
	v_and_b32_sdwa v74, v55, v132 dst_sel:DWORD dst_unused:UNUSED_PAD src0_sel:WORD_1 src1_sel:DWORD
	v_and_b32_sdwa v75, v54, v132 dst_sel:DWORD dst_unused:UNUSED_PAD src0_sel:WORD_1 src1_sel:DWORD
	v_and_b32_sdwa v76, v57, v132 dst_sel:DWORD dst_unused:UNUSED_PAD src0_sel:WORD_1 src1_sel:DWORD
	v_and_b32_sdwa v77, v56, v132 dst_sel:DWORD dst_unused:UNUSED_PAD src0_sel:WORD_1 src1_sel:DWORD
	v_and_b32_sdwa v78, v59, v132 dst_sel:DWORD dst_unused:UNUSED_PAD src0_sel:WORD_1 src1_sel:DWORD
	v_and_b32_sdwa v79, v58, v132 dst_sel:DWORD dst_unused:UNUSED_PAD src0_sel:WORD_1 src1_sel:DWORD
	v_lshlrev_b32_e32 v39, 16, v73
	v_lshlrev_b32_e32 v38, 16, v72
	v_and_b32_e32 v37, 0xffff0000, v73
	v_and_b32_e32 v36, 0xffff0000, v72
	v_and_b32_sdwa v72, v53, v132 dst_sel:DWORD dst_unused:UNUSED_PAD src0_sel:WORD_1 src1_sel:DWORD
	v_and_b32_sdwa v73, v52, v132 dst_sel:DWORD dst_unused:UNUSED_PAD src0_sel:WORD_1 src1_sel:DWORD
	v_add3_u32 v60, v60, v65, s44
	v_add3_u32 v61, v61, v64, s44
	v_add3_u32 v63, v63, v66, s44
	v_add3_u32 v62, v62, v67, s44
	v_add3_u32 v64, v48, v69, s44
	v_add3_u32 v65, v49, v68, s44
	v_add3_u32 v48, v51, v70, s44
	v_add3_u32 v49, v50, v71, s44
	v_add3_u32 v50, v55, v74, s44
	v_add3_u32 v51, v54, v75, s44
	v_add3_u32 v54, v56, v77, s44
	v_add3_u32 v55, v57, v76, s44
	v_add3_u32 v56, v59, v78, s44
	v_add3_u32 v57, v58, v79, s44
	v_add3_u32 v52, v52, v73, s44
	v_add3_u32 v53, v53, v72, s44
	v_and_b32_e32 v58, 0xffff0000, v63
	v_and_b32_e32 v59, 0xffff0000, v62
	v_and_b32_e32 v62, 0xffff0000, v48
	v_and_b32_e32 v63, 0xffff0000, v49
	v_and_b32_e32 v66, 0xffff0000, v50
	v_and_b32_e32 v67, 0xffff0000, v51
	v_and_b32_e32 v56, 0xffff0000, v56
	v_and_b32_e32 v57, 0xffff0000, v57
	v_or_b32_sdwa v49, v58, v61 dst_sel:DWORD dst_unused:UNUSED_PAD src0_sel:DWORD src1_sel:WORD_1
	v_or_b32_sdwa v48, v59, v60 dst_sel:DWORD dst_unused:UNUSED_PAD src0_sel:DWORD src1_sel:WORD_1
	v_or_b32_sdwa v51, v62, v65 dst_sel:DWORD dst_unused:UNUSED_PAD src0_sel:DWORD src1_sel:WORD_1
	v_or_b32_sdwa v50, v63, v64 dst_sel:DWORD dst_unused:UNUSED_PAD src0_sel:DWORD src1_sel:WORD_1
	v_or_b32_sdwa v53, v66, v53 dst_sel:DWORD dst_unused:UNUSED_PAD src0_sel:DWORD src1_sel:WORD_1
	v_or_b32_sdwa v52, v67, v52 dst_sel:DWORD dst_unused:UNUSED_PAD src0_sel:DWORD src1_sel:WORD_1
	v_or_b32_sdwa v55, v56, v55 dst_sel:DWORD dst_unused:UNUSED_PAD src0_sel:DWORD src1_sel:WORD_1
	v_or_b32_sdwa v54, v57, v54 dst_sel:DWORD dst_unused:UNUSED_PAD src0_sel:DWORD src1_sel:WORD_1
	global_store_dwordx4 v[100:101], v[48:51], off
	global_store_dwordx4 v[102:103], v[52:55], off
	s_barrier
	ds_write2_b32 v119, v0, v16 offset1:32
	ds_write2_b32 v119, v1, v17 offset0:132 offset1:164
	ds_write2_b32 v122, v2, v18 offset0:8 offset1:40
	ds_write2_b32 v122, v3, v19 offset0:140 offset1:172
	ds_write2_b32 v123, v4, v20 offset0:32 offset1:64
	ds_write2_b32 v123, v5, v21 offset0:164 offset1:196
	ds_write2_b32 v124, v6, v22 offset0:40 offset1:72
	ds_write2_b32 v124, v7, v23 offset0:172 offset1:204
	ds_write2_b32 v125, v8, v24 offset0:64 offset1:96
	ds_write2_b32 v125, v9, v25 offset0:196 offset1:228
	ds_write2_b32 v126, v10, v26 offset0:72 offset1:104
	ds_write2_b32 v126, v11, v27 offset0:204 offset1:236
	ds_write2_b32 v127, v12, v28 offset0:96 offset1:128
	ds_write2_b32 v129, v13, v29 offset0:100 offset1:132
	ds_write2_b32 v130, v14, v30 offset0:104 offset1:136
	ds_write2_b32 v131, v15, v31 offset0:108 offset1:140
	s_waitcnt lgkmcnt(0)
	s_barrier
	ds_read_b128 v[8:11], v120 offset:128
	ds_read_b128 v[12:15], v120 offset:144
	ds_read_b128 v[4:7], v121
	ds_read_b128 v[0:3], v121 offset:16
	ds_read_b128 v[16:19], v120
	s_waitcnt lgkmcnt(4)
	v_mul_f32_e32 v48, 0xbfb8aa3b, v8
	v_mul_f32_e32 v50, 0xbfb8aa3b, v10
	s_waitcnt lgkmcnt(3)
	v_mul_f32_e32 v52, 0xbfb8aa3b, v12
	v_mul_f32_e32 v53, 0xbfb8aa3b, v13
	s_waitcnt lgkmcnt(2)
	v_mov_b32_e32 v12, v4
	v_mov_b32_e32 v13, v6
	v_mov_b32_e32 v6, v5
	s_waitcnt lgkmcnt(1)
	v_mov_b32_e32 v4, v0
	v_mov_b32_e32 v5, v2
	v_mov_b32_e32 v2, v1
	v_exp_f32_e32 v0, v48
	v_exp_f32_e32 v1, v50
	ds_read_b128 v[20:23], v120 offset:16
	v_mul_f32_e32 v49, 0xbfb8aa3b, v9
	v_mul_f32_e32 v51, 0xbfb8aa3b, v11
	ds_read_b128 v[24:27], v121 offset:128
	v_mul_f32_e32 v54, 0xbfb8aa3b, v14
	v_mul_f32_e32 v55, 0xbfb8aa3b, v15
	v_exp_f32_e32 v14, v49
	v_exp_f32_e32 v15, v51
	s_waitcnt lgkmcnt(2)
	v_mov_b32_e32 v8, v16
	v_mov_b32_e32 v9, v18
	v_mov_b32_e32 v18, v17
	v_exp_f32_e32 v16, v52
	v_exp_f32_e32 v17, v54
	v_pk_add_f32 v[0:1], v[0:1], 1.0 op_sel_hi:[1,0]
	ds_read_b128 v[28:31], v121 offset:144
	s_waitcnt lgkmcnt(2)
	v_mov_b32_e32 v10, v20
	v_mov_b32_e32 v11, v22
	v_mov_b32_e32 v22, v21
	v_exp_f32_e32 v20, v53
	v_exp_f32_e32 v21, v55
	v_pk_add_f32 v[14:15], v[14:15], 1.0 op_sel_hi:[1,0]
	s_waitcnt lgkmcnt(1)
	v_mul_f32_e32 v24, 0xbfb8aa3b, v24
	v_mul_f32_e32 v25, 0xbfb8aa3b, v25
	v_mul_f32_e32 v56, 0xbfb8aa3b, v26
	v_exp_f32_e32 v24, v24
	v_exp_f32_e32 v26, v25
	v_exp_f32_e32 v25, v56
	v_pk_add_f32 v[16:17], v[16:17], 1.0 op_sel_hi:[1,0]
	v_mul_f32_e32 v27, 0xbfb8aa3b, v27
	v_exp_f32_e32 v27, v27
	v_pk_add_f32 v[20:21], v[20:21], 1.0 op_sel_hi:[1,0]
	s_waitcnt lgkmcnt(0)
	v_mul_f32_e32 v28, 0xbfb8aa3b, v28
	v_mul_f32_e32 v29, 0xbfb8aa3b, v29
	v_mul_f32_e32 v57, 0xbfb8aa3b, v30
	v_exp_f32_e32 v28, v28
	v_exp_f32_e32 v30, v29
	v_exp_f32_e32 v29, v57
	v_pk_add_f32 v[24:25], v[24:25], 1.0 op_sel_hi:[1,0]
	v_mul_f32_e32 v31, 0xbfb8aa3b, v31
	v_exp_f32_e32 v31, v31
	v_pk_add_f32 v[26:27], v[26:27], 1.0 op_sel_hi:[1,0]
	v_pk_add_f32 v[28:29], v[28:29], 1.0 op_sel_hi:[1,0]
	s_mov_b64 vcc, s[30:31]
	v_rcp_f32_e32 v1, v1
	s_nop 0
	s_mov_b64 vcc, s[28:29]
	v_pk_add_f32 v[30:31], v[30:31], 1.0 op_sel_hi:[1,0]
	v_rcp_f32_e32 v0, v0
	s_nop 0
	s_mov_b64 vcc, s[26:27]
	v_pk_mul_f32 v[0:1], v[8:9], v[0:1]
	s_mov_b64 vcc, s[24:25]
	v_rcp_f32_e32 v9, v15
	s_nop 0
	v_rcp_f32_e32 v8, v14
	s_nop 0
	s_mov_b64 vcc, s[22:23]
	v_pk_mul_f32 v[0:1], v[0:1], v[46:47]
	v_pk_mul_f32 v[8:9], v[18:19], v[8:9]
	v_rcp_f32_e32 v15, v17
	s_nop 0
	s_mov_b64 vcc, s[20:21]
	v_and_b32_sdwa v18, v1, v132 dst_sel:DWORD dst_unused:UNUSED_PAD src0_sel:WORD_1 src1_sel:DWORD
	v_and_b32_sdwa v19, v0, v132 dst_sel:DWORD dst_unused:UNUSED_PAD src0_sel:WORD_1 src1_sel:DWORD
	v_pk_mul_f32 v[8:9], v[8:9], v[44:45]
	v_rcp_f32_e32 v14, v16
	s_nop 0
	s_mov_b64 vcc, s[16:17]
	v_add3_u32 v17, v0, v19, s44
	v_add3_u32 v18, v1, v18, s44
	v_and_b32_sdwa v19, v9, v132 dst_sel:DWORD dst_unused:UNUSED_PAD src0_sel:WORD_1 src1_sel:DWORD
	v_pk_mul_f32 v[0:1], v[10:11], v[14:15]
	s_mov_b64 vcc, s[14:15]
	v_and_b32_sdwa v44, v8, v132 dst_sel:DWORD dst_unused:UNUSED_PAD src0_sel:WORD_1 src1_sel:DWORD
	v_rcp_f32_e32 v11, v21
	s_nop 0
	v_add3_u32 v9, v9, v19, s44
	v_rcp_f32_e32 v10, v20
	s_nop 0
	s_mov_b64 vcc, s[12:13]
	v_add3_u32 v8, v8, v44, s44
	v_pk_mul_f32 v[0:1], v[0:1], v[42:43]
	v_and_b32_e32 v9, 0xffff0000, v9
	v_pk_mul_f32 v[10:11], v[22:23], v[10:11]
	v_rcp_f32_e32 v15, v25
	s_nop 0
	s_mov_b64 vcc, s[10:11]
	v_and_b32_e32 v8, 0xffff0000, v8
	v_and_b32_sdwa v16, v1, v132 dst_sel:DWORD dst_unused:UNUSED_PAD src0_sel:WORD_1 src1_sel:DWORD
	v_and_b32_sdwa v19, v0, v132 dst_sel:DWORD dst_unused:UNUSED_PAD src0_sel:WORD_1 src1_sel:DWORD
	v_or_b32_sdwa v9, v9, v18 dst_sel:DWORD dst_unused:UNUSED_PAD src0_sel:DWORD src1_sel:WORD_1
	v_pk_mul_f32 v[10:11], v[10:11], v[40:41]
	v_rcp_f32_e32 v14, v24
	s_nop 0
	s_mov_b64 vcc, s[8:9]
	v_or_b32_sdwa v8, v8, v17 dst_sel:DWORD dst_unused:UNUSED_PAD src0_sel:DWORD src1_sel:WORD_1
	v_add3_u32 v17, v0, v19, s44
	v_add3_u32 v16, v1, v16, s44
	v_and_b32_sdwa v19, v11, v132 dst_sel:DWORD dst_unused:UNUSED_PAD src0_sel:WORD_1 src1_sel:DWORD
	v_pk_mul_f32 v[0:1], v[12:13], v[14:15]
	s_mov_b64 vcc, s[6:7]
	v_and_b32_sdwa v20, v10, v132 dst_sel:DWORD dst_unused:UNUSED_PAD src0_sel:WORD_1 src1_sel:DWORD
	v_rcp_f32_e32 v13, v27
	s_nop 0
	v_add3_u32 v11, v11, v19, s44
	v_pk_mul_f32 v[0:1], v[0:1], v[38:39]
	v_rcp_f32_e32 v12, v26
	s_nop 0
	s_mov_b64 vcc, s[4:5]
	v_add3_u32 v10, v10, v20, s44
	v_and_b32_e32 v11, 0xffff0000, v11
	v_pk_mul_f32 v[6:7], v[6:7], v[12:13]
	v_and_b32_sdwa v12, v1, v132 dst_sel:DWORD dst_unused:UNUSED_PAD src0_sel:WORD_1 src1_sel:DWORD
	v_rcp_f32_e32 v13, v29
	s_nop 0
	s_mov_b64 vcc, s[34:35]
	v_and_b32_e32 v10, 0xffff0000, v10
	v_and_b32_sdwa v15, v0, v132 dst_sel:DWORD dst_unused:UNUSED_PAD src0_sel:WORD_1 src1_sel:DWORD
	v_or_b32_sdwa v11, v11, v16 dst_sel:DWORD dst_unused:UNUSED_PAD src0_sel:DWORD src1_sel:WORD_1
	v_add3_u32 v16, v1, v12, s44
	v_rcp_f32_e32 v12, v28
	s_nop 0
	s_mov_b64 vcc, s[0:1]
	v_or_b32_sdwa v10, v10, v17 dst_sel:DWORD dst_unused:UNUSED_PAD src0_sel:DWORD src1_sel:WORD_1
	v_pk_mul_f32 v[6:7], v[6:7], v[36:37]
	v_add3_u32 v15, v0, v15, s44
	v_pk_mul_f32 v[0:1], v[4:5], v[12:13]
	global_store_dwordx4 v[98:99], v[8:11], off
	v_rcp_f32_e32 v5, v31
	s_nop 0
	v_rcp_f32_e32 v4, v30
	s_nop 0
	v_and_b32_sdwa v8, v7, v132 dst_sel:DWORD dst_unused:UNUSED_PAD src0_sel:WORD_1 src1_sel:DWORD
	v_and_b32_sdwa v9, v6, v132 dst_sel:DWORD dst_unused:UNUSED_PAD src0_sel:WORD_1 src1_sel:DWORD
	v_add3_u32 v8, v7, v8, s44
	v_add3_u32 v9, v6, v9, s44
	v_pk_mul_f32 v[6:7], v[0:1], v[34:35]
	v_pk_mul_f32 v[2:3], v[2:3], v[4:5]
	v_and_b32_sdwa v4, v7, v132 dst_sel:DWORD dst_unused:UNUSED_PAD src0_sel:WORD_1 src1_sel:DWORD
	v_and_b32_sdwa v5, v6, v132 dst_sel:DWORD dst_unused:UNUSED_PAD src0_sel:WORD_1 src1_sel:DWORD
	v_pk_mul_f32 v[2:3], v[2:3], v[32:33]
	v_add3_u32 v5, v6, v5, s44
	v_add3_u32 v4, v7, v4, s44
	v_and_b32_sdwa v6, v3, v132 dst_sel:DWORD dst_unused:UNUSED_PAD src0_sel:WORD_1 src1_sel:DWORD
	v_and_b32_sdwa v7, v2, v132 dst_sel:DWORD dst_unused:UNUSED_PAD src0_sel:WORD_1 src1_sel:DWORD
	v_add3_u32 v3, v3, v6, s44
	v_add3_u32 v2, v2, v7, s44
	v_and_b32_e32 v0, 0xffff0000, v8
	v_and_b32_e32 v8, 0xffff0000, v9
	v_and_b32_e32 v3, 0xffff0000, v3
	v_and_b32_e32 v2, 0xffff0000, v2
	v_or_b32_sdwa v1, v0, v16 dst_sel:DWORD dst_unused:UNUSED_PAD src0_sel:DWORD src1_sel:WORD_1
	v_or_b32_sdwa v0, v8, v15 dst_sel:DWORD dst_unused:UNUSED_PAD src0_sel:DWORD src1_sel:WORD_1
	v_or_b32_sdwa v3, v3, v4 dst_sel:DWORD dst_unused:UNUSED_PAD src0_sel:DWORD src1_sel:WORD_1
	v_or_b32_sdwa v2, v2, v5 dst_sel:DWORD dst_unused:UNUSED_PAD src0_sel:DWORD src1_sel:WORD_1
	global_store_dwordx4 v[96:97], v[0:3], off
	s_barrier
	s_cbranch_scc1 .LBB0_864

.LBB0_923:
	s_lshr_b32 s0, s2, 1
	s_mul_i32 s0, s0, s92
	s_add_i32 s0, s0, s94
	s_lshl_b32 s1, s0, 7
	s_lshl_b32 s0, s0, 1
	s_and_b32 s9, s2, 1
	s_and_b32 s20, s1, 0x1f80
	s_and_b32 s8, s0, 0xffffff80
	s_bitcmp1_b32 s2, 0
	s_cselect_b64 s[6:7], -1, 0
	s_cmp_eq_u32 s9, 0
	s_cselect_b64 s[0:1], -1, 0
	s_and_b64 s[22:23], s[0:1], exec
	s_cselect_b32 s9, s11, 0x1000000
	s_cselect_b32 s24, s12, 0x2a80000
	s_cselect_b32 s21, s13, 0xbf80000
	s_add_u32 s9, s88, s9
	s_addc_u32 s23, s89, 0
	s_lshl_b32 s22, s20, 11
	s_add_u32 s22, s9, s22
	s_addc_u32 s23, s23, 0
	s_mov_b64 s[56:57], s[22:23]
	s_add_u32 s26, s88, s24
	s_addc_u32 s27, s89, 0
	s_ashr_i32 s9, s8, 31
	s_lshl_b64 s[24:25], s[8:9], 11
	s_add_u32 s24, s26, s24
	s_addc_u32 s25, s27, s25
	s_mov_b64 s[58:59], s[24:25]
	s_add_u32 s21, s88, s21
	s_addc_u32 s23, s89, 0
	s_lshl_b64 s[8:9], s[8:9], 1
	s_add_u32 s22, s21, s8
	s_addc_u32 s23, s23, s9
	v_lshl_add_u64 v[136:137], v[94:95], 0, s[8:9]
	s_mov_b64 s[8:9], -1
	s_and_b64 vcc, s[0:1], exec
	v_readfirstlane_b32 s61, v168
	v_lshrrev_b32_e32 v64, 3, v168
	v_bfe_u32 v65, v168, 4, 3
	v_and_b32_e32 v66, 7, v168
	v_xor_b32_e32 v65, v65, v66
	v_lshlrev_b32_e32 v65, 4, v65
	s_lshr_b32 s61, s61, 6
	s_lshl_b32 s61, s61, 10
	s_movk_i32 s60, 0x800
	v_mul_lo_u32 v64, v64, s60
	v_add_u32_e32 v64, v64, v65
	v_add_u32_e32 v65, 0x10000, v64
	v_add_u32_e32 v66, 0x20000, v64
	v_add_u32_e32 v67, 0x30000, v64
	v_mov_b32_e32 v0, 0
	v_mov_b32_e32 v1, v0
	v_mov_b32_e32 v2, v0
	v_mov_b32_e32 v3, v0
	v_mov_b32_e32 v4, v0
	v_mov_b32_e32 v5, v0
	v_mov_b32_e32 v6, v0
	v_mov_b32_e32 v7, v0
	v_mov_b32_e32 v8, v0
	v_mov_b32_e32 v9, v0
	v_mov_b32_e32 v10, v0
	v_mov_b32_e32 v11, v0
	v_mov_b32_e32 v12, v0
	v_mov_b32_e32 v13, v0
	v_mov_b32_e32 v14, v0
	v_mov_b32_e32 v15, v0
	v_mov_b32_e32 v16, v0
	v_mov_b32_e32 v17, v0
	v_mov_b32_e32 v18, v0
	v_mov_b32_e32 v19, v0
	v_mov_b32_e32 v20, v0
	v_mov_b32_e32 v21, v0
	v_mov_b32_e32 v22, v0
	v_mov_b32_e32 v23, v0
	v_mov_b32_e32 v24, v0
	v_mov_b32_e32 v25, v0
	v_mov_b32_e32 v26, v0
	v_mov_b32_e32 v27, v0
	v_mov_b32_e32 v28, v0
	v_mov_b32_e32 v29, v0
	v_mov_b32_e32 v30, v0
	v_mov_b32_e32 v31, v0
	v_mov_b32_e32 v32, v0
	v_mov_b32_e32 v33, v0
	v_mov_b32_e32 v34, v0
	v_mov_b32_e32 v35, v0
	v_mov_b32_e32 v36, v0
	v_mov_b32_e32 v37, v0
	v_mov_b32_e32 v38, v0
	v_mov_b32_e32 v39, v0
	v_mov_b32_e32 v40, v0
	v_mov_b32_e32 v41, v0
	v_mov_b32_e32 v42, v0
	v_mov_b32_e32 v43, v0
	v_mov_b32_e32 v44, v0
	v_mov_b32_e32 v45, v0
	v_mov_b32_e32 v46, v0
	v_mov_b32_e32 v47, v0
	v_mov_b32_e32 v48, v0
	v_mov_b32_e32 v49, v0
	v_mov_b32_e32 v50, v0
	v_mov_b32_e32 v51, v0
	v_mov_b32_e32 v52, v0
	v_mov_b32_e32 v53, v0
	v_mov_b32_e32 v54, v0
	v_mov_b32_e32 v55, v0
	v_mov_b32_e32 v56, v0
	v_mov_b32_e32 v57, v0
	v_mov_b32_e32 v58, v0
	v_mov_b32_e32 v59, v0
	v_mov_b32_e32 v60, v0
	v_mov_b32_e32 v61, v0
	v_mov_b32_e32 v62, v0
	v_mov_b32_e32 v63, v0
	s_add_u32 m0, s61, 0x0
	s_nop 0
	global_load_lds_dwordx4 v64, s[56:57]
	s_add_u32 m0, s61, 0x1000
	s_nop 0
	global_load_lds_dwordx4 v65, s[56:57]
	s_add_u32 m0, s61, 0x2000
	s_nop 0
	global_load_lds_dwordx4 v66, s[56:57]
	s_add_u32 m0, s61, 0x3000
	s_nop 0
	global_load_lds_dwordx4 v67, s[56:57]
	s_add_u32 m0, s61, 0x8000
	s_nop 0
	global_load_lds_dwordx4 v64, s[58:59]
	s_add_u32 m0, s61, 0x9000
	s_nop 0
	global_load_lds_dwordx4 v65, s[58:59]
	s_add_u32 m0, s61, 0xa000
	s_nop 0
	global_load_lds_dwordx4 v66, s[58:59]
	s_add_u32 m0, s61, 0xb000
	s_nop 0
	global_load_lds_dwordx4 v67, s[58:59]
	s_add_u32 s56, s56, 0x80
	s_addc_u32 s57, s57, 0
	s_add_u32 s58, s58, 0x80
	s_addc_u32 s59, s59, 0
	s_add_u32 m0, s61, 0x4000
	s_nop 0
	global_load_lds_dwordx4 v64, s[56:57]
	s_add_u32 m0, s61, 0x5000
	s_nop 0
	global_load_lds_dwordx4 v65, s[56:57]
	s_add_u32 m0, s61, 0x6000
	s_nop 0
	global_load_lds_dwordx4 v66, s[56:57]
	s_add_u32 m0, s61, 0x7000
	s_nop 0
	global_load_lds_dwordx4 v67, s[56:57]
	s_add_u32 m0, s61, 0xc000
	s_nop 0
	global_load_lds_dwordx4 v64, s[58:59]
	s_add_u32 m0, s61, 0xd000
	s_nop 0
	global_load_lds_dwordx4 v65, s[58:59]
	s_add_u32 m0, s61, 0xe000
	s_nop 0
	global_load_lds_dwordx4 v66, s[58:59]
	s_add_u32 m0, s61, 0xf000
	s_nop 0
	global_load_lds_dwordx4 v67, s[58:59]
	s_add_u32 s56, s56, 0x80
	s_addc_u32 s57, s57, 0
	s_add_u32 s58, s58, 0x80
	s_addc_u32 s59, s59, 0
	s_waitcnt vmcnt(8)
	s_barrier
	ds_read_b128 v[186:189], v142 offset:0
	ds_read_b128 v[190:193], v142 offset:4096
	ds_read_b128 v[194:197], v143 offset:32768
	ds_read_b128 v[198:201], v143 offset:36864
	ds_read_b128 v[202:205], v144 offset:0
	ds_read_b128 v[206:209], v144 offset:4096
	ds_read_b128 v[210:213], v145 offset:32768
	ds_read_b128 v[214:217], v145 offset:36864
	ds_read_b128 v[218:221], v146 offset:0
	ds_read_b128 v[222:225], v146 offset:4096
	ds_read_b128 v[226:229], v147 offset:32768
	ds_read_b128 v[230:233], v147 offset:36864
	s_mov_b32 s60, 0
.Lgm_loop_gemmF2:
	ds_read_b128 v[234:237], v148 offset:0
	ds_read_b128 v[238:241], v148 offset:4096
	ds_read_b128 v[242:245], v149 offset:32768
	ds_read_b128 v[246:249], v149 offset:36864
	s_waitcnt lgkmcnt(12)
	v_mfma_f32_32x32x16_bf16 v[32:47], v[186:189], v[194:197], v[32:47]
	v_mfma_f32_32x32x16_bf16 v[48:63], v[186:189], v[198:201], v[48:63]
	v_mfma_f32_32x32x16_bf16 v[0:15], v[190:193], v[194:197], v[0:15]
	v_mfma_f32_32x32x16_bf16 v[16:31], v[190:193], v[198:201], v[16:31]
	s_waitcnt vmcnt(0) lgkmcnt(0)
	s_barrier
	s_cmp_lt_u32 s60, 14
	s_cbranch_scc0 .Lgm_nodma0_gemmF2
	s_add_u32 m0, s61, 0x0
	s_nop 0
	global_load_lds_dwordx4 v64, s[56:57]
	s_add_u32 m0, s61, 0x1000
	s_nop 0
	global_load_lds_dwordx4 v65, s[56:57]
	s_add_u32 m0, s61, 0x2000
	s_nop 0
	global_load_lds_dwordx4 v66, s[56:57]
	s_add_u32 m0, s61, 0x3000
	s_nop 0
	global_load_lds_dwordx4 v67, s[56:57]
	s_add_u32 m0, s61, 0x8000
	s_nop 0
	global_load_lds_dwordx4 v64, s[58:59]
	s_add_u32 m0, s61, 0x9000
	s_nop 0
	global_load_lds_dwordx4 v65, s[58:59]
	s_add_u32 m0, s61, 0xa000
	s_nop 0
	global_load_lds_dwordx4 v66, s[58:59]
	s_add_u32 m0, s61, 0xb000
	s_nop 0
	global_load_lds_dwordx4 v67, s[58:59]
	s_add_u32 s56, s56, 0x80
	s_addc_u32 s57, s57, 0
	s_add_u32 s58, s58, 0x80
	s_addc_u32 s59, s59, 0
	ds_read_b128 v[186:189], v142 offset:16384
	ds_read_b128 v[190:193], v142 offset:20480
	ds_read_b128 v[194:197], v143 offset:49152
	ds_read_b128 v[198:201], v143 offset:53248
	v_mfma_f32_32x32x16_bf16 v[32:47], v[202:205], v[210:213], v[32:47]
	v_mfma_f32_32x32x16_bf16 v[48:63], v[202:205], v[214:217], v[48:63]
	v_mfma_f32_32x32x16_bf16 v[0:15], v[206:209], v[210:213], v[0:15]
	v_mfma_f32_32x32x16_bf16 v[16:31], v[206:209], v[214:217], v[16:31]
	ds_read_b128 v[202:205], v144 offset:16384
	ds_read_b128 v[206:209], v144 offset:20480
	ds_read_b128 v[210:213], v145 offset:49152
	ds_read_b128 v[214:217], v145 offset:53248
	v_mfma_f32_32x32x16_bf16 v[32:47], v[218:221], v[226:229], v[32:47]
	v_mfma_f32_32x32x16_bf16 v[48:63], v[218:221], v[230:233], v[48:63]
	v_mfma_f32_32x32x16_bf16 v[0:15], v[222:225], v[226:229], v[0:15]
	v_mfma_f32_32x32x16_bf16 v[16:31], v[222:225], v[230:233], v[16:31]
	ds_read_b128 v[218:221], v146 offset:16384
	ds_read_b128 v[222:225], v146 offset:20480
	ds_read_b128 v[226:229], v147 offset:49152
	ds_read_b128 v[230:233], v147 offset:53248
	v_mfma_f32_32x32x16_bf16 v[32:47], v[234:237], v[242:245], v[32:47]
	v_mfma_f32_32x32x16_bf16 v[48:63], v[234:237], v[246:249], v[48:63]
	v_mfma_f32_32x32x16_bf16 v[0:15], v[238:241], v[242:245], v[0:15]
	v_mfma_f32_32x32x16_bf16 v[16:31], v[238:241], v[246:249], v[16:31]
	s_branch .Lgm_join0_gemmF2
.Lgm_nodma0_gemmF2:
	ds_read_b128 v[186:189], v142 offset:16384
	ds_read_b128 v[190:193], v142 offset:20480
	ds_read_b128 v[194:197], v143 offset:49152
	ds_read_b128 v[198:201], v143 offset:53248
	v_mfma_f32_32x32x16_bf16 v[32:47], v[202:205], v[210:213], v[32:47]
	v_mfma_f32_32x32x16_bf16 v[48:63], v[202:205], v[214:217], v[48:63]
	v_mfma_f32_32x32x16_bf16 v[0:15], v[206:209], v[210:213], v[0:15]
	v_mfma_f32_32x32x16_bf16 v[16:31], v[206:209], v[214:217], v[16:31]
	ds_read_b128 v[202:205], v144 offset:16384
	ds_read_b128 v[206:209], v144 offset:20480
	ds_read_b128 v[210:213], v145 offset:49152
	ds_read_b128 v[214:217], v145 offset:53248
	v_mfma_f32_32x32x16_bf16 v[32:47], v[218:221], v[226:229], v[32:47]
	v_mfma_f32_32x32x16_bf16 v[48:63], v[218:221], v[230:233], v[48:63]
	v_mfma_f32_32x32x16_bf16 v[0:15], v[222:225], v[226:229], v[0:15]
	v_mfma_f32_32x32x16_bf16 v[16:31], v[222:225], v[230:233], v[16:31]
	ds_read_b128 v[218:221], v146 offset:16384
	ds_read_b128 v[222:225], v146 offset:20480
	ds_read_b128 v[226:229], v147 offset:49152
	ds_read_b128 v[230:233], v147 offset:53248
	v_mfma_f32_32x32x16_bf16 v[32:47], v[234:237], v[242:245], v[32:47]
	v_mfma_f32_32x32x16_bf16 v[48:63], v[234:237], v[246:249], v[48:63]
	v_mfma_f32_32x32x16_bf16 v[0:15], v[238:241], v[242:245], v[0:15]
	v_mfma_f32_32x32x16_bf16 v[16:31], v[238:241], v[246:249], v[16:31]
.Lgm_join0_gemmF2:
	ds_read_b128 v[234:237], v148 offset:16384
	ds_read_b128 v[238:241], v148 offset:20480
	ds_read_b128 v[242:245], v149 offset:49152
	ds_read_b128 v[246:249], v149 offset:53248
	s_waitcnt lgkmcnt(12)
	v_mfma_f32_32x32x16_bf16 v[32:47], v[186:189], v[194:197], v[32:47]
	v_mfma_f32_32x32x16_bf16 v[48:63], v[186:189], v[198:201], v[48:63]
	v_mfma_f32_32x32x16_bf16 v[0:15], v[190:193], v[194:197], v[0:15]
	v_mfma_f32_32x32x16_bf16 v[16:31], v[190:193], v[198:201], v[16:31]
	s_waitcnt vmcnt(0) lgkmcnt(0)
	s_barrier
	s_cmp_lt_u32 s60, 14
	s_cbranch_scc0 .Lgm_nodma1_gemmF2
	s_add_u32 m0, s61, 0x4000
	s_nop 0
	global_load_lds_dwordx4 v64, s[56:57]
	s_add_u32 m0, s61, 0x5000
	s_nop 0
	global_load_lds_dwordx4 v65, s[56:57]
	s_add_u32 m0, s61, 0x6000
	s_nop 0
	global_load_lds_dwordx4 v66, s[56:57]
	s_add_u32 m0, s61, 0x7000
	s_nop 0
	global_load_lds_dwordx4 v67, s[56:57]
	s_add_u32 m0, s61, 0xc000
	s_nop 0
	global_load_lds_dwordx4 v64, s[58:59]
	s_add_u32 m0, s61, 0xd000
	s_nop 0
	global_load_lds_dwordx4 v65, s[58:59]
	s_add_u32 m0, s61, 0xe000
	s_nop 0
	global_load_lds_dwordx4 v66, s[58:59]
	s_add_u32 m0, s61, 0xf000
	s_nop 0
	global_load_lds_dwordx4 v67, s[58:59]
	s_add_u32 s56, s56, 0x80
	s_addc_u32 s57, s57, 0
	s_add_u32 s58, s58, 0x80
	s_addc_u32 s59, s59, 0
	ds_read_b128 v[186:189], v142 offset:0
	ds_read_b128 v[190:193], v142 offset:4096
	ds_read_b128 v[194:197], v143 offset:32768
	ds_read_b128 v[198:201], v143 offset:36864
	v_mfma_f32_32x32x16_bf16 v[32:47], v[202:205], v[210:213], v[32:47]
	v_mfma_f32_32x32x16_bf16 v[48:63], v[202:205], v[214:217], v[48:63]
	v_mfma_f32_32x32x16_bf16 v[0:15], v[206:209], v[210:213], v[0:15]
	v_mfma_f32_32x32x16_bf16 v[16:31], v[206:209], v[214:217], v[16:31]
	ds_read_b128 v[202:205], v144 offset:0
	ds_read_b128 v[206:209], v144 offset:4096
	ds_read_b128 v[210:213], v145 offset:32768
	ds_read_b128 v[214:217], v145 offset:36864
	v_mfma_f32_32x32x16_bf16 v[32:47], v[218:221], v[226:229], v[32:47]
	v_mfma_f32_32x32x16_bf16 v[48:63], v[218:221], v[230:233], v[48:63]
	v_mfma_f32_32x32x16_bf16 v[0:15], v[222:225], v[226:229], v[0:15]
	v_mfma_f32_32x32x16_bf16 v[16:31], v[222:225], v[230:233], v[16:31]
	ds_read_b128 v[218:221], v146 offset:0
	ds_read_b128 v[222:225], v146 offset:4096
	ds_read_b128 v[226:229], v147 offset:32768
	ds_read_b128 v[230:233], v147 offset:36864
	v_mfma_f32_32x32x16_bf16 v[32:47], v[234:237], v[242:245], v[32:47]
	v_mfma_f32_32x32x16_bf16 v[48:63], v[234:237], v[246:249], v[48:63]
	v_mfma_f32_32x32x16_bf16 v[0:15], v[238:241], v[242:245], v[0:15]
	v_mfma_f32_32x32x16_bf16 v[16:31], v[238:241], v[246:249], v[16:31]
	s_branch .Lgm_join1_gemmF2
.Lgm_nodma1_gemmF2:
	ds_read_b128 v[186:189], v142 offset:0
	ds_read_b128 v[190:193], v142 offset:4096
	ds_read_b128 v[194:197], v143 offset:32768
	ds_read_b128 v[198:201], v143 offset:36864
	v_mfma_f32_32x32x16_bf16 v[32:47], v[202:205], v[210:213], v[32:47]
	v_mfma_f32_32x32x16_bf16 v[48:63], v[202:205], v[214:217], v[48:63]
	v_mfma_f32_32x32x16_bf16 v[0:15], v[206:209], v[210:213], v[0:15]
	v_mfma_f32_32x32x16_bf16 v[16:31], v[206:209], v[214:217], v[16:31]
	ds_read_b128 v[202:205], v144 offset:0
	ds_read_b128 v[206:209], v144 offset:4096
	ds_read_b128 v[210:213], v145 offset:32768
	ds_read_b128 v[214:217], v145 offset:36864
	v_mfma_f32_32x32x16_bf16 v[32:47], v[218:221], v[226:229], v[32:47]
	v_mfma_f32_32x32x16_bf16 v[48:63], v[218:221], v[230:233], v[48:63]
	v_mfma_f32_32x32x16_bf16 v[0:15], v[222:225], v[226:229], v[0:15]
	v_mfma_f32_32x32x16_bf16 v[16:31], v[222:225], v[230:233], v[16:31]
	ds_read_b128 v[218:221], v146 offset:0
	ds_read_b128 v[222:225], v146 offset:4096
	ds_read_b128 v[226:229], v147 offset:32768
	ds_read_b128 v[230:233], v147 offset:36864
	v_mfma_f32_32x32x16_bf16 v[32:47], v[234:237], v[242:245], v[32:47]
	v_mfma_f32_32x32x16_bf16 v[48:63], v[234:237], v[246:249], v[48:63]
	v_mfma_f32_32x32x16_bf16 v[0:15], v[238:241], v[242:245], v[0:15]
	v_mfma_f32_32x32x16_bf16 v[16:31], v[238:241], v[246:249], v[16:31]
.Lgm_join1_gemmF2:
	s_add_u32 s60, s60, 2
	s_cmp_lt_u32 s60, 16
	s_cbranch_scc1 .Lgm_loop_gemmF2
	s_waitcnt lgkmcnt(0)
	s_barrier
	s_nop 7
	v_or_b32_e32 v190, s20, v138
	v_lshlrev_b32_e32 v92, 12, v190
	v_add_u32_e32 v189, s20, v139
	v_add_u32_e32 v188, s20, v140
	v_add_u32_e32 v187, s20, v141
	s_or_b32 s20, s20, 32
	v_or_b32_e32 v186, s20, v138
	v_add_u32_e32 v167, s20, v139
	v_add_u32_e32 v166, s20, v140
	v_add_u32_e32 v165, s20, v141
	v_lshl_add_u64 v[64:65], s[22:23], 0, v[100:101]
	v_lshl_add_u64 v[66:67], v[64:65], 0, v[92:93]
	v_lshlrev_b32_e32 v92, 12, v189
	global_load_dwordx4 v[208:211], v[66:67], off nt
	v_lshl_add_u64 v[66:67], v[64:65], 0, v[92:93]
	v_lshlrev_b32_e32 v92, 12, v188
	global_load_dwordx4 v[88:91], v[66:67], off nt
	v_lshl_add_u64 v[66:67], v[64:65], 0, v[92:93]
	v_lshlrev_b32_e32 v92, 12, v187
	global_load_dwordx4 v[84:87], v[66:67], off nt
	v_lshl_add_u64 v[66:67], v[64:65], 0, v[92:93]
	v_lshlrev_b32_e32 v92, 12, v186
	global_load_dwordx4 v[80:83], v[66:67], off nt
	v_lshl_add_u64 v[66:67], v[64:65], 0, v[92:93]
	v_lshlrev_b32_e32 v92, 12, v167
	global_load_dwordx4 v[76:79], v[66:67], off nt
	v_lshl_add_u64 v[66:67], v[64:65], 0, v[92:93]
	v_lshlrev_b32_e32 v92, 12, v166
	global_load_dwordx4 v[72:75], v[66:67], off nt
	v_lshl_add_u64 v[66:67], v[64:65], 0, v[92:93]
	v_lshlrev_b32_e32 v92, 12, v165
	v_lshl_add_u64 v[64:65], v[64:65], 0, v[92:93]
	global_load_dwordx4 v[68:71], v[66:67], off nt
	global_load_dwordx4 v[64:67], v[64:65], off nt
	ds_write2_b32 v150, v32, v48 offset1:32
	ds_write2_b32 v150, v33, v49 offset0:132 offset1:164
	ds_write2_b32 v152, v34, v50 offset0:8 offset1:40
	ds_write2_b32 v152, v35, v51 offset0:140 offset1:172
	ds_write2_b32 v153, v36, v52 offset0:32 offset1:64
	ds_write2_b32 v153, v37, v53 offset0:164 offset1:196
	ds_write2_b32 v154, v38, v54 offset0:40 offset1:72
	ds_write2_b32 v154, v39, v55 offset0:172 offset1:204
	ds_write2_b32 v155, v40, v56 offset0:64 offset1:96
	ds_write2_b32 v155, v41, v57 offset0:196 offset1:228
	ds_write2_b32 v156, v42, v58 offset0:72 offset1:104
	ds_write2_b32 v156, v43, v59 offset0:204 offset1:236
	ds_write2_b32 v157, v44, v60 offset0:96 offset1:128
	ds_write2_b32 v158, v45, v61 offset0:100 offset1:132
	ds_write2_b32 v159, v46, v62 offset0:104 offset1:136
	ds_write2_b32 v160, v47, v63 offset0:108 offset1:140
	s_waitcnt lgkmcnt(0)
	s_barrier
	ds_read_b128 v[32:35], v151
	ds_read_b128 v[40:43], v151 offset:16
	s_waitcnt lgkmcnt(1)
	v_mov_b32_e32 v48, v32
	v_mov_b32_e32 v49, v34
	v_mov_b32_e32 v34, v33
	s_waitcnt lgkmcnt(0)
	v_mov_b32_e32 v32, v40
	v_mov_b32_e32 v33, v42
	v_mov_b32_e32 v42, v41
	s_waitcnt vmcnt(7)
	v_lshlrev_b32_e32 v37, 16, v209
	v_lshlrev_b32_e32 v36, 16, v208
	v_and_b32_e32 v39, 0xffff0000, v209
	v_and_b32_e32 v38, 0xffff0000, v208
	v_lshlrev_b32_e32 v45, 16, v211
	v_lshlrev_b32_e32 v44, 16, v210
	v_and_b32_e32 v47, 0xffff0000, v211
	v_and_b32_e32 v46, 0xffff0000, v210
	v_pk_mul_f32 v[36:37], v[48:49], v[36:37]
	v_pk_mul_f32 v[38:39], v[34:35], v[38:39]
	v_pk_mul_f32 v[32:33], v[32:33], v[44:45]
	v_pk_mul_f32 v[34:35], v[42:43], v[46:47]
	s_cbranch_vccnz .LBB0_925
	v_lshlrev_b32_e32 v40, 11, v190
	v_lshlrev_b32_e32 v92, 1, v40
	v_lshlrev_b32_e32 v41, 16, v117
	v_lshlrev_b32_e32 v40, 16, v116
	v_and_b32_e32 v43, 0xffff0000, v117
	v_and_b32_e32 v42, 0xffff0000, v116
	v_pk_add_f32 v[40:41], v[36:37], v[40:41]
	v_pk_add_f32 v[42:43], v[38:39], v[42:43]
	v_and_b32_sdwa v46, v41, v161 dst_sel:DWORD dst_unused:UNUSED_PAD src0_sel:WORD_1 src1_sel:DWORD
	v_and_b32_sdwa v47, v40, v161 dst_sel:DWORD dst_unused:UNUSED_PAD src0_sel:WORD_1 src1_sel:DWORD
	v_add3_u32 v40, v40, v47, s17
	v_add3_u32 v41, v41, v46, s17
	v_and_b32_sdwa v46, v43, v161 dst_sel:DWORD dst_unused:UNUSED_PAD src0_sel:WORD_1 src1_sel:DWORD
	v_and_b32_sdwa v47, v42, v161 dst_sel:DWORD dst_unused:UNUSED_PAD src0_sel:WORD_1 src1_sel:DWORD
	v_add3_u32 v43, v43, v46, s17
	v_add3_u32 v42, v42, v47, s17
	v_and_b32_e32 v43, 0xffff0000, v43
	v_and_b32_e32 v42, 0xffff0000, v42
	v_or_b32_sdwa v41, v43, v41 dst_sel:DWORD dst_unused:UNUSED_PAD src0_sel:DWORD src1_sel:WORD_1
	v_or_b32_sdwa v40, v42, v40 dst_sel:DWORD dst_unused:UNUSED_PAD src0_sel:DWORD src1_sel:WORD_1
	v_lshlrev_b32_e32 v43, 16, v135
	v_lshlrev_b32_e32 v42, 16, v134
	v_and_b32_e32 v47, 0xffff0000, v135
	v_and_b32_e32 v46, 0xffff0000, v134
	v_pk_add_f32 v[42:43], v[32:33], v[42:43]
	v_pk_add_f32 v[46:47], v[34:35], v[46:47]
	v_and_b32_sdwa v48, v43, v161 dst_sel:DWORD dst_unused:UNUSED_PAD src0_sel:WORD_1 src1_sel:DWORD
	v_and_b32_sdwa v49, v42, v161 dst_sel:DWORD dst_unused:UNUSED_PAD src0_sel:WORD_1 src1_sel:DWORD
	v_add3_u32 v42, v42, v49, s17
	v_add3_u32 v43, v43, v48, s17
	v_and_b32_sdwa v48, v47, v161 dst_sel:DWORD dst_unused:UNUSED_PAD src0_sel:WORD_1 src1_sel:DWORD
	v_and_b32_sdwa v49, v46, v161 dst_sel:DWORD dst_unused:UNUSED_PAD src0_sel:WORD_1 src1_sel:DWORD
	v_add3_u32 v47, v47, v48, s17
	v_add3_u32 v46, v46, v49, s17
	v_and_b32_e32 v47, 0xffff0000, v47
	v_and_b32_e32 v46, 0xffff0000, v46
	v_lshl_add_u64 v[44:45], v[136:137], 0, v[92:93]
	v_or_b32_sdwa v43, v47, v43 dst_sel:DWORD dst_unused:UNUSED_PAD src0_sel:DWORD src1_sel:WORD_1
	v_or_b32_sdwa v42, v46, v42 dst_sel:DWORD dst_unused:UNUSED_PAD src0_sel:DWORD src1_sel:WORD_1
	s_mov_b64 s[8:9], 0
	global_store_dwordx4 v[44:45], v[40:43], off

.Lgm_loop_G:
	ds_read_b128 v[112:115], v197 offset:0
	ds_read_b128 v[116:119], v197 offset:4096
	ds_read_b128 v[120:123], v201 offset:32768
	ds_read_b128 v[124:127], v201 offset:36864
	s_waitcnt lgkmcnt(12)
	v_mfma_f32_32x32x16_bf16 v[48:63], v[64:67], v[72:75], v[48:63]
	v_mfma_f32_32x32x16_bf16 v[32:47], v[64:67], v[76:79], v[32:47]
	v_mfma_f32_32x32x16_bf16 v[16:31], v[68:71], v[72:75], v[16:31]
	v_mfma_f32_32x32x16_bf16 v[0:15], v[68:71], v[76:79], v[0:15]
	s_waitcnt vmcnt(0) lgkmcnt(0)
	s_barrier
	s_cmp_lt_u32 s6, 30
	s_cbranch_scc0 .Lgm_nodma0_G
	s_add_u32 m0, s25, 0x0
	s_nop 0
	global_load_lds_dwordx4 v190, s[16:17]
	s_add_u32 m0, s25, 0x1000
	s_nop 0
	global_load_lds_dwordx4 v191, s[16:17]
	s_add_u32 m0, s25, 0x2000
	s_nop 0
	global_load_lds_dwordx4 v192, s[16:17]
	s_add_u32 m0, s25, 0x3000
	s_nop 0
	global_load_lds_dwordx4 v193, s[16:17]
	s_add_u32 m0, s25, 0x8000
	s_nop 0
	global_load_lds_dwordx4 v190, s[20:21]
	s_add_u32 m0, s25, 0x9000
	s_nop 0
	global_load_lds_dwordx4 v191, s[20:21]
	s_add_u32 m0, s25, 0xa000
	s_nop 0
	global_load_lds_dwordx4 v192, s[20:21]
	s_add_u32 m0, s25, 0xb000
	s_nop 0
	global_load_lds_dwordx4 v193, s[20:21]
	s_add_u32 s16, s16, 0x80
	s_addc_u32 s17, s17, 0
	s_add_u32 s20, s20, 0x80
	s_addc_u32 s21, s21, 0
	ds_read_b128 v[64:67], v194 offset:16384
	ds_read_b128 v[68:71], v194 offset:20480
	ds_read_b128 v[72:75], v198 offset:49152
	ds_read_b128 v[76:79], v198 offset:53248
	v_mfma_f32_32x32x16_bf16 v[48:63], v[80:83], v[88:91], v[48:63]
	v_mfma_f32_32x32x16_bf16 v[32:47], v[80:83], v[92:95], v[32:47]
	v_mfma_f32_32x32x16_bf16 v[16:31], v[84:87], v[88:91], v[16:31]
	v_mfma_f32_32x32x16_bf16 v[0:15], v[84:87], v[92:95], v[0:15]
	ds_read_b128 v[80:83], v195 offset:16384
	ds_read_b128 v[84:87], v195 offset:20480
	ds_read_b128 v[88:91], v199 offset:49152
	ds_read_b128 v[92:95], v199 offset:53248
	v_mfma_f32_32x32x16_bf16 v[48:63], v[96:99], v[104:107], v[48:63]
	v_mfma_f32_32x32x16_bf16 v[32:47], v[96:99], v[108:111], v[32:47]
	v_mfma_f32_32x32x16_bf16 v[16:31], v[100:103], v[104:107], v[16:31]
	v_mfma_f32_32x32x16_bf16 v[0:15], v[100:103], v[108:111], v[0:15]
	ds_read_b128 v[96:99], v196 offset:16384
	ds_read_b128 v[100:103], v196 offset:20480
	ds_read_b128 v[104:107], v200 offset:49152
	ds_read_b128 v[108:111], v200 offset:53248
	v_mfma_f32_32x32x16_bf16 v[48:63], v[112:115], v[120:123], v[48:63]
	v_mfma_f32_32x32x16_bf16 v[32:47], v[112:115], v[124:127], v[32:47]
	v_mfma_f32_32x32x16_bf16 v[16:31], v[116:119], v[120:123], v[16:31]
	v_mfma_f32_32x32x16_bf16 v[0:15], v[116:119], v[124:127], v[0:15]
	s_branch .Lgm_join0_G

.Lgm_join0_G:
	ds_read_b128 v[112:115], v197 offset:16384
	ds_read_b128 v[116:119], v197 offset:20480
	ds_read_b128 v[120:123], v201 offset:49152
	ds_read_b128 v[124:127], v201 offset:53248
	s_waitcnt lgkmcnt(12)
	v_mfma_f32_32x32x16_bf16 v[48:63], v[64:67], v[72:75], v[48:63]
	v_mfma_f32_32x32x16_bf16 v[32:47], v[64:67], v[76:79], v[32:47]
	v_mfma_f32_32x32x16_bf16 v[16:31], v[68:71], v[72:75], v[16:31]
	v_mfma_f32_32x32x16_bf16 v[0:15], v[68:71], v[76:79], v[0:15]
	s_waitcnt vmcnt(0) lgkmcnt(0)
	s_barrier
	s_cmp_lt_u32 s6, 30
	s_cbranch_scc0 .Lgm_nodma1_G
	s_add_u32 m0, s25, 0x4000
	s_nop 0
	global_load_lds_dwordx4 v190, s[16:17]
	s_add_u32 m0, s25, 0x5000
	s_nop 0
	global_load_lds_dwordx4 v191, s[16:17]
	s_add_u32 m0, s25, 0x6000
	s_nop 0
	global_load_lds_dwordx4 v192, s[16:17]
	s_add_u32 m0, s25, 0x7000
	s_nop 0
	global_load_lds_dwordx4 v193, s[16:17]
	s_add_u32 m0, s25, 0xc000
	s_nop 0
	global_load_lds_dwordx4 v190, s[20:21]
	s_add_u32 m0, s25, 0xd000
	s_nop 0
	global_load_lds_dwordx4 v191, s[20:21]
	s_add_u32 m0, s25, 0xe000
	s_nop 0
	global_load_lds_dwordx4 v192, s[20:21]
	s_add_u32 m0, s25, 0xf000
	s_nop 0
	global_load_lds_dwordx4 v193, s[20:21]
	s_add_u32 s16, s16, 0x80
	s_addc_u32 s17, s17, 0
	s_add_u32 s20, s20, 0x80
	s_addc_u32 s21, s21, 0
	ds_read_b128 v[64:67], v194 offset:0
	ds_read_b128 v[68:71], v194 offset:4096
	ds_read_b128 v[72:75], v198 offset:32768
	ds_read_b128 v[76:79], v198 offset:36864
	v_mfma_f32_32x32x16_bf16 v[48:63], v[80:83], v[88:91], v[48:63]
	v_mfma_f32_32x32x16_bf16 v[32:47], v[80:83], v[92:95], v[32:47]
	v_mfma_f32_32x32x16_bf16 v[16:31], v[84:87], v[88:91], v[16:31]
	v_mfma_f32_32x32x16_bf16 v[0:15], v[84:87], v[92:95], v[0:15]
	ds_read_b128 v[80:83], v195 offset:0
	ds_read_b128 v[84:87], v195 offset:4096
	ds_read_b128 v[88:91], v199 offset:32768
	ds_read_b128 v[92:95], v199 offset:36864
	v_mfma_f32_32x32x16_bf16 v[48:63], v[96:99], v[104:107], v[48:63]
	v_mfma_f32_32x32x16_bf16 v[32:47], v[96:99], v[108:111], v[32:47]
	v_mfma_f32_32x32x16_bf16 v[16:31], v[100:103], v[104:107], v[16:31]
	v_mfma_f32_32x32x16_bf16 v[0:15], v[100:103], v[108:111], v[0:15]
	ds_read_b128 v[96:99], v196 offset:0
	ds_read_b128 v[100:103], v196 offset:4096
	ds_read_b128 v[104:107], v200 offset:32768
	ds_read_b128 v[108:111], v200 offset:36864
	v_mfma_f32_32x32x16_bf16 v[48:63], v[112:115], v[120:123], v[48:63]
	v_mfma_f32_32x32x16_bf16 v[32:47], v[112:115], v[124:127], v[32:47]
	v_mfma_f32_32x32x16_bf16 v[16:31], v[116:119], v[120:123], v[16:31]
	v_mfma_f32_32x32x16_bf16 v[0:15], v[116:119], v[124:127], v[0:15]
	s_branch .Lgm_join1_G

.Lgm_join1_G:
	s_add_u32 s6, s6, 2
	s_cmp_lt_u32 s6, 32
	s_cbranch_scc1 .Lgm_loop_G
	s_waitcnt lgkmcnt(0)
	s_barrier
	s_nop 7

.Lgm_loop_H:
	ds_read_b128 v[112:115], v185 offset:0
	ds_read_b128 v[116:119], v185 offset:4096
	ds_read_b128 v[120:123], v186 offset:32768
	ds_read_b128 v[124:127], v186 offset:36864
	s_waitcnt lgkmcnt(12)
	v_mfma_f32_32x32x16_bf16 v[48:63], v[64:67], v[72:75], v[48:63]
	v_mfma_f32_32x32x16_bf16 v[32:47], v[64:67], v[76:79], v[32:47]
	v_mfma_f32_32x32x16_bf16 v[16:31], v[68:71], v[72:75], v[16:31]
	v_mfma_f32_32x32x16_bf16 v[0:15], v[68:71], v[76:79], v[0:15]
	s_waitcnt vmcnt(0) lgkmcnt(0)
	s_barrier
	s_cmp_lt_u32 s12, 30
	s_cbranch_scc0 .Lgm_nodma0_H
	s_add_u32 m0, s36, 0x0
	s_nop 0
	global_load_lds_dwordx4 v188, s[16:17]
	s_add_u32 m0, s36, 0x1000
	s_nop 0
	global_load_lds_dwordx4 v189, s[16:17]
	s_add_u32 m0, s36, 0x2000
	s_nop 0
	global_load_lds_dwordx4 v190, s[16:17]
	s_add_u32 m0, s36, 0x3000
	s_nop 0
	global_load_lds_dwordx4 v191, s[16:17]
	s_add_u32 m0, s36, 0x8000
	s_nop 0
	global_load_lds_dwordx4 v188, s[34:35]
	s_add_u32 m0, s36, 0x9000
	s_nop 0
	global_load_lds_dwordx4 v189, s[34:35]
	s_add_u32 m0, s36, 0xa000
	s_nop 0
	global_load_lds_dwordx4 v190, s[34:35]
	s_add_u32 m0, s36, 0xb000
	s_nop 0
	global_load_lds_dwordx4 v191, s[34:35]
	s_add_u32 s16, s16, 0x80
	s_addc_u32 s17, s17, 0
	s_add_u32 s34, s34, 0x80
	s_addc_u32 s35, s35, 0
	ds_read_b128 v[64:67], v177 offset:16384
	ds_read_b128 v[68:71], v177 offset:20480
	ds_read_b128 v[72:75], v178 offset:49152
	ds_read_b128 v[76:79], v178 offset:53248
	v_mfma_f32_32x32x16_bf16 v[48:63], v[80:83], v[88:91], v[48:63]
	v_mfma_f32_32x32x16_bf16 v[32:47], v[80:83], v[92:95], v[32:47]
	v_mfma_f32_32x32x16_bf16 v[16:31], v[84:87], v[88:91], v[16:31]
	v_mfma_f32_32x32x16_bf16 v[0:15], v[84:87], v[92:95], v[0:15]
	ds_read_b128 v[80:83], v179 offset:16384
	ds_read_b128 v[84:87], v179 offset:20480
	ds_read_b128 v[88:91], v182 offset:49152
	ds_read_b128 v[92:95], v182 offset:53248
	v_mfma_f32_32x32x16_bf16 v[48:63], v[96:99], v[104:107], v[48:63]
	v_mfma_f32_32x32x16_bf16 v[32:47], v[96:99], v[108:111], v[32:47]
	v_mfma_f32_32x32x16_bf16 v[16:31], v[100:103], v[104:107], v[16:31]
	v_mfma_f32_32x32x16_bf16 v[0:15], v[100:103], v[108:111], v[0:15]
	ds_read_b128 v[96:99], v183 offset:16384
	ds_read_b128 v[100:103], v183 offset:20480
	ds_read_b128 v[104:107], v184 offset:49152
	ds_read_b128 v[108:111], v184 offset:53248
	v_mfma_f32_32x32x16_bf16 v[48:63], v[112:115], v[120:123], v[48:63]
	v_mfma_f32_32x32x16_bf16 v[32:47], v[112:115], v[124:127], v[32:47]
	v_mfma_f32_32x32x16_bf16 v[16:31], v[116:119], v[120:123], v[16:31]
	v_mfma_f32_32x32x16_bf16 v[0:15], v[116:119], v[124:127], v[0:15]
	s_branch .Lgm_join0_H

.Lgm_join0_H:
	ds_read_b128 v[112:115], v185 offset:16384
	ds_read_b128 v[116:119], v185 offset:20480
	ds_read_b128 v[120:123], v186 offset:49152
	ds_read_b128 v[124:127], v186 offset:53248
	s_waitcnt lgkmcnt(12)
	v_mfma_f32_32x32x16_bf16 v[48:63], v[64:67], v[72:75], v[48:63]
	v_mfma_f32_32x32x16_bf16 v[32:47], v[64:67], v[76:79], v[32:47]
	v_mfma_f32_32x32x16_bf16 v[16:31], v[68:71], v[72:75], v[16:31]
	v_mfma_f32_32x32x16_bf16 v[0:15], v[68:71], v[76:79], v[0:15]
	s_waitcnt vmcnt(0) lgkmcnt(0)
	s_barrier
	s_cmp_lt_u32 s12, 30
	s_cbranch_scc0 .Lgm_nodma1_H
	s_add_u32 m0, s36, 0x4000
	s_nop 0
	global_load_lds_dwordx4 v188, s[16:17]
	s_add_u32 m0, s36, 0x5000
	s_nop 0
	global_load_lds_dwordx4 v189, s[16:17]
	s_add_u32 m0, s36, 0x6000
	s_nop 0
	global_load_lds_dwordx4 v190, s[16:17]
	s_add_u32 m0, s36, 0x7000
	s_nop 0
	global_load_lds_dwordx4 v191, s[16:17]
	s_add_u32 m0, s36, 0xc000
	s_nop 0
	global_load_lds_dwordx4 v188, s[34:35]
	s_add_u32 m0, s36, 0xd000
	s_nop 0
	global_load_lds_dwordx4 v189, s[34:35]
	s_add_u32 m0, s36, 0xe000
	s_nop 0
	global_load_lds_dwordx4 v190, s[34:35]
	s_add_u32 m0, s36, 0xf000
	s_nop 0
	global_load_lds_dwordx4 v191, s[34:35]
	s_add_u32 s16, s16, 0x80
	s_addc_u32 s17, s17, 0
	s_add_u32 s34, s34, 0x80
	s_addc_u32 s35, s35, 0
	ds_read_b128 v[64:67], v177 offset:0
	ds_read_b128 v[68:71], v177 offset:4096
	ds_read_b128 v[72:75], v178 offset:32768
	ds_read_b128 v[76:79], v178 offset:36864
	v_mfma_f32_32x32x16_bf16 v[48:63], v[80:83], v[88:91], v[48:63]
	v_mfma_f32_32x32x16_bf16 v[32:47], v[80:83], v[92:95], v[32:47]
	v_mfma_f32_32x32x16_bf16 v[16:31], v[84:87], v[88:91], v[16:31]
	v_mfma_f32_32x32x16_bf16 v[0:15], v[84:87], v[92:95], v[0:15]
	ds_read_b128 v[80:83], v179 offset:0
	ds_read_b128 v[84:87], v179 offset:4096
	ds_read_b128 v[88:91], v182 offset:32768
	ds_read_b128 v[92:95], v182 offset:36864
	v_mfma_f32_32x32x16_bf16 v[48:63], v[96:99], v[104:107], v[48:63]
	v_mfma_f32_32x32x16_bf16 v[32:47], v[96:99], v[108:111], v[32:47]
	v_mfma_f32_32x32x16_bf16 v[16:31], v[100:103], v[104:107], v[16:31]
	v_mfma_f32_32x32x16_bf16 v[0:15], v[100:103], v[108:111], v[0:15]
	ds_read_b128 v[96:99], v183 offset:0
	ds_read_b128 v[100:103], v183 offset:4096
	ds_read_b128 v[104:107], v184 offset:32768
	ds_read_b128 v[108:111], v184 offset:36864
	v_mfma_f32_32x32x16_bf16 v[48:63], v[112:115], v[120:123], v[48:63]
	v_mfma_f32_32x32x16_bf16 v[32:47], v[112:115], v[124:127], v[32:47]
	v_mfma_f32_32x32x16_bf16 v[16:31], v[116:119], v[120:123], v[16:31]
	v_mfma_f32_32x32x16_bf16 v[0:15], v[116:119], v[124:127], v[0:15]
	s_branch .Lgm_join1_H

.Lgm_join1_H:
	s_add_u32 s12, s12, 2
	s_cmp_lt_u32 s12, 32
	s_cbranch_scc1 .Lgm_loop_H
	s_waitcnt lgkmcnt(0)
	s_barrier
	s_nop 7

.LBB0_1111:
	v_cndmask_b32_e64 v80, v17, v49, s[16:17]
	v_cndmask_b32_e64 v81, v16, v48, s[16:17]
	v_add_u32_e32 v82, v161, v162
	v_cndmask_b32_e64 v98, v0, v32, s[16:17]
	v_cndmask_b32_e64 v78, v19, v51, s[16:17]
	v_cndmask_b32_e64 v79, v18, v50, s[16:17]
	v_cndmask_b32_e64 v96, v2, v34, s[16:17]
	v_cndmask_b32_e64 v97, v1, v33, s[16:17]
	ds_write2_b32 v82, v81, v98 offset1:32
	ds_write2_b32 v82, v80, v97 offset0:132 offset1:164
	v_add_u32_e32 v80, 0x400, v82
	v_cndmask_b32_e64 v76, v21, v53, s[16:17]
	v_cndmask_b32_e64 v77, v20, v52, s[16:17]
	v_cndmask_b32_e64 v94, v4, v36, s[16:17]
	v_cndmask_b32_e64 v95, v3, v35, s[16:17]
	ds_write2_b32 v80, v79, v96 offset0:8 offset1:40
	ds_write2_b32 v80, v78, v95 offset0:140 offset1:172
	v_add_u32_e32 v78, 0x1000, v82
	v_cndmask_b32_e64 v74, v23, v55, s[16:17]
	v_cndmask_b32_e64 v75, v22, v54, s[16:17]
	v_cndmask_b32_e64 v92, v6, v38, s[16:17]
	v_cndmask_b32_e64 v93, v5, v37, s[16:17]
	ds_write2_b32 v78, v77, v94 offset0:32 offset1:64
	ds_write2_b32 v78, v76, v93 offset0:164 offset1:196
	v_add_u32_e32 v76, 0x1400, v82
	v_cndmask_b32_e64 v72, v25, v57, s[16:17]
	v_cndmask_b32_e64 v73, v24, v56, s[16:17]
	v_cndmask_b32_e64 v90, v8, v40, s[16:17]
	v_cndmask_b32_e64 v91, v7, v39, s[16:17]
	ds_write2_b32 v76, v75, v92 offset0:40 offset1:72
	ds_write2_b32 v76, v74, v91 offset0:172 offset1:204
	v_add_u32_e32 v74, 0x2000, v82
	v_cndmask_b32_e64 v70, v27, v59, s[16:17]
	v_cndmask_b32_e64 v71, v26, v58, s[16:17]
	v_cndmask_b32_e64 v88, v10, v42, s[16:17]
	v_cndmask_b32_e64 v89, v9, v41, s[16:17]
	ds_write2_b32 v74, v73, v90 offset0:64 offset1:96
	ds_write2_b32 v74, v72, v89 offset0:196 offset1:228
	v_add_u32_e32 v72, 0x2400, v82
	v_cndmask_b32_e64 v69, v28, v60, s[16:17]
	v_cndmask_b32_e64 v86, v12, v44, s[16:17]
	v_cndmask_b32_e64 v87, v11, v43, s[16:17]
	ds_write2_b32 v72, v71, v88 offset0:72 offset1:104
	ds_write2_b32 v72, v70, v87 offset0:204 offset1:236
	v_add_u32_e32 v70, 0x3000, v82
	v_cndmask_b32_e64 v68, v29, v61, s[16:17]
	v_cndmask_b32_e64 v85, v13, v45, s[16:17]
	ds_write2_b32 v70, v69, v86 offset0:96 offset1:128
	v_add_u32_e32 v69, 0x3200, v82
	v_cndmask_b32_e64 v66, 0, 1, s[16:17]
	v_cndmask_b32_e64 v67, v30, v62, s[16:17]
	v_cndmask_b32_e64 v84, v14, v46, s[16:17]
	ds_write2_b32 v69, v68, v85 offset0:100 offset1:132
	v_add_u32_e32 v68, 0x3400, v82
	v_or_b32_e32 v76, s2, v170
	v_cmp_ne_u32_e64 s[0:1], 1, v66
	v_cndmask_b32_e64 v66, v31, v63, s[16:17]
	v_cndmask_b32_e64 v83, v15, v47, s[16:17]
	ds_write2_b32 v68, v67, v84 offset0:104 offset1:136
	v_add_u32_e32 v67, 0x3600, v82
	v_add_u32_e32 v70, v163, v165
	v_lshl_add_u32 v74, v76, 2, s24
	ds_write2_b32 v67, v66, v83 offset0:108 offset1:140
	s_waitcnt lgkmcnt(0)
	s_barrier
	ds_read_b128 v[66:69], v70
	ds_read_b128 v[70:73], v70 offset:16
	ds_read_b32 v77, v74
	s_waitcnt lgkmcnt(0)
	v_mul_f32_e32 v67, v67, v77
	v_mul_f32_e32 v67, 0xbfb8aa3b, v67
	v_mul_f32_e32 v66, v66, v77
	v_exp_f32_e32 v74, v67
	v_mul_f32_e32 v67, v68, v77
	v_mul_f32_e32 v66, 0xbfb8aa3b, v66
	v_mul_f32_e32 v67, 0xbfb8aa3b, v67
	v_exp_f32_e32 v66, v66
	v_exp_f32_e32 v67, v67
	v_mul_f32_e32 v68, v69, v77
	v_mul_f32_e32 v69, v71, v77
	v_mul_f32_e32 v68, 0xbfb8aa3b, v68
	v_mul_f32_e32 v69, 0xbfb8aa3b, v69
	v_pk_add_f32 v[66:67], v[66:67], 1.0 op_sel_hi:[1,0]
	v_exp_f32_e32 v75, v68
	v_mul_f32_e32 v68, v70, v77
	v_exp_f32_e32 v70, v69
	v_mul_f32_e32 v69, v72, v77
	v_or_b32_e32 v72, s38, v76
	v_mul_f32_e32 v71, v73, v77
	v_mul_f32_e32 v68, 0xbfb8aa3b, v68
	v_mul_f32_e32 v69, 0xbfb8aa3b, v69
	v_exp_f32_e32 v68, v68
	v_rcp_f32_e32 v76, v66
	s_nop 0
	v_exp_f32_e32 v69, v69
	v_mul_f32_e32 v71, 0xbfb8aa3b, v71
	v_exp_f32_e32 v71, v71
	v_rcp_f32_e32 v77, v67
	s_nop 0
	v_pk_add_f32 v[66:67], v[74:75], 1.0 op_sel_hi:[1,0]
	v_pk_add_f32 v[68:69], v[68:69], 1.0 op_sel_hi:[1,0]
	v_lshlrev_b32_e32 v130, 12, v72
	v_lshl_add_u64 v[72:73], v[64:65], 0, v[130:131]
	v_rcp_f32_e32 v66, v66
	s_nop 0
	s_nop 0
	v_rcp_f32_e32 v67, v67
	s_nop 0
	v_and_b32_sdwa v75, v76, v181 dst_sel:DWORD dst_unused:UNUSED_PAD src0_sel:WORD_1 src1_sel:DWORD
	v_and_b32_sdwa v74, v77, v181 dst_sel:DWORD dst_unused:UNUSED_PAD src0_sel:WORD_1 src1_sel:DWORD
	v_add3_u32 v75, v76, v75, s30
	v_and_b32_sdwa v76, v67, v181 dst_sel:DWORD dst_unused:UNUSED_PAD src0_sel:WORD_1 src1_sel:DWORD
	v_add3_u32 v74, v77, v74, s30
	v_and_b32_sdwa v77, v66, v181 dst_sel:DWORD dst_unused:UNUSED_PAD src0_sel:WORD_1 src1_sel:DWORD
	v_add3_u32 v67, v67, v76, s30
	v_add3_u32 v66, v66, v77, s30
	v_and_b32_e32 v67, 0xffff0000, v67
	v_and_b32_e32 v66, 0xffff0000, v66
	v_or_b32_sdwa v67, v67, v74 dst_sel:DWORD dst_unused:UNUSED_PAD src0_sel:DWORD src1_sel:WORD_1
	v_or_b32_sdwa v66, v66, v75 dst_sel:DWORD dst_unused:UNUSED_PAD src0_sel:DWORD src1_sel:WORD_1
	s_nop 0
	v_rcp_f32_e32 v74, v68
	s_nop 0
	s_nop 0
	v_rcp_f32_e32 v75, v69
	s_nop 0
	v_pk_add_f32 v[68:69], v[70:71], 1.0 op_sel_hi:[1,0]
	s_nop 0
	s_nop 0
	v_rcp_f32_e32 v68, v68
	s_nop 0
	s_nop 0
	v_rcp_f32_e32 v69, v69
	s_nop 0
	v_and_b32_sdwa v70, v75, v181 dst_sel:DWORD dst_unused:UNUSED_PAD src0_sel:WORD_1 src1_sel:DWORD
	v_and_b32_sdwa v71, v74, v181 dst_sel:DWORD dst_unused:UNUSED_PAD src0_sel:WORD_1 src1_sel:DWORD
	v_add3_u32 v71, v74, v71, s30
	v_add3_u32 v70, v75, v70, s30
	v_and_b32_sdwa v74, v69, v181 dst_sel:DWORD dst_unused:UNUSED_PAD src0_sel:WORD_1 src1_sel:DWORD
	v_and_b32_sdwa v75, v68, v181 dst_sel:DWORD dst_unused:UNUSED_PAD src0_sel:WORD_1 src1_sel:DWORD
	v_add3_u32 v69, v69, v74, s30
	v_add3_u32 v68, v68, v75, s30
	v_and_b32_e32 v69, 0xffff0000, v69
	v_and_b32_e32 v68, 0xffff0000, v68
	v_or_b32_sdwa v69, v69, v70 dst_sel:DWORD dst_unused:UNUSED_PAD src0_sel:DWORD src1_sel:WORD_1
	v_or_b32_sdwa v68, v68, v71 dst_sel:DWORD dst_unused:UNUSED_PAD src0_sel:DWORD src1_sel:WORD_1
	v_or_b32_e32 v76, s2, v171
	global_store_dwordx4 v[72:73], v[66:69], off
	v_add_u32_e32 v70, v163, v166
	v_lshl_add_u32 v74, v76, 2, s24
	ds_read_b128 v[66:69], v70
	ds_read_b128 v[70:73], v70 offset:16
	ds_read_b32 v77, v74
	v_add_lshl_u32 v130, v76, s38, 12
	s_waitcnt lgkmcnt(0)
	v_mul_f32_e32 v67, v67, v77
	v_mul_f32_e32 v67, 0xbfb8aa3b, v67
	v_mul_f32_e32 v66, v66, v77
	v_exp_f32_e32 v74, v67
	v_mul_f32_e32 v67, v68, v77
	v_mul_f32_e32 v66, 0xbfb8aa3b, v66
	v_mul_f32_e32 v67, 0xbfb8aa3b, v67
	v_exp_f32_e32 v66, v66
	v_exp_f32_e32 v67, v67
	v_mul_f32_e32 v68, v69, v77
	v_mul_f32_e32 v69, v71, v77
	v_mul_f32_e32 v68, 0xbfb8aa3b, v68
	v_pk_add_f32 v[66:67], v[66:67], 1.0 op_sel_hi:[1,0]
	v_mul_f32_e32 v69, 0xbfb8aa3b, v69
	v_exp_f32_e32 v75, v68
	v_mul_f32_e32 v68, v70, v77
	v_exp_f32_e32 v70, v69
	v_mul_f32_e32 v69, v72, v77
	v_mul_f32_e32 v71, v73, v77
	v_mul_f32_e32 v68, 0xbfb8aa3b, v68
	v_mul_f32_e32 v69, 0xbfb8aa3b, v69
	v_exp_f32_e32 v68, v68
	v_rcp_f32_e32 v76, v66
	s_nop 0
	v_exp_f32_e32 v69, v69
	v_mul_f32_e32 v71, 0xbfb8aa3b, v71
	v_exp_f32_e32 v71, v71
	v_rcp_f32_e32 v77, v67
	s_nop 0
	v_pk_add_f32 v[66:67], v[74:75], 1.0 op_sel_hi:[1,0]
	v_pk_add_f32 v[68:69], v[68:69], 1.0 op_sel_hi:[1,0]
	v_lshl_add_u64 v[72:73], v[64:65], 0, v[130:131]
	v_rcp_f32_e32 v66, v66
	s_nop 0
	s_nop 0
	v_rcp_f32_e32 v67, v67
	s_nop 0
	v_and_b32_sdwa v75, v76, v181 dst_sel:DWORD dst_unused:UNUSED_PAD src0_sel:WORD_1 src1_sel:DWORD
	v_and_b32_sdwa v74, v77, v181 dst_sel:DWORD dst_unused:UNUSED_PAD src0_sel:WORD_1 src1_sel:DWORD
	v_add3_u32 v75, v76, v75, s30
	v_and_b32_sdwa v76, v67, v181 dst_sel:DWORD dst_unused:UNUSED_PAD src0_sel:WORD_1 src1_sel:DWORD
	v_add3_u32 v74, v77, v74, s30
	v_and_b32_sdwa v77, v66, v181 dst_sel:DWORD dst_unused:UNUSED_PAD src0_sel:WORD_1 src1_sel:DWORD
	v_add3_u32 v67, v67, v76, s30
	v_add3_u32 v66, v66, v77, s30
	v_and_b32_e32 v67, 0xffff0000, v67
	v_and_b32_e32 v66, 0xffff0000, v66
	v_or_b32_sdwa v67, v67, v74 dst_sel:DWORD dst_unused:UNUSED_PAD src0_sel:DWORD src1_sel:WORD_1
	v_or_b32_sdwa v66, v66, v75 dst_sel:DWORD dst_unused:UNUSED_PAD src0_sel:DWORD src1_sel:WORD_1
	s_nop 0
	v_rcp_f32_e32 v74, v68
	s_nop 0
	s_nop 0
	v_rcp_f32_e32 v75, v69
	s_nop 0
	v_pk_add_f32 v[68:69], v[70:71], 1.0 op_sel_hi:[1,0]
	s_nop 0
	s_nop 0
	v_rcp_f32_e32 v68, v68
	s_nop 0
	s_nop 0
	v_rcp_f32_e32 v69, v69
	s_nop 0
	v_and_b32_sdwa v70, v75, v181 dst_sel:DWORD dst_unused:UNUSED_PAD src0_sel:WORD_1 src1_sel:DWORD
	v_and_b32_sdwa v71, v74, v181 dst_sel:DWORD dst_unused:UNUSED_PAD src0_sel:WORD_1 src1_sel:DWORD
	v_add3_u32 v71, v74, v71, s30
	v_add3_u32 v70, v75, v70, s30
	v_and_b32_sdwa v74, v69, v181 dst_sel:DWORD dst_unused:UNUSED_PAD src0_sel:WORD_1 src1_sel:DWORD
	v_and_b32_sdwa v75, v68, v181 dst_sel:DWORD dst_unused:UNUSED_PAD src0_sel:WORD_1 src1_sel:DWORD
	v_add3_u32 v69, v69, v74, s30
	v_add3_u32 v68, v68, v75, s30
	v_and_b32_e32 v69, 0xffff0000, v69
	v_and_b32_e32 v68, 0xffff0000, v68
	v_or_b32_sdwa v69, v69, v70 dst_sel:DWORD dst_unused:UNUSED_PAD src0_sel:DWORD src1_sel:WORD_1
	v_or_b32_sdwa v68, v68, v71 dst_sel:DWORD dst_unused:UNUSED_PAD src0_sel:DWORD src1_sel:WORD_1
	v_or_b32_e32 v76, s2, v175
	global_store_dwordx4 v[72:73], v[66:69], off
	v_add_u32_e32 v70, v163, v167
	v_lshl_add_u32 v74, v76, 2, s24
	ds_read_b128 v[66:69], v70
	ds_read_b128 v[70:73], v70 offset:16
	ds_read_b32 v77, v74
	v_add_lshl_u32 v130, v76, s38, 12
	s_waitcnt lgkmcnt(0)
	v_mul_f32_e32 v67, v67, v77
	v_mul_f32_e32 v67, 0xbfb8aa3b, v67
	v_mul_f32_e32 v66, v66, v77
	v_exp_f32_e32 v74, v67
	v_mul_f32_e32 v67, v68, v77
	v_mul_f32_e32 v66, 0xbfb8aa3b, v66
	v_mul_f32_e32 v67, 0xbfb8aa3b, v67
	v_exp_f32_e32 v66, v66
	v_exp_f32_e32 v67, v67
	v_mul_f32_e32 v68, v69, v77
	v_mul_f32_e32 v69, v71, v77
	v_mul_f32_e32 v68, 0xbfb8aa3b, v68
	v_pk_add_f32 v[66:67], v[66:67], 1.0 op_sel_hi:[1,0]
	v_mul_f32_e32 v69, 0xbfb8aa3b, v69
	v_exp_f32_e32 v75, v68
	v_mul_f32_e32 v68, v70, v77
	v_exp_f32_e32 v70, v69
	v_mul_f32_e32 v69, v72, v77
	v_mul_f32_e32 v71, v73, v77
	v_mul_f32_e32 v68, 0xbfb8aa3b, v68
	v_mul_f32_e32 v69, 0xbfb8aa3b, v69
	v_exp_f32_e32 v68, v68
	v_rcp_f32_e32 v76, v66
	s_nop 0
	v_exp_f32_e32 v69, v69
	v_mul_f32_e32 v71, 0xbfb8aa3b, v71
	v_exp_f32_e32 v71, v71
	v_rcp_f32_e32 v77, v67
	s_nop 0
	v_pk_add_f32 v[66:67], v[74:75], 1.0 op_sel_hi:[1,0]
	v_pk_add_f32 v[68:69], v[68:69], 1.0 op_sel_hi:[1,0]
	v_lshl_add_u64 v[72:73], v[64:65], 0, v[130:131]
	v_rcp_f32_e32 v66, v66
	s_nop 0
	s_nop 0
	v_rcp_f32_e32 v67, v67
	s_nop 0
	v_and_b32_sdwa v75, v76, v181 dst_sel:DWORD dst_unused:UNUSED_PAD src0_sel:WORD_1 src1_sel:DWORD
	v_and_b32_sdwa v74, v77, v181 dst_sel:DWORD dst_unused:UNUSED_PAD src0_sel:WORD_1 src1_sel:DWORD
	v_add3_u32 v75, v76, v75, s30
	v_and_b32_sdwa v76, v67, v181 dst_sel:DWORD dst_unused:UNUSED_PAD src0_sel:WORD_1 src1_sel:DWORD
	v_add3_u32 v74, v77, v74, s30
	v_and_b32_sdwa v77, v66, v181 dst_sel:DWORD dst_unused:UNUSED_PAD src0_sel:WORD_1 src1_sel:DWORD
	v_add3_u32 v67, v67, v76, s30
	v_add3_u32 v66, v66, v77, s30
	v_and_b32_e32 v67, 0xffff0000, v67
	v_and_b32_e32 v66, 0xffff0000, v66
	v_or_b32_sdwa v67, v67, v74 dst_sel:DWORD dst_unused:UNUSED_PAD src0_sel:DWORD src1_sel:WORD_1
	v_or_b32_sdwa v66, v66, v75 dst_sel:DWORD dst_unused:UNUSED_PAD src0_sel:DWORD src1_sel:WORD_1
	s_nop 0
	v_rcp_f32_e32 v74, v68
	s_nop 0
	s_nop 0
	v_rcp_f32_e32 v75, v69
	s_nop 0
	v_pk_add_f32 v[68:69], v[70:71], 1.0 op_sel_hi:[1,0]
	s_nop 0
	s_nop 0
	v_rcp_f32_e32 v68, v68
	s_nop 0
	s_nop 0
	v_rcp_f32_e32 v69, v69
	s_nop 0
	v_and_b32_sdwa v70, v75, v181 dst_sel:DWORD dst_unused:UNUSED_PAD src0_sel:WORD_1 src1_sel:DWORD
	v_and_b32_sdwa v71, v74, v181 dst_sel:DWORD dst_unused:UNUSED_PAD src0_sel:WORD_1 src1_sel:DWORD
	v_add3_u32 v71, v74, v71, s30
	v_add3_u32 v70, v75, v70, s30
	v_and_b32_sdwa v74, v69, v181 dst_sel:DWORD dst_unused:UNUSED_PAD src0_sel:WORD_1 src1_sel:DWORD
	v_and_b32_sdwa v75, v68, v181 dst_sel:DWORD dst_unused:UNUSED_PAD src0_sel:WORD_1 src1_sel:DWORD
	v_add3_u32 v69, v69, v74, s30
	v_add3_u32 v68, v68, v75, s30
	v_and_b32_e32 v69, 0xffff0000, v69
	v_and_b32_e32 v68, 0xffff0000, v68
	v_or_b32_sdwa v69, v69, v70 dst_sel:DWORD dst_unused:UNUSED_PAD src0_sel:DWORD src1_sel:WORD_1
	v_or_b32_sdwa v68, v68, v71 dst_sel:DWORD dst_unused:UNUSED_PAD src0_sel:DWORD src1_sel:WORD_1
	v_or_b32_e32 v76, s2, v176
	global_store_dwordx4 v[72:73], v[66:69], off
	v_add_u32_e32 v70, v163, v174
	v_lshl_add_u32 v74, v76, 2, s24
	ds_read_b128 v[66:69], v70
	ds_read_b128 v[70:73], v70 offset:16
	ds_read_b32 v77, v74
	v_add_lshl_u32 v130, v76, s38, 12
	s_mov_b32 s2, 32
	s_waitcnt lgkmcnt(0)
	v_mul_f32_e32 v67, v67, v77
	v_mul_f32_e32 v67, 0xbfb8aa3b, v67
	v_mul_f32_e32 v66, v66, v77
	v_exp_f32_e32 v74, v67
	v_mul_f32_e32 v67, v68, v77
	v_mul_f32_e32 v66, 0xbfb8aa3b, v66
	v_mul_f32_e32 v67, 0xbfb8aa3b, v67
	v_exp_f32_e32 v66, v66
	v_exp_f32_e32 v67, v67
	v_mul_f32_e32 v68, v69, v77
	v_mul_f32_e32 v69, v71, v77
	v_mul_f32_e32 v68, 0xbfb8aa3b, v68
	v_pk_add_f32 v[66:67], v[66:67], 1.0 op_sel_hi:[1,0]
	v_mul_f32_e32 v69, 0xbfb8aa3b, v69
	v_exp_f32_e32 v75, v68
	v_mul_f32_e32 v68, v70, v77
	v_exp_f32_e32 v70, v69
	v_mul_f32_e32 v69, v72, v77
	v_mul_f32_e32 v71, v73, v77
	v_mul_f32_e32 v68, 0xbfb8aa3b, v68
	v_mul_f32_e32 v69, 0xbfb8aa3b, v69
	v_exp_f32_e32 v68, v68
	v_rcp_f32_e32 v76, v66
	s_nop 0
	v_exp_f32_e32 v69, v69
	v_mul_f32_e32 v71, 0xbfb8aa3b, v71
	v_exp_f32_e32 v71, v71
	v_rcp_f32_e32 v77, v67
	s_nop 0
	v_pk_add_f32 v[66:67], v[74:75], 1.0 op_sel_hi:[1,0]
	v_pk_add_f32 v[68:69], v[68:69], 1.0 op_sel_hi:[1,0]
	v_lshl_add_u64 v[72:73], v[64:65], 0, v[130:131]
	v_rcp_f32_e32 v66, v66
	s_nop 0
	s_nop 0
	v_rcp_f32_e32 v67, v67
	s_nop 0
	v_and_b32_sdwa v75, v76, v181 dst_sel:DWORD dst_unused:UNUSED_PAD src0_sel:WORD_1 src1_sel:DWORD
	v_and_b32_sdwa v74, v77, v181 dst_sel:DWORD dst_unused:UNUSED_PAD src0_sel:WORD_1 src1_sel:DWORD
	v_add3_u32 v75, v76, v75, s30
	v_and_b32_sdwa v76, v67, v181 dst_sel:DWORD dst_unused:UNUSED_PAD src0_sel:WORD_1 src1_sel:DWORD
	v_add3_u32 v74, v77, v74, s30
	v_and_b32_sdwa v77, v66, v181 dst_sel:DWORD dst_unused:UNUSED_PAD src0_sel:WORD_1 src1_sel:DWORD
	v_add3_u32 v67, v67, v76, s30
	v_add3_u32 v66, v66, v77, s30
	v_and_b32_e32 v67, 0xffff0000, v67
	v_and_b32_e32 v66, 0xffff0000, v66
	v_or_b32_sdwa v67, v67, v74 dst_sel:DWORD dst_unused:UNUSED_PAD src0_sel:DWORD src1_sel:WORD_1
	v_or_b32_sdwa v66, v66, v75 dst_sel:DWORD dst_unused:UNUSED_PAD src0_sel:DWORD src1_sel:WORD_1
	s_nop 0
	v_rcp_f32_e32 v74, v68
	s_nop 0
	s_nop 0
	v_rcp_f32_e32 v75, v69
	s_nop 0
	v_pk_add_f32 v[68:69], v[70:71], 1.0 op_sel_hi:[1,0]
	s_nop 0
	s_nop 0
	v_rcp_f32_e32 v68, v68
	s_nop 0
	s_mov_b64 s[16:17], 0
	v_rcp_f32_e32 v69, v69
	s_nop 0
	v_and_b32_sdwa v70, v75, v181 dst_sel:DWORD dst_unused:UNUSED_PAD src0_sel:WORD_1 src1_sel:DWORD
	v_and_b32_sdwa v71, v74, v181 dst_sel:DWORD dst_unused:UNUSED_PAD src0_sel:WORD_1 src1_sel:DWORD
	v_add3_u32 v71, v74, v71, s30
	v_add3_u32 v70, v75, v70, s30
	v_and_b32_sdwa v74, v69, v181 dst_sel:DWORD dst_unused:UNUSED_PAD src0_sel:WORD_1 src1_sel:DWORD
	v_and_b32_sdwa v75, v68, v181 dst_sel:DWORD dst_unused:UNUSED_PAD src0_sel:WORD_1 src1_sel:DWORD
	v_add3_u32 v69, v69, v74, s30
	v_add3_u32 v68, v68, v75, s30
	v_and_b32_e32 v69, 0xffff0000, v69
	v_and_b32_e32 v68, 0xffff0000, v68
	v_or_b32_sdwa v69, v69, v70 dst_sel:DWORD dst_unused:UNUSED_PAD src0_sel:DWORD src1_sel:WORD_1
	v_or_b32_sdwa v68, v68, v71 dst_sel:DWORD dst_unused:UNUSED_PAD src0_sel:DWORD src1_sel:WORD_1
	s_and_b64 vcc, exec, s[0:1]
	global_store_dwordx4 v[72:73], v[66:69], off
	s_barrier
	s_cbranch_vccz .LBB0_1111
	s_branch .LBB0_1086
